# v26: v23 + counted-wait ladders in the MMA blocks (lgkmcnt 6/4/2/0 per group of 4 MFMAs instead of one lgkmcnt(0) at the block head)
# speedup vs baseline: 1.0090x; 1.0090x over previous
; #define PG8_STAGE(bufoff, gbase, voff) do { _Pragma("unroll") for (int _i = 0; _i < 2; ++_i) \
;         __builtin_amdgcn_global_load_lds((const unsigned*)((const char*)(gbase) + (voff)[_i]), (LAS unsigned*)(lds + (bufoff) + ldsw + _i * 8192), 16, 0, 0); } while (0)
; #define PG8_WAIT_V(n) asm volatile("s_waitcnt vmcnt(" #n ")" ::: "memory")
; #define PG8_BAR __builtin_amdgcn_s_barrier()
; template <class Epi, class Ptrs>
; __device__ __forceinline__ void gemm_phase(LAS unsigned char* lds, const int K, const StaticOrder& S, const Ptrs& P, const Epi& E) {
;     ...
;     for (int i = 0; i < 2; ++i) { int R, C; stage_rc(tid * 16 + i * 8192, R, C); const int Rb = (R & ~31) + perm32(R & 31);
;         voffA[i] = (unsigned)(R * K + C) * 2u; voffB[i] = (unsigned)(Rb * K + C) * 2u; }
;     const size_t kstep = (size_t)(BK * 2);
;     const size_t hstep = (size_t)HALF * K * 2;
;     const unsigned ldsw = (unsigned)wid * 1024u;
;     const int aoff = lds_byte(wr * 64 + fr, fq * 8), boff = lds_byte(wc * 32 + fr, fq * 8);
;     ...
;     Unit cur, nxt; int ui = 0;
;     if (!S.next(0, cur)) return;
;     f32x4 acc[2][2][4][2];
; #pragma unroll
;     for (int a = 0; a < 2; ++a)
; #pragma unroll
;         for (int b = 0; b < 2; ++b)
; #pragma unroll
;             for (int m = 0; m < 4; ++m)
; #pragma unroll
;                 for (int n = 0; n < 2; ++n) acc[a][b][m][n] = (f32x4){0.f, 0.f, 0.f, 0.f};
;     bf16x8 At[4][2], B0[2][2], B1[2][2];
;     const char* cA; const char* cB; P.get(cur, cA, cB);
;     PG8_STAGE(PG8_SB(0, 0), cB, voffB); PG8_STAGE(PG8_SA(0, 0), cA, voffA); PG8_STAGE(PG8_SB(0, 1), cB + hstep, voffB); PG8_STAGE(PG8_SA(0, 1), cA + hstep, voffA);
;     if (wr == 1) PG8_BAR;
;     PG8_WAIT_V(4); PG8_BAR;
;     PG8_STAGE(PG8_SB(1, 0), cB + kstep, voffB); PG8_STAGE(PG8_SA(1, 0), cA + kstep, voffA); PG8_STAGE(PG8_SB(1, 1), cB + hstep + kstep, voffB);
;     PG8_WAIT_V(6); PG8_BAR;
.LBB0_120:
	s_add_u32 s4, s28, 0x35000000
	s_addc_u32 s5, s29, 0
	s_mov_b64 s[58:59], 0x80
	v_writelane_b32 v254, s4, 0
	v_lshl_add_u64 v[6:7], v[6:7], 0, s[58:59]
	s_waitcnt vmcnt(4)
	s_barrier
	v_writelane_b32 v254, s5, 1
	s_add_u32 s4, s28, 0x26000000
	s_addc_u32 s5, s29, 0
	s_add_u32 s42, s28, 0x32000000
	s_addc_u32 s43, s29, 0
	s_add_u32 s44, s28, 0x2000000
	s_addc_u32 s45, s29, 0
	s_add_u32 s48, s26, 0xc000000
	s_addc_u32 s49, s27, 0
	s_add_u32 s54, s28, 0x3e000000
	s_addc_u32 s55, s29, 0
	s_add_u32 s56, s28, 0xe000000
	s_addc_u32 s57, s29, 0
	s_lshl_b32 s1, s1, 5
	s_and_b32 s88, s1, 0x60
	s_add_i32 m0, s67, 0x18000
	v_writelane_b32 v254, s4, 2
	s_ashr_i32 s86, s3, 31
	s_ashr_i32 s87, s2, 31
	s_lshl_b32 s20, s0, 13
	s_lshl_b32 s1, s88, 7
	global_load_lds_dwordx4 v[6:7], off
	v_lshl_add_u64 v[4:5], v[4:5], 0, s[58:59]
	s_add_i32 m0, s67, 0x1a000
	s_add_i32 s89, s67, 0x8000
	s_add_i32 s90, s67, 0xa000
	v_writelane_b32 v254, s5, 3
	global_load_lds_dwordx4 v[4:5], off
	v_lshl_add_u64 v[2:3], v[2:3], 0, s[58:59]
	s_mov_b32 m0, s89
	s_add_u32 s4, s78, 0x40080
	global_load_lds_dwordx4 v[2:3], off
	v_lshl_add_u64 v[0:1], v[0:1], 0, s[58:59]
	s_mov_b32 m0, s90
	s_addc_u32 s5, s79, 0
	global_load_lds_dwordx4 v[0:1], off
	s_add_i32 m0, s67, 0x1c000
	v_lshl_add_u64 v[0:1], s[4:5], 0, v[134:135]
	global_load_lds_dwordx4 v[0:1], off
	v_lshl_add_u64 v[0:1], s[4:5], 0, v[138:139]
	s_add_i32 m0, s67, 0x1e000
	v_lshlrev_b32_e32 v2, 6, v208
	global_load_lds_dwordx4 v[0:1], off
	v_and_b32_e32 v0, 15, v208
	v_lshlrev_b32_e32 v1, 1, v130
	s_movk_i32 s4, 0x3c0
	v_lshlrev_b32_e32 v3, 2, v208
	v_and_or_b32 v2, v2, s4, v1
	v_and_b32_e32 v3, 32, v3
	v_cmp_eq_u32_e64 s[10:11], 0, v0
	v_lshl_or_b32 v129, s0, 6, v0
	v_lshl_or_b32 v0, v0, 6, v1
	v_lshlrev_b32_e32 v1, 8, v208
	v_bitop3_b32 v131, s1, v2, v3 bitop3:0xf6
	v_and_b32_e32 v1, 0x38000, v1
	v_lshlrev_b32_e32 v2, 11, v10
	v_or3_b32 v1, v8, v1, v2
	v_add_u32_e32 v142, v1, v9
	v_lshlrev_b32_e32 v1, 4, v11
	s_waitcnt vmcnt(6)
	v_and_b32_e32 v1, 0x78000, v1
	v_bitop3_b32 v0, v0, s20, v3 bitop3:0xde
	v_or3_b32 v1, v8, v1, v2
	s_add_i32 s91, 0, 0x10000
	s_add_i32 s92, 0, 0x14000
	v_or_b32_e32 v204, s88, v130
	v_mov_b32_e32 v143, v141
	v_add_u32_e32 v144, v1, v9
	v_mov_b32_e32 v145, v141
	v_mov_b64_e32 v[146:147], 0x2100
	v_mov_b64_e32 v[148:149], 0x20ff
	v_add_u32_e32 v205, s91, v131
	v_add_u32_e32 v206, 0, v0
	v_add_u32_e32 v207, s92, v131
	s_mov_b32 s60, 0xbfb8aa3b
	s_lshl_b32 s62, s0, 2
	s_mov_b32 s64, 0x3dd2d3e7
	s_mov_b32 s66, 0xc0135761
	s_mov_b32 s93, 0x600000
	s_mov_b32 s94, 0x900000
	s_mov_b32 s95, 0x1800000
	s_mov_b32 s96, 0x1b00000
	s_mov_b32 s97, 0x1e00000
	s_mov_b32 s98, 0x2100000
	s_mov_b32 s99, 0x40000
	s_mov_b32 s22, 0x48000
	s_mov_b32 s23, 0x50000
	s_nop 0
	s_nop 0
	s_nop 0
	s_nop 0
	s_nop 0
	s_nop 0
	s_nop 0
	s_nop 0
	s_nop 0
	s_nop 0
	s_nop 0
	s_nop 0
	s_nop 0
	s_nop 0
	s_nop 0
	s_nop 0
	s_nop 0
	s_nop 0
	s_nop 0
	s_nop 0
	s_nop 0
	s_nop 0
	s_nop 0
	s_nop 0
	s_nop 0
	s_nop 0
	s_nop 0
	s_nop 0
	s_nop 0
	s_nop 0
	s_nop 0
	s_nop 0
	s_nop 0
	s_nop 0
	s_nop 0
	s_nop 0
	s_nop 0
	s_nop 0
	s_nop 0
	s_nop 0
	s_nop 0
	s_nop 0
	s_nop 0
	s_nop 0
	s_nop 0
	s_nop 0
	s_nop 0
	s_nop 0
	s_nop 0
	s_nop 0
	s_nop 0
	s_mov_b32 s24, 0
	s_cmpk_lt_u32 s61, 0x100
	s_cbranch_scc1 .Lsprio_0
	s_setprio 1

; #define PG8_STAGE(bufoff, gbase, voff) do { _Pragma("unroll") for (int _i = 0; _i < 2; ++_i) \
;         __builtin_amdgcn_global_load_lds((const unsigned*)((const char*)(gbase) + (voff)[_i]), (LAS unsigned*)(lds + (bufoff) + ldsw + _i * 8192), 16, 0, 0); } while (0)
; #define PG8_LDA(dst, b, h) do { _Pragma("unroll") for (int m = 0; m < 4; ++m) _Pragma("unroll") for (int k = 0; k < 2; ++k) dst[m][k] = *(const LAS bf16x8*)(lds + PG8_SA(b, h) + aoff + m * 2048 + k * 1024); } while (0)
; #define PG8_WAIT_V(n) asm volatile("s_waitcnt vmcnt(" #n ")" ::: "memory")
; #define PG8_BAR __builtin_amdgcn_s_barrier()
; template <class Epi, class Ptrs>
; __device__ __forceinline__ void gemm_phase(LAS unsigned char* lds, const int K, const StaticOrder& S, const Ptrs& P, const Epi& E) {
;     ...
;         for (int t = 0; t < nt; t += 2) {
;             const bool last = (t == nt - 2);
;             const char* a1 = cA + (size_t)(t + 1) * kstep;
;             const char* a2 = last ? nA : cA + (size_t)(t + 2) * kstep; const char* b2 = last ? nB : cB + (size_t)(t + 2) * kstep;
;             const char* a3 = a2 + kstep; const char* b3 = b2 + kstep;
;             PG8_LDB(B0, 0, 0); PG8_SCHED; PG8_LDA(At, 0, 0); PG8_STAGE(PG8_SA(1, 1), a1 + hstep, voffA);
;             PG8_WAIT_L(8); PG8_BAR; PG8_WAIT_L(0); PG8_MMA(0, 0, At, B0); PG8_BAR; PG8_SCHED;
;             PG8_LDB(B1, 0, 1); PG8_STAGE(PG8_SB(0, 0), b2, voffB);
;             PG8_BAR; PG8_WAIT_L(0); PG8_MMA(0, 1, At, B1); PG8_BAR;
;             PG8_LDA(At, 0, 1); PG8_STAGE(PG8_SA(0, 0), a2, voffA);
;             PG8_BAR; PG8_WAIT_L(0); PG8_MMA(1, 0, At, B0); PG8_BAR; PG8_SCHED;
;             PG8_STAGE(PG8_SB(0, 1), b2 + hstep, voffB);
;             PG8_WAIT_V(6); PG8_BAR; PG8_MMA(1, 1, At, B1); PG8_BAR;
;             PG8_LDB(B0, 1, 0); PG8_SCHED; PG8_LDA(At, 1, 0); PG8_STAGE(PG8_SA(0, 1), a2 + hstep, voffA);
;             PG8_WAIT_L(8); PG8_BAR; PG8_WAIT_L(0); PG8_MMA(0, 0, At, B0); PG8_BAR; PG8_SCHED;
;             PG8_LDB(B1, 1, 1); PG8_STAGE(PG8_SB(1, 0), b3, voffB);
;             PG8_BAR; PG8_WAIT_L(0); PG8_MMA(0, 1, At, B1); PG8_BAR;
;             PG8_LDA(At, 1, 1); PG8_STAGE(PG8_SA(1, 0), a3, voffA);
;             PG8_BAR; PG8_WAIT_L(0); PG8_MMA(1, 0, At, B0); PG8_BAR; PG8_SCHED;
;             PG8_STAGE(PG8_SB(1, 1), b3 + hstep, voffB);
;             PG8_WAIT_V(6); PG8_BAR; PG8_MMA(1, 1, At, B1); PG8_BAR;
.LBB0_126:
	s_add_u32 s6, s6, 0x40080
	s_addc_u32 s7, s7, 0
	s_add_u32 s20, s78, 0x100
	s_addc_u32 s25, s79, 0
	s_mov_b32 s63, -2
	v_add_u32_e32 v252, 0x18000, v131
	v_add_u32_e32 v253, 0x1c000, v131
	ds_read_b128 v[150:153], v205
	ds_read_b128 v[154:157], v205 offset:1024
	ds_read_b128 v[158:161], v205 offset:2048
	ds_read_b128 v[162:165], v205 offset:3072
	s_add_u32 s69, s6, 0xfffc0080
	s_addc_u32 s71, s7, -1
	s_cmp_eq_u32 s63, 12
	s_cselect_b32 s81, s1, s71
	s_cselect_b32 s80, s0, s69
	s_cselect_b32 s79, s73, s25
	s_cselect_b32 s78, s72, s20
	s_add_i32 m0, s67, 0xc000
	ds_read_b128 v[166:169], v206
	ds_read_b128 v[170:173], v206 offset:1024
	ds_read_b128 v[174:177], v206 offset:2048
	ds_read_b128 v[178:181], v206 offset:3072
	ds_read_b128 v[182:185], v206 offset:4096
	ds_read_b128 v[186:189], v206 offset:5120
	ds_read_b128 v[190:193], v206 offset:6144
	ds_read_b128 v[194:197], v206 offset:7168
	global_load_lds_dwordx4 v142, s[6:7]
	s_add_i32 m0, s67, 0xe000
	s_nop 0
	global_load_lds_dwordx4 v144, s[6:7]
	s_waitcnt lgkmcnt(8)
	s_barrier
	s_waitcnt lgkmcnt(6)
	v_mfma_f32_16x16x32_bf16 v[120:123], v[150:153], v[166:169], 0
	v_mfma_f32_16x16x32_bf16 v[120:123], v[154:157], v[170:173], v[120:123]
	v_mfma_f32_16x16x32_bf16 v[116:119], v[162:165], v[170:173], 0
	v_mfma_f32_16x16x32_bf16 v[116:119], v[158:161], v[166:169], v[116:119]
	s_waitcnt lgkmcnt(4)
	v_mfma_f32_16x16x32_bf16 v[100:103], v[158:161], v[174:177], 0
	v_mfma_f32_16x16x32_bf16 v[100:103], v[162:165], v[178:181], v[100:103]
	v_mfma_f32_16x16x32_bf16 v[104:107], v[154:157], v[178:181], 0
	v_mfma_f32_16x16x32_bf16 v[104:107], v[150:153], v[174:177], v[104:107]
	s_waitcnt lgkmcnt(2)
	v_mfma_f32_16x16x32_bf16 v[88:91], v[150:153], v[182:185], 0
	v_mfma_f32_16x16x32_bf16 v[88:91], v[154:157], v[186:189], v[88:91]
	v_mfma_f32_16x16x32_bf16 v[84:87], v[162:165], v[186:189], 0
	v_mfma_f32_16x16x32_bf16 v[84:87], v[158:161], v[182:185], v[84:87]
	s_waitcnt lgkmcnt(0)
	v_mfma_f32_16x16x32_bf16 v[68:71], v[158:161], v[190:193], 0
	v_mfma_f32_16x16x32_bf16 v[68:71], v[162:165], v[194:197], v[68:71]
	v_mfma_f32_16x16x32_bf16 v[72:75], v[154:157], v[194:197], 0
	v_mfma_f32_16x16x32_bf16 v[72:75], v[150:153], v[190:193], v[72:75]
	s_barrier
	s_add_i32 s69, s91, s65
	s_add_u32 s100, s78, 0x80
	s_addc_u32 s101, s79, 0
	s_mov_b32 m0, s69
	ds_read_b128 v[198:201], v207
	ds_read_b128 v[210:213], v207 offset:1024
	ds_read_b128 v[214:217], v207 offset:2048
	ds_read_b128 v[218:221], v207 offset:3072
	global_load_lds_dwordx4 v134, s[78:79]
	s_add_i32 m0, s69, 0x2000
	s_nop 0
	global_load_lds_dwordx4 v138, s[78:79]
	s_barrier
	s_waitcnt lgkmcnt(0)
	v_mfma_f32_16x16x32_bf16 v[124:127], v[198:201], v[166:169], 0
	v_mfma_f32_16x16x32_bf16 v[124:127], v[210:213], v[170:173], v[124:127]
	v_mfma_f32_16x16x32_bf16 v[112:115], v[218:221], v[170:173], 0
	v_mfma_f32_16x16x32_bf16 v[112:115], v[214:217], v[166:169], v[112:115]
	v_mfma_f32_16x16x32_bf16 v[96:99], v[214:217], v[174:177], 0
	v_mfma_f32_16x16x32_bf16 v[96:99], v[218:221], v[178:181], v[96:99]
	v_mfma_f32_16x16x32_bf16 v[108:111], v[210:213], v[178:181], 0
	v_mfma_f32_16x16x32_bf16 v[108:111], v[198:201], v[174:177], v[108:111]
	v_mfma_f32_16x16x32_bf16 v[92:95], v[198:201], v[182:185], 0
	v_mfma_f32_16x16x32_bf16 v[92:95], v[210:213], v[186:189], v[92:95]
	v_mfma_f32_16x16x32_bf16 v[80:83], v[218:221], v[186:189], 0
	v_mfma_f32_16x16x32_bf16 v[80:83], v[214:217], v[182:185], v[80:83]
	v_mfma_f32_16x16x32_bf16 v[64:67], v[214:217], v[190:193], 0
	v_mfma_f32_16x16x32_bf16 v[64:67], v[218:221], v[194:197], v[64:67]
	v_mfma_f32_16x16x32_bf16 v[76:79], v[210:213], v[194:197], 0
	v_mfma_f32_16x16x32_bf16 v[76:79], v[198:201], v[190:193], v[76:79]
	s_barrier
	s_mov_b32 m0, s67
	ds_read_b128 v[166:169], v206 offset:16384
	ds_read_b128 v[170:173], v206 offset:17408
	ds_read_b128 v[174:177], v206 offset:18432
	ds_read_b128 v[178:181], v206 offset:19456
	ds_read_b128 v[182:185], v206 offset:20480
	ds_read_b128 v[186:189], v206 offset:21504
	ds_read_b128 v[190:193], v206 offset:22528
	ds_read_b128 v[194:197], v206 offset:23552
	global_load_lds_dwordx4 v132, s[80:81]
	s_mov_b32 m0, s75
	s_nop 0
	global_load_lds_dwordx4 v136, s[80:81]
	s_barrier
	s_waitcnt lgkmcnt(6)
	v_mfma_f32_16x16x32_bf16 v[56:59], v[150:153], v[166:169], 0
	v_mfma_f32_16x16x32_bf16 v[56:59], v[154:157], v[170:173], v[56:59]
	v_mfma_f32_16x16x32_bf16 v[52:55], v[162:165], v[170:173], 0
	v_mfma_f32_16x16x32_bf16 v[52:55], v[158:161], v[166:169], v[52:55]
	s_waitcnt lgkmcnt(4)
	v_mfma_f32_16x16x32_bf16 v[36:39], v[158:161], v[174:177], 0
	v_mfma_f32_16x16x32_bf16 v[36:39], v[162:165], v[178:181], v[36:39]
	v_mfma_f32_16x16x32_bf16 v[40:43], v[154:157], v[178:181], 0
	v_mfma_f32_16x16x32_bf16 v[40:43], v[150:153], v[174:177], v[40:43]
	s_waitcnt lgkmcnt(2)
	v_mfma_f32_16x16x32_bf16 v[24:27], v[150:153], v[182:185], 0
	v_mfma_f32_16x16x32_bf16 v[24:27], v[154:157], v[186:189], v[24:27]
	v_mfma_f32_16x16x32_bf16 v[20:23], v[162:165], v[186:189], 0
	v_mfma_f32_16x16x32_bf16 v[20:23], v[158:161], v[182:185], v[20:23]
	s_waitcnt lgkmcnt(0)
	v_mfma_f32_16x16x32_bf16 v[4:7], v[158:161], v[190:193], 0
	v_mfma_f32_16x16x32_bf16 v[4:7], v[162:165], v[194:197], v[4:7]
	v_mfma_f32_16x16x32_bf16 v[8:11], v[154:157], v[194:197], 0
	v_mfma_f32_16x16x32_bf16 v[8:11], v[150:153], v[190:193], v[8:11]
	s_barrier
	s_add_u32 s82, s78, 0x40000
	s_addc_u32 s83, s79, 0
	s_add_i32 s69, s92, s65
	s_mov_b32 m0, s69
	s_nop 0
	global_load_lds_dwordx4 v134, s[82:83]
	s_add_i32 m0, s69, 0x2000
	s_nop 0
	global_load_lds_dwordx4 v138, s[82:83]
	s_waitcnt vmcnt(6)
	s_barrier
; #define PG8_STAGE(bufoff, gbase, voff) do { _Pragma("unroll") for (int _i = 0; _i < 2; ++_i) \
;         __builtin_amdgcn_global_load_lds((const unsigned*)((const char*)(gbase) + (voff)[_i]), (LAS unsigned*)(lds + (bufoff) + ldsw + _i * 8192), 16, 0, 0); } while (0)
; #define PG8_LDA(dst, b, h) do { _Pragma("unroll") for (int m = 0; m < 4; ++m) _Pragma("unroll") for (int k = 0; k < 2; ++k) dst[m][k] = *(const LAS bf16x8*)(lds + PG8_SA(b, h) + aoff + m * 2048 + k * 1024); } while (0)
; #define PG8_LDB(dst, b, h) do { _Pragma("unroll") for (int n = 0; n < 2; ++n) _Pragma("unroll") for (int k = 0; k < 2; ++k) dst[n][k] = *(const LAS bf16x8*)(lds + PG8_SB(b, h) + boff + n * 2048 + k * 1024); } while (0)
; #define PG8_WAIT_V(n) asm volatile("s_waitcnt vmcnt(" #n ")" ::: "memory")
; #define PG8_WAIT_L(n) asm volatile("s_waitcnt lgkmcnt(" #n ")" ::: "memory")
; #define PG8_BAR __builtin_amdgcn_s_barrier()
; #define PG8_SCHED __builtin_amdgcn_sched_barrier(0)
; template <class Epi, class Ptrs>
; __device__ __forceinline__ void gemm_phase(LAS unsigned char* lds, const int K, const StaticOrder& S, const Ptrs& P, const Epi& E) {
;     ...
;             PG8_LDB(B0, 0, 0); PG8_SCHED; PG8_LDA(At, 0, 0); PG8_STAGE(PG8_SA(1, 1), a1 + hstep, voffA);
;             PG8_WAIT_L(8); PG8_BAR; PG8_WAIT_L(0); PG8_MMA(0, 0, At, B0); PG8_BAR; PG8_SCHED;
;             PG8_LDB(B1, 0, 1); PG8_STAGE(PG8_SB(0, 0), b2, voffB);
;             PG8_BAR; PG8_WAIT_L(0); PG8_MMA(0, 1, At, B1); PG8_BAR;
;             PG8_LDA(At, 0, 1); PG8_STAGE(PG8_SA(0, 0), a2, voffA);
;             PG8_BAR; PG8_WAIT_L(0); PG8_MMA(1, 0, At, B0); PG8_BAR; PG8_SCHED;
;             PG8_STAGE(PG8_SB(0, 1), b2 + hstep, voffB);
;             PG8_WAIT_V(6); PG8_BAR; PG8_MMA(1, 1, At, B1); PG8_BAR;
;             PG8_LDB(B0, 1, 0); PG8_SCHED; PG8_LDA(At, 1, 0); PG8_STAGE(PG8_SA(0, 1), a2 + hstep, voffA);
;             PG8_WAIT_L(8); PG8_BAR; PG8_WAIT_L(0); PG8_MMA(0, 0, At, B0); PG8_BAR; PG8_SCHED;
;             PG8_LDB(B1, 1, 1); PG8_STAGE(PG8_SB(1, 0), b3, voffB);
;             PG8_BAR; PG8_WAIT_L(0); PG8_MMA(0, 1, At, B1); PG8_BAR;
;             PG8_LDA(At, 1, 1); PG8_STAGE(PG8_SA(1, 0), a3, voffA);
;             PG8_BAR; PG8_WAIT_L(0); PG8_MMA(1, 0, At, B0); PG8_BAR; PG8_SCHED;
;             PG8_STAGE(PG8_SB(1, 1), b3 + hstep, voffB);
;             PG8_WAIT_V(6); PG8_BAR; PG8_MMA(1, 1, At, B1); PG8_BAR;
	v_mfma_f32_16x16x32_bf16 v[60:63], v[198:201], v[166:169], 0
	v_mfma_f32_16x16x32_bf16 v[60:63], v[210:213], v[170:173], v[60:63]
	v_mfma_f32_16x16x32_bf16 v[48:51], v[218:221], v[170:173], 0
	v_mfma_f32_16x16x32_bf16 v[48:51], v[214:217], v[166:169], v[48:51]
	v_mfma_f32_16x16x32_bf16 v[32:35], v[214:217], v[174:177], 0
	v_mfma_f32_16x16x32_bf16 v[32:35], v[218:221], v[178:181], v[32:35]
	v_mfma_f32_16x16x32_bf16 v[44:47], v[210:213], v[178:181], 0
	v_mfma_f32_16x16x32_bf16 v[44:47], v[198:201], v[174:177], v[44:47]
	v_mfma_f32_16x16x32_bf16 v[28:31], v[198:201], v[182:185], 0
	v_mfma_f32_16x16x32_bf16 v[28:31], v[210:213], v[186:189], v[28:31]
	v_mfma_f32_16x16x32_bf16 v[16:19], v[218:221], v[186:189], 0
	v_mfma_f32_16x16x32_bf16 v[16:19], v[214:217], v[182:185], v[16:19]
	v_mfma_f32_16x16x32_bf16 v[0:3], v[214:217], v[190:193], 0
	v_mfma_f32_16x16x32_bf16 v[0:3], v[218:221], v[194:197], v[0:3]
	v_mfma_f32_16x16x32_bf16 v[12:15], v[210:213], v[194:197], 0
	v_mfma_f32_16x16x32_bf16 v[12:15], v[198:201], v[190:193], v[12:15]
	s_barrier
	s_add_i32 s69, 0, 0x18000
	ds_read_b128 v[150:153], v252
	ds_read_b128 v[154:157], v252 offset:1024
	ds_read_b128 v[158:161], v252 offset:2048
	ds_read_b128 v[162:165], v252 offset:3072
	s_add_u32 s80, s80, 0x40000
	s_addc_u32 s81, s81, 0
	s_mov_b32 m0, s77
	ds_read_b128 v[166:169], v206 offset:32768
	ds_read_b128 v[170:173], v206 offset:33792
	ds_read_b128 v[174:177], v206 offset:34816
	ds_read_b128 v[178:181], v206 offset:35840
	ds_read_b128 v[182:185], v206 offset:36864
	ds_read_b128 v[186:189], v206 offset:37888
	ds_read_b128 v[190:193], v206 offset:38912
	ds_read_b128 v[194:197], v206 offset:39936
	global_load_lds_dwordx4 v132, s[80:81]
	s_mov_b32 m0, s85
	s_nop 0
	global_load_lds_dwordx4 v136, s[80:81]
	s_waitcnt lgkmcnt(8)
	s_barrier
	s_waitcnt lgkmcnt(6)
	v_mfma_f32_16x16x32_bf16 v[120:123], v[150:153], v[166:169], v[120:123]
	v_mfma_f32_16x16x32_bf16 v[120:123], v[154:157], v[170:173], v[120:123]
	v_mfma_f32_16x16x32_bf16 v[116:119], v[162:165], v[170:173], v[116:119]
	v_mfma_f32_16x16x32_bf16 v[116:119], v[158:161], v[166:169], v[116:119]
	s_waitcnt lgkmcnt(4)
	v_mfma_f32_16x16x32_bf16 v[100:103], v[158:161], v[174:177], v[100:103]
	v_mfma_f32_16x16x32_bf16 v[100:103], v[162:165], v[178:181], v[100:103]
	v_mfma_f32_16x16x32_bf16 v[104:107], v[154:157], v[178:181], v[104:107]
	v_mfma_f32_16x16x32_bf16 v[104:107], v[150:153], v[174:177], v[104:107]
	s_waitcnt lgkmcnt(2)
	v_mfma_f32_16x16x32_bf16 v[88:91], v[150:153], v[182:185], v[88:91]
	v_mfma_f32_16x16x32_bf16 v[88:91], v[154:157], v[186:189], v[88:91]
	v_mfma_f32_16x16x32_bf16 v[84:87], v[162:165], v[186:189], v[84:87]
	v_mfma_f32_16x16x32_bf16 v[84:87], v[158:161], v[182:185], v[84:87]
	s_waitcnt lgkmcnt(0)
	v_mfma_f32_16x16x32_bf16 v[68:71], v[158:161], v[190:193], v[68:71]
	v_mfma_f32_16x16x32_bf16 v[68:71], v[162:165], v[194:197], v[68:71]
	v_mfma_f32_16x16x32_bf16 v[72:75], v[154:157], v[194:197], v[72:75]
	v_mfma_f32_16x16x32_bf16 v[72:75], v[150:153], v[190:193], v[72:75]
	s_barrier
	s_add_i32 s71, 0, 0x1c000
	s_add_i32 s69, s69, s65
	s_mov_b32 m0, s69
	ds_read_b128 v[198:201], v253
	ds_read_b128 v[210:213], v253 offset:1024
	ds_read_b128 v[214:217], v253 offset:2048
	ds_read_b128 v[218:221], v253 offset:3072
	global_load_lds_dwordx4 v134, s[100:101]
	s_add_i32 m0, s69, 0x2000
	s_nop 0
	global_load_lds_dwordx4 v138, s[100:101]
	s_barrier
	s_waitcnt lgkmcnt(0)
	v_mfma_f32_16x16x32_bf16 v[124:127], v[198:201], v[166:169], v[124:127]
	v_mfma_f32_16x16x32_bf16 v[124:127], v[210:213], v[170:173], v[124:127]
	v_mfma_f32_16x16x32_bf16 v[112:115], v[218:221], v[170:173], v[112:115]
	v_mfma_f32_16x16x32_bf16 v[112:115], v[214:217], v[166:169], v[112:115]
	v_mfma_f32_16x16x32_bf16 v[96:99], v[214:217], v[174:177], v[96:99]
	v_mfma_f32_16x16x32_bf16 v[96:99], v[218:221], v[178:181], v[96:99]
	v_mfma_f32_16x16x32_bf16 v[108:111], v[210:213], v[178:181], v[108:111]
	v_mfma_f32_16x16x32_bf16 v[108:111], v[198:201], v[174:177], v[108:111]
	v_mfma_f32_16x16x32_bf16 v[92:95], v[198:201], v[182:185], v[92:95]
	v_mfma_f32_16x16x32_bf16 v[92:95], v[210:213], v[186:189], v[92:95]
	v_mfma_f32_16x16x32_bf16 v[80:83], v[218:221], v[186:189], v[80:83]
	v_mfma_f32_16x16x32_bf16 v[80:83], v[214:217], v[182:185], v[80:83]
	v_mfma_f32_16x16x32_bf16 v[64:67], v[214:217], v[190:193], v[64:67]
	v_mfma_f32_16x16x32_bf16 v[64:67], v[218:221], v[194:197], v[64:67]
	v_mfma_f32_16x16x32_bf16 v[76:79], v[210:213], v[194:197], v[76:79]
	v_mfma_f32_16x16x32_bf16 v[76:79], v[198:201], v[190:193], v[76:79]
	s_barrier
	s_mov_b32 m0, s89
	s_add_u32 s100, s80, 0xfffc0080
	s_addc_u32 s101, s81, -1
	ds_read_b128 v[166:169], v206 offset:49152
	ds_read_b128 v[170:173], v206 offset:50176
	ds_read_b128 v[174:177], v206 offset:51200
	ds_read_b128 v[178:181], v206 offset:52224
	ds_read_b128 v[182:185], v206 offset:53248
	ds_read_b128 v[186:189], v206 offset:54272
	ds_read_b128 v[190:193], v206 offset:55296
	ds_read_b128 v[194:197], v206 offset:56320
	global_load_lds_dwordx4 v132, s[100:101]
	s_mov_b32 m0, s90
	s_nop 0
	global_load_lds_dwordx4 v136, s[100:101]
	s_barrier
; #define PG8_STAGE(bufoff, gbase, voff) do { _Pragma("unroll") for (int _i = 0; _i < 2; ++_i) \
;         __builtin_amdgcn_global_load_lds((const unsigned*)((const char*)(gbase) + (voff)[_i]), (LAS unsigned*)(lds + (bufoff) + ldsw + _i * 8192), 16, 0, 0); } while (0)
; #define PG8_LDA(dst, b, h) do { _Pragma("unroll") for (int m = 0; m < 4; ++m) _Pragma("unroll") for (int k = 0; k < 2; ++k) dst[m][k] = *(const LAS bf16x8*)(lds + PG8_SA(b, h) + aoff + m * 2048 + k * 1024); } while (0)
; #define PG8_WAIT_V(n) asm volatile("s_waitcnt vmcnt(" #n ")" ::: "memory")
; #define PG8_BAR __builtin_amdgcn_s_barrier()
; template <class Epi, class Ptrs>
; __device__ __forceinline__ void gemm_phase(LAS unsigned char* lds, const int K, const StaticOrder& S, const Ptrs& P, const Epi& E) {
;     ...
;         for (int t = 0; t < nt; t += 2) {
;             const bool last = (t == nt - 2);
;             const char* a1 = cA + (size_t)(t + 1) * kstep;
;             const char* a2 = last ? nA : cA + (size_t)(t + 2) * kstep; const char* b2 = last ? nB : cB + (size_t)(t + 2) * kstep;
;             const char* a3 = a2 + kstep; const char* b3 = b2 + kstep;
;             PG8_LDB(B0, 0, 0); PG8_SCHED; PG8_LDA(At, 0, 0); PG8_STAGE(PG8_SA(1, 1), a1 + hstep, voffA);
;             PG8_WAIT_L(8); PG8_BAR; PG8_WAIT_L(0); PG8_MMA(0, 0, At, B0); PG8_BAR; PG8_SCHED;
;             PG8_LDB(B1, 0, 1); PG8_STAGE(PG8_SB(0, 0), b2, voffB);
;             PG8_BAR; PG8_WAIT_L(0); PG8_MMA(0, 1, At, B1); PG8_BAR;
;             PG8_LDA(At, 0, 1); PG8_STAGE(PG8_SA(0, 0), a2, voffA);
;             PG8_BAR; PG8_WAIT_L(0); PG8_MMA(1, 0, At, B0); PG8_BAR; PG8_SCHED;
;             PG8_STAGE(PG8_SB(0, 1), b2 + hstep, voffB);
;             PG8_WAIT_V(6); PG8_BAR; PG8_MMA(1, 1, At, B1); PG8_BAR;
;             PG8_LDB(B0, 1, 0); PG8_SCHED; PG8_LDA(At, 1, 0); PG8_STAGE(PG8_SA(0, 1), a2 + hstep, voffA);
;             PG8_WAIT_L(8); PG8_BAR; PG8_WAIT_L(0); PG8_MMA(0, 0, At, B0); PG8_BAR; PG8_SCHED;
;             PG8_LDB(B1, 1, 1); PG8_STAGE(PG8_SB(1, 0), b3, voffB);
;             PG8_BAR; PG8_WAIT_L(0); PG8_MMA(0, 1, At, B1); PG8_BAR;
;             PG8_LDA(At, 1, 1); PG8_STAGE(PG8_SA(1, 0), a3, voffA);
;             PG8_BAR; PG8_WAIT_L(0); PG8_MMA(1, 0, At, B0); PG8_BAR; PG8_SCHED;
;             PG8_STAGE(PG8_SB(1, 1), b3 + hstep, voffB);
;             PG8_WAIT_V(6); PG8_BAR; PG8_MMA(1, 1, At, B1); PG8_BAR;
	s_waitcnt lgkmcnt(6)
	v_mfma_f32_16x16x32_bf16 v[56:59], v[150:153], v[166:169], v[56:59]
	v_mfma_f32_16x16x32_bf16 v[56:59], v[154:157], v[170:173], v[56:59]
	v_mfma_f32_16x16x32_bf16 v[52:55], v[162:165], v[170:173], v[52:55]
	v_mfma_f32_16x16x32_bf16 v[52:55], v[158:161], v[166:169], v[52:55]
	s_waitcnt lgkmcnt(4)
	v_mfma_f32_16x16x32_bf16 v[36:39], v[158:161], v[174:177], v[36:39]
	v_mfma_f32_16x16x32_bf16 v[36:39], v[162:165], v[178:181], v[36:39]
	v_mfma_f32_16x16x32_bf16 v[40:43], v[154:157], v[178:181], v[40:43]
	v_mfma_f32_16x16x32_bf16 v[40:43], v[150:153], v[174:177], v[40:43]
	s_waitcnt lgkmcnt(2)
	v_mfma_f32_16x16x32_bf16 v[24:27], v[150:153], v[182:185], v[24:27]
	v_mfma_f32_16x16x32_bf16 v[24:27], v[154:157], v[186:189], v[24:27]
	v_mfma_f32_16x16x32_bf16 v[20:23], v[162:165], v[186:189], v[20:23]
	v_mfma_f32_16x16x32_bf16 v[20:23], v[158:161], v[182:185], v[20:23]
	s_waitcnt lgkmcnt(0)
	v_mfma_f32_16x16x32_bf16 v[4:7], v[158:161], v[190:193], v[4:7]
	v_mfma_f32_16x16x32_bf16 v[4:7], v[162:165], v[194:197], v[4:7]
	v_mfma_f32_16x16x32_bf16 v[8:11], v[154:157], v[194:197], v[8:11]
	v_mfma_f32_16x16x32_bf16 v[8:11], v[150:153], v[190:193], v[8:11]
	s_barrier
	s_add_u32 s78, s78, 0x40080
	s_addc_u32 s79, s79, 0
	s_add_i32 s69, s71, s65
	s_mov_b32 m0, s69
	s_nop 0
	global_load_lds_dwordx4 v134, s[78:79]
	s_add_i32 m0, s69, 0x2000
	s_nop 0
	global_load_lds_dwordx4 v138, s[78:79]
	s_waitcnt vmcnt(6)
	s_barrier
	v_mfma_f32_16x16x32_bf16 v[60:63], v[198:201], v[166:169], v[60:63]
	v_mfma_f32_16x16x32_bf16 v[60:63], v[210:213], v[170:173], v[60:63]
	v_mfma_f32_16x16x32_bf16 v[48:51], v[218:221], v[170:173], v[48:51]
	v_mfma_f32_16x16x32_bf16 v[48:51], v[214:217], v[166:169], v[48:51]
	v_mfma_f32_16x16x32_bf16 v[32:35], v[214:217], v[174:177], v[32:35]
	v_mfma_f32_16x16x32_bf16 v[32:35], v[218:221], v[178:181], v[32:35]
	v_mfma_f32_16x16x32_bf16 v[44:47], v[210:213], v[178:181], v[44:47]
	v_mfma_f32_16x16x32_bf16 v[44:47], v[198:201], v[174:177], v[44:47]
	v_mfma_f32_16x16x32_bf16 v[28:31], v[198:201], v[182:185], v[28:31]
	v_mfma_f32_16x16x32_bf16 v[28:31], v[210:213], v[186:189], v[28:31]
	v_mfma_f32_16x16x32_bf16 v[16:19], v[218:221], v[186:189], v[16:19]
	v_mfma_f32_16x16x32_bf16 v[16:19], v[214:217], v[182:185], v[16:19]
	v_mfma_f32_16x16x32_bf16 v[0:3], v[214:217], v[190:193], v[0:3]
	v_mfma_f32_16x16x32_bf16 v[0:3], v[218:221], v[194:197], v[0:3]
	v_mfma_f32_16x16x32_bf16 v[12:15], v[210:213], v[194:197], v[12:15]
	v_mfma_f32_16x16x32_bf16 v[12:15], v[198:201], v[190:193], v[12:15]
	s_barrier
	s_add_i32 s63, s63, 2
	s_add_u32 s6, s6, 0x100
	s_addc_u32 s7, s7, 0
	s_add_u32 s20, s20, 0x100
	s_addc_u32 s25, s25, 0
	s_cmp_gt_u32 s63, 13
.LBB0_127:
	ds_read_b128 v[150:153], v205
	ds_read_b128 v[154:157], v205 offset:1024
	ds_read_b128 v[158:161], v205 offset:2048
	ds_read_b128 v[162:165], v205 offset:3072
	s_add_u32 s69, s6, 0xfffc0080
	s_addc_u32 s71, s7, -1
	s_cmp_eq_u32 s63, 12
	s_cselect_b32 s81, s1, s71
	s_cselect_b32 s80, s0, s69
	s_cselect_b32 s79, s73, s25
	s_cselect_b32 s78, s72, s20
	s_add_i32 m0, s67, 0xc000
	ds_read_b128 v[166:169], v206
	ds_read_b128 v[170:173], v206 offset:1024
	ds_read_b128 v[174:177], v206 offset:2048
	ds_read_b128 v[178:181], v206 offset:3072
	ds_read_b128 v[182:185], v206 offset:4096
	ds_read_b128 v[186:189], v206 offset:5120
	ds_read_b128 v[190:193], v206 offset:6144
	ds_read_b128 v[194:197], v206 offset:7168
	global_load_lds_dwordx4 v142, s[6:7]
	s_add_i32 m0, s67, 0xe000
	s_nop 0
	global_load_lds_dwordx4 v144, s[6:7]
	s_waitcnt lgkmcnt(8)
	s_barrier
	s_waitcnt lgkmcnt(6)
	v_mfma_f32_16x16x32_bf16 v[120:123], v[150:153], v[166:169], v[120:123]
	v_mfma_f32_16x16x32_bf16 v[120:123], v[154:157], v[170:173], v[120:123]
	v_mfma_f32_16x16x32_bf16 v[116:119], v[162:165], v[170:173], v[116:119]
	v_mfma_f32_16x16x32_bf16 v[116:119], v[158:161], v[166:169], v[116:119]
	s_waitcnt lgkmcnt(4)
	v_mfma_f32_16x16x32_bf16 v[100:103], v[158:161], v[174:177], v[100:103]
	v_mfma_f32_16x16x32_bf16 v[100:103], v[162:165], v[178:181], v[100:103]
	v_mfma_f32_16x16x32_bf16 v[104:107], v[154:157], v[178:181], v[104:107]
	v_mfma_f32_16x16x32_bf16 v[104:107], v[150:153], v[174:177], v[104:107]
	s_waitcnt lgkmcnt(2)
	v_mfma_f32_16x16x32_bf16 v[88:91], v[150:153], v[182:185], v[88:91]
	v_mfma_f32_16x16x32_bf16 v[88:91], v[154:157], v[186:189], v[88:91]
	v_mfma_f32_16x16x32_bf16 v[84:87], v[162:165], v[186:189], v[84:87]
	v_mfma_f32_16x16x32_bf16 v[84:87], v[158:161], v[182:185], v[84:87]
	s_waitcnt lgkmcnt(0)
	v_mfma_f32_16x16x32_bf16 v[68:71], v[158:161], v[190:193], v[68:71]
	v_mfma_f32_16x16x32_bf16 v[68:71], v[162:165], v[194:197], v[68:71]
	v_mfma_f32_16x16x32_bf16 v[72:75], v[154:157], v[194:197], v[72:75]
	v_mfma_f32_16x16x32_bf16 v[72:75], v[150:153], v[190:193], v[72:75]
	s_barrier
	s_add_i32 s69, s91, s65
	s_add_u32 s100, s78, 0x80
	s_addc_u32 s101, s79, 0
	s_mov_b32 m0, s69
	ds_read_b128 v[198:201], v207
	ds_read_b128 v[210:213], v207 offset:1024
	ds_read_b128 v[214:217], v207 offset:2048
	ds_read_b128 v[218:221], v207 offset:3072
	global_load_lds_dwordx4 v134, s[78:79]
	s_add_i32 m0, s69, 0x2000
	s_nop 0
	global_load_lds_dwordx4 v138, s[78:79]
	s_barrier
; #define PG8_STAGE(bufoff, gbase, voff) do { _Pragma("unroll") for (int _i = 0; _i < 2; ++_i) \
;         __builtin_amdgcn_global_load_lds((const unsigned*)((const char*)(gbase) + (voff)[_i]), (LAS unsigned*)(lds + (bufoff) + ldsw + _i * 8192), 16, 0, 0); } while (0)
; #define PG8_LDA(dst, b, h) do { _Pragma("unroll") for (int m = 0; m < 4; ++m) _Pragma("unroll") for (int k = 0; k < 2; ++k) dst[m][k] = *(const LAS bf16x8*)(lds + PG8_SA(b, h) + aoff + m * 2048 + k * 1024); } while (0)
; #define PG8_WAIT_V(n) asm volatile("s_waitcnt vmcnt(" #n ")" ::: "memory")
; #define PG8_BAR __builtin_amdgcn_s_barrier()
; template <class Epi, class Ptrs>
; __device__ __forceinline__ void gemm_phase(LAS unsigned char* lds, const int K, const StaticOrder& S, const Ptrs& P, const Epi& E) {
;     ...
;         for (int t = 0; t < nt; t += 2) {
;             const bool last = (t == nt - 2);
;             const char* a1 = cA + (size_t)(t + 1) * kstep;
;             const char* a2 = last ? nA : cA + (size_t)(t + 2) * kstep; const char* b2 = last ? nB : cB + (size_t)(t + 2) * kstep;
;             const char* a3 = a2 + kstep; const char* b3 = b2 + kstep;
;             PG8_LDB(B0, 0, 0); PG8_SCHED; PG8_LDA(At, 0, 0); PG8_STAGE(PG8_SA(1, 1), a1 + hstep, voffA);
;             PG8_WAIT_L(8); PG8_BAR; PG8_WAIT_L(0); PG8_MMA(0, 0, At, B0); PG8_BAR; PG8_SCHED;
;             PG8_LDB(B1, 0, 1); PG8_STAGE(PG8_SB(0, 0), b2, voffB);
;             PG8_BAR; PG8_WAIT_L(0); PG8_MMA(0, 1, At, B1); PG8_BAR;
;             PG8_LDA(At, 0, 1); PG8_STAGE(PG8_SA(0, 0), a2, voffA);
;             PG8_BAR; PG8_WAIT_L(0); PG8_MMA(1, 0, At, B0); PG8_BAR; PG8_SCHED;
;             PG8_STAGE(PG8_SB(0, 1), b2 + hstep, voffB);
;             PG8_WAIT_V(6); PG8_BAR; PG8_MMA(1, 1, At, B1); PG8_BAR;
;             PG8_LDB(B0, 1, 0); PG8_SCHED; PG8_LDA(At, 1, 0); PG8_STAGE(PG8_SA(0, 1), a2 + hstep, voffA);
;             PG8_WAIT_L(8); PG8_BAR; PG8_WAIT_L(0); PG8_MMA(0, 0, At, B0); PG8_BAR; PG8_SCHED;
;             PG8_LDB(B1, 1, 1); PG8_STAGE(PG8_SB(1, 0), b3, voffB);
;             PG8_BAR; PG8_WAIT_L(0); PG8_MMA(0, 1, At, B1); PG8_BAR;
;             PG8_LDA(At, 1, 1); PG8_STAGE(PG8_SA(1, 0), a3, voffA);
;             PG8_BAR; PG8_WAIT_L(0); PG8_MMA(1, 0, At, B0); PG8_BAR; PG8_SCHED;
;             PG8_STAGE(PG8_SB(1, 1), b3 + hstep, voffB);
;             PG8_WAIT_V(6); PG8_BAR; PG8_MMA(1, 1, At, B1); PG8_BAR;
	s_waitcnt lgkmcnt(0)
	v_mfma_f32_16x16x32_bf16 v[124:127], v[198:201], v[166:169], v[124:127]
	v_mfma_f32_16x16x32_bf16 v[124:127], v[210:213], v[170:173], v[124:127]
	v_mfma_f32_16x16x32_bf16 v[112:115], v[218:221], v[170:173], v[112:115]
	v_mfma_f32_16x16x32_bf16 v[112:115], v[214:217], v[166:169], v[112:115]
	v_mfma_f32_16x16x32_bf16 v[96:99], v[214:217], v[174:177], v[96:99]
	v_mfma_f32_16x16x32_bf16 v[96:99], v[218:221], v[178:181], v[96:99]
	v_mfma_f32_16x16x32_bf16 v[108:111], v[210:213], v[178:181], v[108:111]
	v_mfma_f32_16x16x32_bf16 v[108:111], v[198:201], v[174:177], v[108:111]
	v_mfma_f32_16x16x32_bf16 v[92:95], v[198:201], v[182:185], v[92:95]
	v_mfma_f32_16x16x32_bf16 v[92:95], v[210:213], v[186:189], v[92:95]
	v_mfma_f32_16x16x32_bf16 v[80:83], v[218:221], v[186:189], v[80:83]
	v_mfma_f32_16x16x32_bf16 v[80:83], v[214:217], v[182:185], v[80:83]
	v_mfma_f32_16x16x32_bf16 v[64:67], v[214:217], v[190:193], v[64:67]
	v_mfma_f32_16x16x32_bf16 v[64:67], v[218:221], v[194:197], v[64:67]
	v_mfma_f32_16x16x32_bf16 v[76:79], v[210:213], v[194:197], v[76:79]
	v_mfma_f32_16x16x32_bf16 v[76:79], v[198:201], v[190:193], v[76:79]
	s_barrier
	s_mov_b32 m0, s67
	ds_read_b128 v[166:169], v206 offset:16384
	ds_read_b128 v[170:173], v206 offset:17408
	ds_read_b128 v[174:177], v206 offset:18432
	ds_read_b128 v[178:181], v206 offset:19456
	ds_read_b128 v[182:185], v206 offset:20480
	ds_read_b128 v[186:189], v206 offset:21504
	ds_read_b128 v[190:193], v206 offset:22528
	ds_read_b128 v[194:197], v206 offset:23552
	global_load_lds_dwordx4 v132, s[80:81]
	s_mov_b32 m0, s75
	s_nop 0
	global_load_lds_dwordx4 v136, s[80:81]
	s_barrier
	s_waitcnt lgkmcnt(6)
	v_mfma_f32_16x16x32_bf16 v[56:59], v[150:153], v[166:169], v[56:59]
	v_mfma_f32_16x16x32_bf16 v[56:59], v[154:157], v[170:173], v[56:59]
	v_mfma_f32_16x16x32_bf16 v[52:55], v[162:165], v[170:173], v[52:55]
	v_mfma_f32_16x16x32_bf16 v[52:55], v[158:161], v[166:169], v[52:55]
	s_waitcnt lgkmcnt(4)
	v_mfma_f32_16x16x32_bf16 v[36:39], v[158:161], v[174:177], v[36:39]
	v_mfma_f32_16x16x32_bf16 v[36:39], v[162:165], v[178:181], v[36:39]
	v_mfma_f32_16x16x32_bf16 v[40:43], v[154:157], v[178:181], v[40:43]
	v_mfma_f32_16x16x32_bf16 v[40:43], v[150:153], v[174:177], v[40:43]
	s_waitcnt lgkmcnt(2)
	v_mfma_f32_16x16x32_bf16 v[24:27], v[150:153], v[182:185], v[24:27]
	v_mfma_f32_16x16x32_bf16 v[24:27], v[154:157], v[186:189], v[24:27]
	v_mfma_f32_16x16x32_bf16 v[20:23], v[162:165], v[186:189], v[20:23]
	v_mfma_f32_16x16x32_bf16 v[20:23], v[158:161], v[182:185], v[20:23]
	s_waitcnt lgkmcnt(0)
	v_mfma_f32_16x16x32_bf16 v[4:7], v[158:161], v[190:193], v[4:7]
	v_mfma_f32_16x16x32_bf16 v[4:7], v[162:165], v[194:197], v[4:7]
	v_mfma_f32_16x16x32_bf16 v[8:11], v[154:157], v[194:197], v[8:11]
	v_mfma_f32_16x16x32_bf16 v[8:11], v[150:153], v[190:193], v[8:11]
	s_barrier
	s_add_u32 s82, s78, 0x40000
	s_addc_u32 s83, s79, 0
	s_add_i32 s69, s92, s65
	s_mov_b32 m0, s69
	s_nop 0
	global_load_lds_dwordx4 v134, s[82:83]
	s_add_i32 m0, s69, 0x2000
	s_nop 0
	global_load_lds_dwordx4 v138, s[82:83]
	s_waitcnt vmcnt(6)
	s_barrier
	v_mfma_f32_16x16x32_bf16 v[60:63], v[198:201], v[166:169], v[60:63]
	v_mfma_f32_16x16x32_bf16 v[60:63], v[210:213], v[170:173], v[60:63]
	v_mfma_f32_16x16x32_bf16 v[48:51], v[218:221], v[170:173], v[48:51]
	v_mfma_f32_16x16x32_bf16 v[48:51], v[214:217], v[166:169], v[48:51]
	v_mfma_f32_16x16x32_bf16 v[32:35], v[214:217], v[174:177], v[32:35]
	v_mfma_f32_16x16x32_bf16 v[32:35], v[218:221], v[178:181], v[32:35]
	v_mfma_f32_16x16x32_bf16 v[44:47], v[210:213], v[178:181], v[44:47]
	v_mfma_f32_16x16x32_bf16 v[44:47], v[198:201], v[174:177], v[44:47]
	v_mfma_f32_16x16x32_bf16 v[28:31], v[198:201], v[182:185], v[28:31]
	v_mfma_f32_16x16x32_bf16 v[28:31], v[210:213], v[186:189], v[28:31]
	v_mfma_f32_16x16x32_bf16 v[16:19], v[218:221], v[186:189], v[16:19]
	v_mfma_f32_16x16x32_bf16 v[16:19], v[214:217], v[182:185], v[16:19]
	v_mfma_f32_16x16x32_bf16 v[0:3], v[214:217], v[190:193], v[0:3]
	v_mfma_f32_16x16x32_bf16 v[0:3], v[218:221], v[194:197], v[0:3]
	v_mfma_f32_16x16x32_bf16 v[12:15], v[210:213], v[194:197], v[12:15]
	v_mfma_f32_16x16x32_bf16 v[12:15], v[198:201], v[190:193], v[12:15]
	s_barrier
	s_add_i32 s69, 0, 0x18000
	ds_read_b128 v[150:153], v252
	ds_read_b128 v[154:157], v252 offset:1024
	ds_read_b128 v[158:161], v252 offset:2048
	ds_read_b128 v[162:165], v252 offset:3072
	s_add_u32 s80, s80, 0x40000
	s_addc_u32 s81, s81, 0
	s_mov_b32 m0, s77
	ds_read_b128 v[166:169], v206 offset:32768
	ds_read_b128 v[170:173], v206 offset:33792
	ds_read_b128 v[174:177], v206 offset:34816
	ds_read_b128 v[178:181], v206 offset:35840
	ds_read_b128 v[182:185], v206 offset:36864
	ds_read_b128 v[186:189], v206 offset:37888
	ds_read_b128 v[190:193], v206 offset:38912
	ds_read_b128 v[194:197], v206 offset:39936
	global_load_lds_dwordx4 v132, s[80:81]
	s_mov_b32 m0, s85
	s_nop 0
	global_load_lds_dwordx4 v136, s[80:81]
	s_waitcnt lgkmcnt(8)
	s_barrier
	s_waitcnt lgkmcnt(6)
	v_mfma_f32_16x16x32_bf16 v[120:123], v[150:153], v[166:169], v[120:123]
	v_mfma_f32_16x16x32_bf16 v[120:123], v[154:157], v[170:173], v[120:123]
	v_mfma_f32_16x16x32_bf16 v[116:119], v[162:165], v[170:173], v[116:119]
	v_mfma_f32_16x16x32_bf16 v[116:119], v[158:161], v[166:169], v[116:119]
	s_waitcnt lgkmcnt(4)
	v_mfma_f32_16x16x32_bf16 v[100:103], v[158:161], v[174:177], v[100:103]
	v_mfma_f32_16x16x32_bf16 v[100:103], v[162:165], v[178:181], v[100:103]
	v_mfma_f32_16x16x32_bf16 v[104:107], v[154:157], v[178:181], v[104:107]
	v_mfma_f32_16x16x32_bf16 v[104:107], v[150:153], v[174:177], v[104:107]
	s_waitcnt lgkmcnt(2)
	v_mfma_f32_16x16x32_bf16 v[88:91], v[150:153], v[182:185], v[88:91]
	v_mfma_f32_16x16x32_bf16 v[88:91], v[154:157], v[186:189], v[88:91]
	v_mfma_f32_16x16x32_bf16 v[84:87], v[162:165], v[186:189], v[84:87]
	v_mfma_f32_16x16x32_bf16 v[84:87], v[158:161], v[182:185], v[84:87]
	s_waitcnt lgkmcnt(0)
	v_mfma_f32_16x16x32_bf16 v[68:71], v[158:161], v[190:193], v[68:71]
	v_mfma_f32_16x16x32_bf16 v[68:71], v[162:165], v[194:197], v[68:71]
	v_mfma_f32_16x16x32_bf16 v[72:75], v[154:157], v[194:197], v[72:75]
	v_mfma_f32_16x16x32_bf16 v[72:75], v[150:153], v[190:193], v[72:75]
	s_barrier
; #define PG8_BAR __builtin_amdgcn_s_barrier()
; template <class Epi, class Ptrs>
; __device__ __forceinline__ void gemm_phase(LAS unsigned char* lds, const int K, const StaticOrder& S, const Ptrs& P, const Epi& E) {
;     ...
;         for (int t = 0; t < nt; t += 2) {
;             const bool last = (t == nt - 2);
;             const char* a1 = cA + (size_t)(t + 1) * kstep;
;             const char* a2 = last ? nA : cA + (size_t)(t + 2) * kstep; const char* b2 = last ? nB : cB + (size_t)(t + 2) * kstep;
;             const char* a3 = a2 + kstep; const char* b3 = b2 + kstep;
;             PG8_LDB(B0, 0, 0); PG8_SCHED; PG8_LDA(At, 0, 0); PG8_STAGE(PG8_SA(1, 1), a1 + hstep, voffA);
;             PG8_WAIT_L(8); PG8_BAR; PG8_WAIT_L(0); PG8_MMA(0, 0, At, B0); PG8_BAR; PG8_SCHED;
;             PG8_LDB(B1, 0, 1); PG8_STAGE(PG8_SB(0, 0), b2, voffB);
;             PG8_BAR; PG8_WAIT_L(0); PG8_MMA(0, 1, At, B1); PG8_BAR;
;             PG8_LDA(At, 0, 1); PG8_STAGE(PG8_SA(0, 0), a2, voffA);
;             PG8_BAR; PG8_WAIT_L(0); PG8_MMA(1, 0, At, B0); PG8_BAR; PG8_SCHED;
;             PG8_STAGE(PG8_SB(0, 1), b2 + hstep, voffB);
;             PG8_WAIT_V(6); PG8_BAR; PG8_MMA(1, 1, At, B1); PG8_BAR;
;             PG8_LDB(B0, 1, 0); PG8_SCHED; PG8_LDA(At, 1, 0); PG8_STAGE(PG8_SA(0, 1), a2 + hstep, voffA);
;             PG8_WAIT_L(8); PG8_BAR; PG8_WAIT_L(0); PG8_MMA(0, 0, At, B0); PG8_BAR; PG8_SCHED;
;             PG8_LDB(B1, 1, 1); PG8_STAGE(PG8_SB(1, 0), b3, voffB);
;             PG8_BAR; PG8_WAIT_L(0); PG8_MMA(0, 1, At, B1); PG8_BAR;
;             PG8_LDA(At, 1, 1); PG8_STAGE(PG8_SA(1, 0), a3, voffA);
;             PG8_BAR; PG8_WAIT_L(0); PG8_MMA(1, 0, At, B0); PG8_BAR; PG8_SCHED;
;             PG8_STAGE(PG8_SB(1, 1), b3 + hstep, voffB);
;             PG8_WAIT_V(6); PG8_BAR; PG8_MMA(1, 1, At, B1); PG8_BAR;
;     __device__ __forceinline__ void operator()(const f32x4 (&acc)[2][2][4][2], const Unit& u, int ui, int wr, int wc, int fr, int fq) const {
;         const int pn = u.pn;
;         if (pn < 8) {
;             bf16_t* base = (bf16_t*)(ws + WS_U) + (size_t)(u.pm * 256 + wr * 64 + fr) * DM + pn * 128 + wc * 32 + 8 * fq;
; #pragma unroll
;             for (int ai = 0; ai < 2; ++ai)
; #pragma unroll
;                 for (int m = 0; m < 4; ++m) {
;                     const f32x4 g0 = g1_4(acc[ai][0][m][0], acc[ai][1][m][0]), g1 = g1_4(acc[ai][0][m][1], acc[ai][1][m][1]);
	s_add_i32 s71, 0, 0x1c000
	s_add_i32 s69, s69, s65
	s_mov_b32 m0, s69
	ds_read_b128 v[198:201], v253
	ds_read_b128 v[210:213], v253 offset:1024
	ds_read_b128 v[214:217], v253 offset:2048
	ds_read_b128 v[218:221], v253 offset:3072
	global_load_lds_dwordx4 v134, s[100:101]
	s_add_i32 m0, s69, 0x2000
	s_nop 0
	global_load_lds_dwordx4 v138, s[100:101]
	s_barrier
	s_waitcnt lgkmcnt(0)
	v_mfma_f32_16x16x32_bf16 v[124:127], v[198:201], v[166:169], v[124:127]
	v_mfma_f32_16x16x32_bf16 v[124:127], v[210:213], v[170:173], v[124:127]
	v_mfma_f32_16x16x32_bf16 v[112:115], v[218:221], v[170:173], v[112:115]
	v_mfma_f32_16x16x32_bf16 v[112:115], v[214:217], v[166:169], v[112:115]
	v_mfma_f32_16x16x32_bf16 v[96:99], v[214:217], v[174:177], v[96:99]
	v_mfma_f32_16x16x32_bf16 v[96:99], v[218:221], v[178:181], v[96:99]
	v_mfma_f32_16x16x32_bf16 v[108:111], v[210:213], v[178:181], v[108:111]
	v_mfma_f32_16x16x32_bf16 v[108:111], v[198:201], v[174:177], v[108:111]
	v_mfma_f32_16x16x32_bf16 v[92:95], v[198:201], v[182:185], v[92:95]
	v_mfma_f32_16x16x32_bf16 v[92:95], v[210:213], v[186:189], v[92:95]
	v_mfma_f32_16x16x32_bf16 v[80:83], v[218:221], v[186:189], v[80:83]
	v_mfma_f32_16x16x32_bf16 v[80:83], v[214:217], v[182:185], v[80:83]
	v_mfma_f32_16x16x32_bf16 v[64:67], v[214:217], v[190:193], v[64:67]
	v_mfma_f32_16x16x32_bf16 v[64:67], v[218:221], v[194:197], v[64:67]
	v_mfma_f32_16x16x32_bf16 v[76:79], v[210:213], v[194:197], v[76:79]
	v_mfma_f32_16x16x32_bf16 v[76:79], v[198:201], v[190:193], v[76:79]
	s_barrier
	s_mov_b32 m0, s89
	s_add_u32 s100, s80, 0xfffc0080
	s_addc_u32 s101, s81, -1
	ds_read_b128 v[166:169], v206 offset:49152
	ds_read_b128 v[170:173], v206 offset:50176
	ds_read_b128 v[174:177], v206 offset:51200
	ds_read_b128 v[178:181], v206 offset:52224
	ds_read_b128 v[182:185], v206 offset:53248
	ds_read_b128 v[186:189], v206 offset:54272
	ds_read_b128 v[190:193], v206 offset:55296
	ds_read_b128 v[194:197], v206 offset:56320
	global_load_lds_dwordx4 v132, s[100:101]
	s_mov_b32 m0, s90
	s_nop 0
	global_load_lds_dwordx4 v136, s[100:101]
	s_barrier
	s_waitcnt lgkmcnt(6)
	v_mfma_f32_16x16x32_bf16 v[56:59], v[150:153], v[166:169], v[56:59]
	v_mfma_f32_16x16x32_bf16 v[56:59], v[154:157], v[170:173], v[56:59]
	v_mfma_f32_16x16x32_bf16 v[52:55], v[162:165], v[170:173], v[52:55]
	v_mfma_f32_16x16x32_bf16 v[52:55], v[158:161], v[166:169], v[52:55]
	s_waitcnt lgkmcnt(4)
	v_mfma_f32_16x16x32_bf16 v[36:39], v[158:161], v[174:177], v[36:39]
	v_mfma_f32_16x16x32_bf16 v[36:39], v[162:165], v[178:181], v[36:39]
	v_mfma_f32_16x16x32_bf16 v[40:43], v[154:157], v[178:181], v[40:43]
	v_mfma_f32_16x16x32_bf16 v[40:43], v[150:153], v[174:177], v[40:43]
	s_waitcnt lgkmcnt(2)
	v_mfma_f32_16x16x32_bf16 v[24:27], v[150:153], v[182:185], v[24:27]
	v_mfma_f32_16x16x32_bf16 v[24:27], v[154:157], v[186:189], v[24:27]
	v_mfma_f32_16x16x32_bf16 v[20:23], v[162:165], v[186:189], v[20:23]
	v_mfma_f32_16x16x32_bf16 v[20:23], v[158:161], v[182:185], v[20:23]
	s_waitcnt lgkmcnt(0)
	v_mfma_f32_16x16x32_bf16 v[4:7], v[158:161], v[190:193], v[4:7]
	v_mfma_f32_16x16x32_bf16 v[4:7], v[162:165], v[194:197], v[4:7]
	v_mfma_f32_16x16x32_bf16 v[8:11], v[154:157], v[194:197], v[8:11]
	v_mfma_f32_16x16x32_bf16 v[8:11], v[150:153], v[190:193], v[8:11]
	s_barrier
	s_add_u32 s78, s78, 0x40080
	s_addc_u32 s79, s79, 0
	s_add_i32 s69, s71, s65
	s_mov_b32 m0, s69
	s_nop 0
	global_load_lds_dwordx4 v134, s[78:79]
	s_add_i32 m0, s69, 0x2000
	s_nop 0
	global_load_lds_dwordx4 v138, s[78:79]
	s_waitcnt vmcnt(6)
	s_barrier
	v_mfma_f32_16x16x32_bf16 v[60:63], v[198:201], v[166:169], v[60:63]
	v_mfma_f32_16x16x32_bf16 v[60:63], v[210:213], v[170:173], v[60:63]
	v_mfma_f32_16x16x32_bf16 v[48:51], v[218:221], v[170:173], v[48:51]
	v_mfma_f32_16x16x32_bf16 v[48:51], v[214:217], v[166:169], v[48:51]
	v_mfma_f32_16x16x32_bf16 v[32:35], v[214:217], v[174:177], v[32:35]
	v_mfma_f32_16x16x32_bf16 v[32:35], v[218:221], v[178:181], v[32:35]
	v_mfma_f32_16x16x32_bf16 v[44:47], v[210:213], v[178:181], v[44:47]
	v_mfma_f32_16x16x32_bf16 v[44:47], v[198:201], v[174:177], v[44:47]
	v_mfma_f32_16x16x32_bf16 v[28:31], v[198:201], v[182:185], v[28:31]
	v_mfma_f32_16x16x32_bf16 v[28:31], v[210:213], v[186:189], v[28:31]
	v_mfma_f32_16x16x32_bf16 v[16:19], v[218:221], v[186:189], v[16:19]
	v_mfma_f32_16x16x32_bf16 v[16:19], v[214:217], v[182:185], v[16:19]
	v_mfma_f32_16x16x32_bf16 v[0:3], v[214:217], v[190:193], v[0:3]
	v_mfma_f32_16x16x32_bf16 v[0:3], v[218:221], v[194:197], v[0:3]
	v_mfma_f32_16x16x32_bf16 v[12:15], v[210:213], v[194:197], v[12:15]
	v_mfma_f32_16x16x32_bf16 v[12:15], v[198:201], v[190:193], v[12:15]
	s_barrier
	s_add_i32 s63, s63, 2
	s_add_u32 s6, s6, 0x100
	s_addc_u32 s7, s7, 0
	s_add_u32 s20, s20, 0x100
	s_addc_u32 s25, s25, 0
	s_cmp_gt_u32 s63, 13
	s_cbranch_scc0 .LBB0_127
	s_cmp_gt_i32 s74, 7
	s_mov_b64 s[6:7], -1
	s_cbranch_scc0 .LBB0_188
	s_sub_i32 s25, s74, 17
	s_cmp_gt_u32 s25, 3
	s_cbranch_scc0 .LBB0_170
	s_lshl_b32 s69, s76, 8
	s_cmp_gt_u32 s74, 11
	s_cbranch_scc0 .LBB0_135
	s_cmp_eq_u32 s74, 12
	s_mov_b64 s[6:7], 0
	s_cbranch_scc1 .LBB0_134
	s_cmp_gt_u32 s74, 16
	s_cbranch_scc1 .LBB0_191
	s_lshl_b32 s20, s74, 8
	v_readlane_b32 s80, v254, 2
	s_addk_i32 s20, 0xf300
	s_mov_b64 s[78:79], 0x400
	s_mov_b64 s[82:83], -1
	s_mov_b32 s63, s69
	v_readlane_b32 s81, v254, 3
	s_andn2_b64 vcc, exec, s[6:7]
	s_cbranch_vccz .LBB0_136
	s_branch .LBB0_137

; __device__ __forceinline__ unsigned xb_ld(unsigned* p)              { return __hip_atomic_load(p, __ATOMIC_RELAXED, __HIP_MEMORY_SCOPE_AGENT); }
; __device__ __forceinline__ void xcd_barrier_complete(unsigned* bar, unsigned x, unsigned& nloc, unsigned& nx) {
;     const unsigned G = gridDim.x * gridDim.y * gridDim.z;
;     unsigned sum, cnt, mine, sp = 0u;
;     for (;;) {
;         sum = 0u; cnt = 0u; mine = 0u;
; #pragma unroll
;         for (unsigned j = 0; j < 16; ++j) { const unsigned c = xb_ld(&bar[XB_XCNT(j)]); sum += c; cnt += (c > 0u) ? 1u : 0u; mine = (j == x) ? c : mine; }
;         if (sum == G) break;
;         __builtin_amdgcn_s_sleep(1);
;         if ((++sp & 255u) == 0u) { if (xb_ld(&bar[XB_TMO])) break; if (sp > XB_SPIN_CAP) { atomicAdd(&bar[XB_TMO], 1u); break; } }
;     }
;     nloc = mine > 0u ? mine : 1u; nx = cnt > 0u ? cnt : 1u;
; __device__ __forceinline__ void xcd_barrier(const XcdBarrier& b) {
;     asm volatile("s_waitcnt vmcnt(0)" ::: "memory");
;     __syncthreads();
;     if (threadIdx.x == 0) {
;         unsigned* bar = b.bar;
;         __builtin_amdgcn_s_waitcnt(0);
;         unsigned nloc = b.st[0], nx = b.st[1];
;         if (nloc == 0u) { xcd_barrier_complete(bar, b.x, nloc, nx); b.st[0] = nloc; b.st[1] = nx; }
.LBB0_195:
	s_nop 0
	s_nop 0
	s_nop 0
	s_nop 0
	s_nop 0
	s_nop 0
	s_nop 0
	s_nop 0
	s_nop 0
	s_nop 0
	s_nop 0
	s_nop 0
	s_nop 0
	s_nop 0
	s_nop 0
	s_nop 0
	s_nop 0
	s_nop 0
	s_nop 0
	s_nop 0
	s_nop 0
	s_nop 0
	s_cmp_gt_i32 s31, 2
	s_cselect_b64 s[0:1], -1, 0
	s_and_b64 s[4:5], s[18:19], s[0:1]
	s_andn2_b64 vcc, exec, s[4:5]
	s_cbranch_vccnz .LBB0_245
	s_waitcnt vmcnt(0)
	s_waitcnt vmcnt(0) lgkmcnt(0)
	s_barrier
	s_and_saveexec_b64 s[4:5], s[8:9]
	s_cbranch_execz .LBB0_244
	s_add_i32 s6, 0, 0x25ff0
	v_mov_b32_e32 v0, s6
	s_waitcnt vmcnt(0) expcnt(0) lgkmcnt(0)
	ds_read_b32 v2, v0
	s_add_i32 s6, 0, 0x25ff4
	v_mov_b32_e32 v0, s6
	ds_read_b32 v0, v0
	s_waitcnt lgkmcnt(1)
	v_cmp_ne_u32_e32 vcc, 0, v2
	s_cbranch_vccnz .LBB0_212
	s_load_dwordx2 s[18:19], s[52:53], 0x4
	s_add_u32 s6, s28, 0x3e800200
	s_addc_u32 s7, s29, 0
	s_add_u32 s10, s28, 0x3e800400
	s_addc_u32 s11, s29, 0
	s_waitcnt lgkmcnt(0)
	s_mul_i32 s76, s18, s3
	s_add_u32 s18, s28, 0x3e800500
	s_mul_i32 s76, s76, s19
	s_addc_u32 s19, s29, 0
	s_add_u32 s20, s28, 0x3e800600
	s_addc_u32 s21, s29, 0
	s_add_u32 s22, s28, 0x3e800700
	s_addc_u32 s23, s29, 0
	s_add_u32 s24, s28, 0x3e800800
	s_addc_u32 s25, s29, 0
	s_add_u32 s42, s28, 0x3e800900
	s_addc_u32 s43, s29, 0
	s_add_u32 s44, s28, 0x3e800a00
	s_addc_u32 s45, s29, 0
	s_add_u32 s48, s28, 0x3e800b00
	s_addc_u32 s49, s29, 0
	s_add_u32 s54, s28, 0x3e800c00
	s_addc_u32 s55, s29, 0
	s_add_u32 s56, s28, 0x3e800d00
	s_addc_u32 s57, s29, 0
	s_add_u32 s58, s28, 0x3e800e00
	s_addc_u32 s59, s29, 0
	s_add_u32 s60, s28, 0x3e800f00
	s_addc_u32 s61, s29, 0
	s_add_u32 s62, s28, 0x3e801000
	s_addc_u32 s63, s29, 0
	s_add_u32 s64, s28, 0x3e801100
	s_addc_u32 s65, s29, 0
	s_add_u32 s66, s28, 0x3e801200
	s_addc_u32 s67, s29, 0
	s_add_u32 s68, s28, 0x3e801300
	s_addc_u32 s69, s29, 0
	s_mov_b32 s77, 1
	v_mov_b32_e32 v16, 0
	s_branch .LBB0_200

; #define PG8_STAGE(bufoff, gbase, voff) do { _Pragma("unroll") for (int _i = 0; _i < 2; ++_i) \
;         __builtin_amdgcn_global_load_lds((const unsigned*)((const char*)(gbase) + (voff)[_i]), (LAS unsigned*)(lds + (bufoff) + ldsw + _i * 8192), 16, 0, 0); } while (0)
; #define PG8_WAIT_V(n) asm volatile("s_waitcnt vmcnt(" #n ")" ::: "memory")
; #define PG8_BAR __builtin_amdgcn_s_barrier()
; template <class Epi, class Ptrs>
; __device__ __forceinline__ void gemm_phase(LAS unsigned char* lds, const int K, const StaticOrder& S, const Ptrs& P, const Epi& E) {
;     ...
;     for (int i = 0; i < 2; ++i) { int R, C; stage_rc(tid * 16 + i * 8192, R, C); const int Rb = (R & ~31) + perm32(R & 31);
;         voffA[i] = (unsigned)(R * K + C) * 2u; voffB[i] = (unsigned)(Rb * K + C) * 2u; }
;     const size_t kstep = (size_t)(BK * 2);
;     const size_t hstep = (size_t)HALF * K * 2;
;     const unsigned ldsw = (unsigned)wid * 1024u;
;     const int aoff = lds_byte(wr * 64 + fr, fq * 8), boff = lds_byte(wc * 32 + fr, fq * 8);
;     ...
;     Unit cur, nxt; int ui = 0;
;     if (!S.next(0, cur)) return;
;     f32x4 acc[2][2][4][2];
; #pragma unroll
;     for (int a = 0; a < 2; ++a)
; #pragma unroll
;         for (int b = 0; b < 2; ++b)
; #pragma unroll
;             for (int m = 0; m < 4; ++m)
; #pragma unroll
;                 for (int n = 0; n < 2; ++n) acc[a][b][m][n] = (f32x4){0.f, 0.f, 0.f, 0.f};
;     bf16x8 At[4][2], B0[2][2], B1[2][2];
;     const char* cA; const char* cB; P.get(cur, cA, cB);
;     PG8_STAGE(PG8_SB(0, 0), cB, voffB); PG8_STAGE(PG8_SA(0, 0), cA, voffA); PG8_STAGE(PG8_SB(0, 1), cB + hstep, voffB); PG8_STAGE(PG8_SA(0, 1), cA + hstep, voffA);
;     if (wr == 1) PG8_BAR;
;     PG8_WAIT_V(4); PG8_BAR;
;     PG8_STAGE(PG8_SB(1, 0), cB + kstep, voffB); PG8_STAGE(PG8_SA(1, 0), cA + kstep, voffA); PG8_STAGE(PG8_SB(1, 1), cB + hstep + kstep, voffB);
;     PG8_WAIT_V(6); PG8_BAR;
.LBB0_346:
	s_add_u32 s14, s28, 0x2000000
	s_addc_u32 s15, s29, 0
	s_add_u32 s16, s28, 0x3e000000
	s_addc_u32 s17, s29, 0
	s_ashr_i32 s58, s3, 31
	s_ashr_i32 s59, s2, 31
	s_add_u32 s60, s38, 0xf8000000
	s_mov_b64 s[18:19], 0x80
	s_addc_u32 s61, s39, -1
	s_and_b32 s62, s1, 3
	s_add_i32 m0, s54, 0x18000
	v_lshl_add_u64 v[6:7], v[6:7], 0, s[18:19]
	s_lshl_b32 s1, s0, 13
	s_lshl_b32 s20, s62, 12
	s_waitcnt vmcnt(4)
	s_barrier
	global_load_lds_dwordx4 v[6:7], off
	v_lshl_add_u64 v[4:5], v[4:5], 0, s[18:19]
	s_add_i32 m0, s54, 0x1a000
	s_add_i32 s63, s54, 0x8000
	s_add_i32 s64, s54, 0xa000
	global_load_lds_dwordx4 v[4:5], off
	v_lshl_add_u64 v[2:3], v[2:3], 0, s[18:19]
	s_mov_b32 m0, s63
	s_add_u32 s4, s42, 0x40080
	global_load_lds_dwordx4 v[2:3], off
	v_lshl_add_u64 v[0:1], v[0:1], 0, s[18:19]
	s_mov_b32 m0, s64
	s_addc_u32 s5, s43, 0
	global_load_lds_dwordx4 v[0:1], off
	s_add_i32 m0, s54, 0x1c000
	v_lshl_add_u64 v[0:1], s[4:5], 0, v[178:179]
	global_load_lds_dwordx4 v[0:1], off
	v_lshl_add_u64 v[0:1], s[4:5], 0, v[182:183]
	s_add_i32 m0, s54, 0x1e000
	v_lshlrev_b32_e32 v4, 6, v208
	global_load_lds_dwordx4 v[0:1], off
	v_bfe_u32 v1, v208, 4, 2
	v_lshlrev_b32_e32 v2, 3, v1
	v_lshlrev_b32_e32 v3, 4, v1
	v_cmp_eq_u32_e64 s[6:7], 0, v1
	v_lshlrev_b32_e32 v1, 8, v208
	v_lshl_or_b32 v206, s62, 5, v2
	v_and_b32_e32 v1, 0x38000, v1
	v_lshlrev_b32_e32 v2, 11, v10
	v_or3_b32 v1, v8, v1, v2
	v_and_b32_e32 v0, 15, v208
	s_movk_i32 s4, 0x3c0
	v_lshlrev_b32_e32 v5, 2, v208
	v_add_u32_e32 v184, v1, v9
	v_lshlrev_b32_e32 v1, 4, v11
	v_and_or_b32 v4, v4, s4, v3
	v_and_b32_e32 v5, 32, v5
	v_lshl_or_b32 v204, s0, 6, v0
	v_lshl_or_b32 v0, v0, 6, v3
	s_waitcnt vmcnt(6)
	v_and_b32_e32 v1, 0x78000, v1
	v_bitop3_b32 v0, v0, s1, v5 bitop3:0xde
	v_bitop3_b32 v205, s20, v4, v5 bitop3:0xf6
	v_or3_b32 v1, v8, v1, v2
	s_add_i32 s66, 0, 0x10000
	s_add_i32 s67, 0, 0x14000
	v_mov_b32_e32 v185, v179
	v_add_u32_e32 v186, v1, v9
	v_mov_b32_e32 v187, v179
	v_mov_b64_e32 v[188:189], 0x600
	v_mov_b64_e32 v[190:191], 0x5ff
	s_movk_i32 s65, 0xc1
	v_add_u32_e32 v207, s66, v205
	v_add_u32_e32 v209, 0, v0
	v_add_u32_e32 v210, s67, v205
	s_nop 0
	s_nop 0
	s_nop 0
	s_nop 0
	s_nop 0
	s_nop 0
	s_nop 0
	s_nop 0
	s_nop 0
	s_nop 0
	s_nop 0
	s_nop 0
	s_nop 0
	s_nop 0
	s_nop 0
	s_nop 0
	s_nop 0
	s_nop 0
	s_nop 0
	s_nop 0
	s_nop 0
	s_nop 0
	s_nop 0
	s_nop 0
	s_nop 0
	s_nop 0
	s_nop 0
	s_nop 0
	s_nop 0
	s_nop 0
	s_nop 0
	s_nop 0
	s_nop 0
	s_nop 0
	s_nop 0
	s_nop 0
	s_nop 0
	s_nop 0
	s_nop 0
	s_nop 0
	s_nop 0
	s_nop 0
	s_nop 0
	s_nop 0
	s_nop 0
	s_nop 0
	s_nop 0
	s_nop 0
	s_nop 0
	s_nop 0
	s_mov_b32 s68, 0
	s_cmpk_lt_u32 s46, 0x100
	s_cbranch_scc1 .Lsprio_1
	s_setprio 1

; #define PG8_STAGE(bufoff, gbase, voff) do { _Pragma("unroll") for (int _i = 0; _i < 2; ++_i) \
;         __builtin_amdgcn_global_load_lds((const unsigned*)((const char*)(gbase) + (voff)[_i]), (LAS unsigned*)(lds + (bufoff) + ldsw + _i * 8192), 16, 0, 0); } while (0)
; #define PG8_LDA(dst, b, h) do { _Pragma("unroll") for (int m = 0; m < 4; ++m) _Pragma("unroll") for (int k = 0; k < 2; ++k) dst[m][k] = *(const LAS bf16x8*)(lds + PG8_SA(b, h) + aoff + m * 2048 + k * 1024); } while (0)
; #define PG8_WAIT_V(n) asm volatile("s_waitcnt vmcnt(" #n ")" ::: "memory")
; #define PG8_BAR __builtin_amdgcn_s_barrier()
; template <class Epi, class Ptrs>
; __device__ __forceinline__ void gemm_phase(LAS unsigned char* lds, const int K, const StaticOrder& S, const Ptrs& P, const Epi& E) {
;     ...
;         for (int t = 0; t < nt; t += 2) {
;             const bool last = (t == nt - 2);
;             const char* a1 = cA + (size_t)(t + 1) * kstep;
;             const char* a2 = last ? nA : cA + (size_t)(t + 2) * kstep; const char* b2 = last ? nB : cB + (size_t)(t + 2) * kstep;
;             const char* a3 = a2 + kstep; const char* b3 = b2 + kstep;
;             PG8_LDB(B0, 0, 0); PG8_SCHED; PG8_LDA(At, 0, 0); PG8_STAGE(PG8_SA(1, 1), a1 + hstep, voffA);
;             PG8_WAIT_L(8); PG8_BAR; PG8_WAIT_L(0); PG8_MMA(0, 0, At, B0); PG8_BAR; PG8_SCHED;
;             PG8_LDB(B1, 0, 1); PG8_STAGE(PG8_SB(0, 0), b2, voffB);
;             PG8_BAR; PG8_WAIT_L(0); PG8_MMA(0, 1, At, B1); PG8_BAR;
;             PG8_LDA(At, 0, 1); PG8_STAGE(PG8_SA(0, 0), a2, voffA);
;             PG8_BAR; PG8_WAIT_L(0); PG8_MMA(1, 0, At, B0); PG8_BAR; PG8_SCHED;
;             PG8_STAGE(PG8_SB(0, 1), b2 + hstep, voffB);
;             PG8_WAIT_V(6); PG8_BAR; PG8_MMA(1, 1, At, B1); PG8_BAR;
;             PG8_LDB(B0, 1, 0); PG8_SCHED; PG8_LDA(At, 1, 0); PG8_STAGE(PG8_SA(0, 1), a2 + hstep, voffA);
;             PG8_WAIT_L(8); PG8_BAR; PG8_WAIT_L(0); PG8_MMA(0, 0, At, B0); PG8_BAR; PG8_SCHED;
;             PG8_LDB(B1, 1, 1); PG8_STAGE(PG8_SB(1, 0), b3, voffB);
;             PG8_BAR; PG8_WAIT_L(0); PG8_MMA(0, 1, At, B1); PG8_BAR;
;             PG8_LDA(At, 1, 1); PG8_STAGE(PG8_SA(1, 0), a3, voffA);
;             PG8_BAR; PG8_WAIT_L(0); PG8_MMA(1, 0, At, B0); PG8_BAR; PG8_SCHED;
;             PG8_STAGE(PG8_SB(1, 1), b3 + hstep, voffB);
;             PG8_WAIT_V(6); PG8_BAR; PG8_MMA(1, 1, At, B1); PG8_BAR;
.LBB0_352:
	s_add_u32 s38, s44, 0x40080
	s_addc_u32 s39, s45, 0
	s_add_u32 s21, s42, 0x100
	s_addc_u32 s23, s43, 0
	s_mov_b32 s41, -2
	v_add_u32_e32 v252, 0x18000, v205
	v_add_u32_e32 v253, 0x1c000, v205
	ds_read_b128 v[128:131], v207
	ds_read_b128 v[132:135], v207 offset:1024
	ds_read_b128 v[136:139], v207 offset:2048
	ds_read_b128 v[140:143], v207 offset:3072
	s_add_u32 s42, s38, 0xfffc0080
	s_addc_u32 s43, s39, -1
	s_cmp_eq_u32 s41, 12
	s_cselect_b32 s45, s1, s43
	s_cselect_b32 s44, s0, s42
	s_cselect_b32 s43, s25, s23
	s_cselect_b32 s42, s24, s21
	s_add_i32 m0, s54, 0xc000
	ds_read_b128 v[144:147], v209
	ds_read_b128 v[148:151], v209 offset:1024
	ds_read_b128 v[152:155], v209 offset:2048
	ds_read_b128 v[156:159], v209 offset:3072
	ds_read_b128 v[160:163], v209 offset:4096
	ds_read_b128 v[164:167], v209 offset:5120
	ds_read_b128 v[168:171], v209 offset:6144
	ds_read_b128 v[172:175], v209 offset:7168
	global_load_lds_dwordx4 v184, s[38:39]
	s_add_i32 m0, s54, 0xe000
	s_nop 0
	global_load_lds_dwordx4 v186, s[38:39]
	s_waitcnt lgkmcnt(8)
	s_barrier
	s_waitcnt lgkmcnt(6)
	v_mfma_f32_16x16x32_bf16 v[124:127], v[128:131], v[144:147], 0
	v_mfma_f32_16x16x32_bf16 v[124:127], v[132:135], v[148:151], v[124:127]
	v_mfma_f32_16x16x32_bf16 v[120:123], v[140:143], v[148:151], 0
	v_mfma_f32_16x16x32_bf16 v[120:123], v[136:139], v[144:147], v[120:123]
	s_waitcnt lgkmcnt(4)
	v_mfma_f32_16x16x32_bf16 v[104:107], v[136:139], v[152:155], 0
	v_mfma_f32_16x16x32_bf16 v[104:107], v[140:143], v[156:159], v[104:107]
	v_mfma_f32_16x16x32_bf16 v[108:111], v[132:135], v[156:159], 0
	v_mfma_f32_16x16x32_bf16 v[108:111], v[128:131], v[152:155], v[108:111]
	s_waitcnt lgkmcnt(2)
	v_mfma_f32_16x16x32_bf16 v[92:95], v[128:131], v[160:163], 0
	v_mfma_f32_16x16x32_bf16 v[92:95], v[132:135], v[164:167], v[92:95]
	v_mfma_f32_16x16x32_bf16 v[88:91], v[140:143], v[164:167], 0
	v_mfma_f32_16x16x32_bf16 v[88:91], v[136:139], v[160:163], v[88:91]
	s_waitcnt lgkmcnt(0)
	v_mfma_f32_16x16x32_bf16 v[72:75], v[136:139], v[168:171], 0
	v_mfma_f32_16x16x32_bf16 v[72:75], v[140:143], v[172:175], v[72:75]
	v_mfma_f32_16x16x32_bf16 v[76:79], v[132:135], v[172:175], 0
	v_mfma_f32_16x16x32_bf16 v[76:79], v[128:131], v[168:171], v[76:79]
	s_barrier
	s_add_i32 s69, s66, s51
	s_add_u32 s90, s42, 0x80
	s_addc_u32 s91, s43, 0
	s_mov_b32 m0, s69
	ds_read_b128 v[192:195], v210
	ds_read_b128 v[196:199], v210 offset:1024
	ds_read_b128 v[200:203], v210 offset:2048
	ds_read_b128 v[212:215], v210 offset:3072
	global_load_lds_dwordx4 v178, s[42:43]
	s_add_i32 m0, s69, 0x2000
	s_nop 0
	global_load_lds_dwordx4 v182, s[42:43]
	s_barrier
	s_waitcnt lgkmcnt(0)
	v_mfma_f32_16x16x32_bf16 v[116:119], v[192:195], v[144:147], 0
	v_mfma_f32_16x16x32_bf16 v[116:119], v[196:199], v[148:151], v[116:119]
	v_mfma_f32_16x16x32_bf16 v[112:115], v[212:215], v[148:151], 0
	v_mfma_f32_16x16x32_bf16 v[112:115], v[200:203], v[144:147], v[112:115]
	v_mfma_f32_16x16x32_bf16 v[96:99], v[200:203], v[152:155], 0
	v_mfma_f32_16x16x32_bf16 v[96:99], v[212:215], v[156:159], v[96:99]
	v_mfma_f32_16x16x32_bf16 v[100:103], v[196:199], v[156:159], 0
	v_mfma_f32_16x16x32_bf16 v[100:103], v[192:195], v[152:155], v[100:103]
	v_mfma_f32_16x16x32_bf16 v[84:87], v[192:195], v[160:163], 0
	v_mfma_f32_16x16x32_bf16 v[84:87], v[196:199], v[164:167], v[84:87]
	v_mfma_f32_16x16x32_bf16 v[80:83], v[212:215], v[164:167], 0
	v_mfma_f32_16x16x32_bf16 v[80:83], v[200:203], v[160:163], v[80:83]
	v_mfma_f32_16x16x32_bf16 v[64:67], v[200:203], v[168:171], 0
	v_mfma_f32_16x16x32_bf16 v[64:67], v[212:215], v[172:175], v[64:67]
	v_mfma_f32_16x16x32_bf16 v[68:71], v[196:199], v[172:175], 0
	v_mfma_f32_16x16x32_bf16 v[68:71], v[192:195], v[168:171], v[68:71]
	s_barrier
	s_mov_b32 m0, s54
	s_add_u32 s92, s44, 0x80
	s_addc_u32 s93, s45, 0
	ds_read_b128 v[144:147], v209 offset:16384
	ds_read_b128 v[148:151], v209 offset:17408
	ds_read_b128 v[152:155], v209 offset:18432
	ds_read_b128 v[156:159], v209 offset:19456
	ds_read_b128 v[160:163], v209 offset:20480
	ds_read_b128 v[164:167], v209 offset:21504
	ds_read_b128 v[168:171], v209 offset:22528
	ds_read_b128 v[172:175], v209 offset:23552
	global_load_lds_dwordx4 v176, s[44:45]
	s_mov_b32 m0, s55
	s_nop 0
	global_load_lds_dwordx4 v180, s[44:45]
	s_barrier
	s_waitcnt lgkmcnt(6)
	v_mfma_f32_16x16x32_bf16 v[60:63], v[128:131], v[144:147], 0
	v_mfma_f32_16x16x32_bf16 v[60:63], v[132:135], v[148:151], v[60:63]
	v_mfma_f32_16x16x32_bf16 v[56:59], v[140:143], v[148:151], 0
	v_mfma_f32_16x16x32_bf16 v[56:59], v[136:139], v[144:147], v[56:59]
	s_waitcnt lgkmcnt(4)
	v_mfma_f32_16x16x32_bf16 v[40:43], v[136:139], v[152:155], 0
	v_mfma_f32_16x16x32_bf16 v[40:43], v[140:143], v[156:159], v[40:43]
	v_mfma_f32_16x16x32_bf16 v[44:47], v[132:135], v[156:159], 0
	v_mfma_f32_16x16x32_bf16 v[44:47], v[128:131], v[152:155], v[44:47]
	s_waitcnt lgkmcnt(2)
	v_mfma_f32_16x16x32_bf16 v[28:31], v[128:131], v[160:163], 0
	v_mfma_f32_16x16x32_bf16 v[28:31], v[132:135], v[164:167], v[28:31]
	v_mfma_f32_16x16x32_bf16 v[24:27], v[140:143], v[164:167], 0
	v_mfma_f32_16x16x32_bf16 v[24:27], v[136:139], v[160:163], v[24:27]
	s_waitcnt lgkmcnt(0)
	v_mfma_f32_16x16x32_bf16 v[8:11], v[136:139], v[168:171], 0
	v_mfma_f32_16x16x32_bf16 v[8:11], v[140:143], v[172:175], v[8:11]
	v_mfma_f32_16x16x32_bf16 v[12:15], v[132:135], v[172:175], 0
	v_mfma_f32_16x16x32_bf16 v[12:15], v[128:131], v[168:171], v[12:15]
	s_barrier
	s_add_u32 s70, s42, 0x40000
	s_addc_u32 s71, s43, 0
	s_add_i32 s69, s67, s51
	s_mov_b32 m0, s69
	s_nop 0
	global_load_lds_dwordx4 v178, s[70:71]
	s_add_i32 m0, s69, 0x2000
	s_nop 0
	global_load_lds_dwordx4 v182, s[70:71]
	s_waitcnt vmcnt(6)
	s_barrier
; #define PG8_STAGE(bufoff, gbase, voff) do { _Pragma("unroll") for (int _i = 0; _i < 2; ++_i) \
;         __builtin_amdgcn_global_load_lds((const unsigned*)((const char*)(gbase) + (voff)[_i]), (LAS unsigned*)(lds + (bufoff) + ldsw + _i * 8192), 16, 0, 0); } while (0)
; #define PG8_LDA(dst, b, h) do { _Pragma("unroll") for (int m = 0; m < 4; ++m) _Pragma("unroll") for (int k = 0; k < 2; ++k) dst[m][k] = *(const LAS bf16x8*)(lds + PG8_SA(b, h) + aoff + m * 2048 + k * 1024); } while (0)
; #define PG8_LDB(dst, b, h) do { _Pragma("unroll") for (int n = 0; n < 2; ++n) _Pragma("unroll") for (int k = 0; k < 2; ++k) dst[n][k] = *(const LAS bf16x8*)(lds + PG8_SB(b, h) + boff + n * 2048 + k * 1024); } while (0)
; #define PG8_WAIT_V(n) asm volatile("s_waitcnt vmcnt(" #n ")" ::: "memory")
; #define PG8_WAIT_L(n) asm volatile("s_waitcnt lgkmcnt(" #n ")" ::: "memory")
; #define PG8_BAR __builtin_amdgcn_s_barrier()
; #define PG8_SCHED __builtin_amdgcn_sched_barrier(0)
; template <class Epi, class Ptrs>
; __device__ __forceinline__ void gemm_phase(LAS unsigned char* lds, const int K, const StaticOrder& S, const Ptrs& P, const Epi& E) {
;     ...
;             PG8_LDB(B0, 0, 0); PG8_SCHED; PG8_LDA(At, 0, 0); PG8_STAGE(PG8_SA(1, 1), a1 + hstep, voffA);
;             PG8_WAIT_L(8); PG8_BAR; PG8_WAIT_L(0); PG8_MMA(0, 0, At, B0); PG8_BAR; PG8_SCHED;
;             PG8_LDB(B1, 0, 1); PG8_STAGE(PG8_SB(0, 0), b2, voffB);
;             PG8_BAR; PG8_WAIT_L(0); PG8_MMA(0, 1, At, B1); PG8_BAR;
;             PG8_LDA(At, 0, 1); PG8_STAGE(PG8_SA(0, 0), a2, voffA);
;             PG8_BAR; PG8_WAIT_L(0); PG8_MMA(1, 0, At, B0); PG8_BAR; PG8_SCHED;
;             PG8_STAGE(PG8_SB(0, 1), b2 + hstep, voffB);
;             PG8_WAIT_V(6); PG8_BAR; PG8_MMA(1, 1, At, B1); PG8_BAR;
;             PG8_LDB(B0, 1, 0); PG8_SCHED; PG8_LDA(At, 1, 0); PG8_STAGE(PG8_SA(0, 1), a2 + hstep, voffA);
;             PG8_WAIT_L(8); PG8_BAR; PG8_WAIT_L(0); PG8_MMA(0, 0, At, B0); PG8_BAR; PG8_SCHED;
;             PG8_LDB(B1, 1, 1); PG8_STAGE(PG8_SB(1, 0), b3, voffB);
;             PG8_BAR; PG8_WAIT_L(0); PG8_MMA(0, 1, At, B1); PG8_BAR;
;             PG8_LDA(At, 1, 1); PG8_STAGE(PG8_SA(1, 0), a3, voffA);
;             PG8_BAR; PG8_WAIT_L(0); PG8_MMA(1, 0, At, B0); PG8_BAR; PG8_SCHED;
;             PG8_STAGE(PG8_SB(1, 1), b3 + hstep, voffB);
;             PG8_WAIT_V(6); PG8_BAR; PG8_MMA(1, 1, At, B1); PG8_BAR;
	v_mfma_f32_16x16x32_bf16 v[52:55], v[192:195], v[144:147], 0
	v_mfma_f32_16x16x32_bf16 v[52:55], v[196:199], v[148:151], v[52:55]
	v_mfma_f32_16x16x32_bf16 v[48:51], v[212:215], v[148:151], 0
	v_mfma_f32_16x16x32_bf16 v[48:51], v[200:203], v[144:147], v[48:51]
	v_mfma_f32_16x16x32_bf16 v[32:35], v[200:203], v[152:155], 0
	v_mfma_f32_16x16x32_bf16 v[32:35], v[212:215], v[156:159], v[32:35]
	v_mfma_f32_16x16x32_bf16 v[36:39], v[196:199], v[156:159], 0
	v_mfma_f32_16x16x32_bf16 v[36:39], v[192:195], v[152:155], v[36:39]
	v_mfma_f32_16x16x32_bf16 v[20:23], v[192:195], v[160:163], 0
	v_mfma_f32_16x16x32_bf16 v[20:23], v[196:199], v[164:167], v[20:23]
	v_mfma_f32_16x16x32_bf16 v[16:19], v[212:215], v[164:167], 0
	v_mfma_f32_16x16x32_bf16 v[16:19], v[200:203], v[160:163], v[16:19]
	v_mfma_f32_16x16x32_bf16 v[0:3], v[200:203], v[168:171], 0
	v_mfma_f32_16x16x32_bf16 v[0:3], v[212:215], v[172:175], v[0:3]
	v_mfma_f32_16x16x32_bf16 v[4:7], v[196:199], v[172:175], 0
	v_mfma_f32_16x16x32_bf16 v[4:7], v[192:195], v[168:171], v[4:7]
	s_barrier
	s_add_i32 s69, 0, 0x18000
	ds_read_b128 v[128:131], v252
	ds_read_b128 v[132:135], v252 offset:1024
	ds_read_b128 v[136:139], v252 offset:2048
	ds_read_b128 v[140:143], v252 offset:3072
	s_add_u32 s44, s44, 0x40000
	s_addc_u32 s45, s45, 0
	s_mov_b32 m0, s56
	ds_read_b128 v[144:147], v209 offset:32768
	ds_read_b128 v[148:151], v209 offset:33792
	ds_read_b128 v[152:155], v209 offset:34816
	ds_read_b128 v[156:159], v209 offset:35840
	ds_read_b128 v[160:163], v209 offset:36864
	ds_read_b128 v[164:167], v209 offset:37888
	ds_read_b128 v[168:171], v209 offset:38912
	ds_read_b128 v[172:175], v209 offset:39936
	global_load_lds_dwordx4 v176, s[44:45]
	s_mov_b32 m0, s57
	s_nop 0
	global_load_lds_dwordx4 v180, s[44:45]
	s_waitcnt lgkmcnt(8)
	s_barrier
	s_waitcnt lgkmcnt(6)
	v_mfma_f32_16x16x32_bf16 v[124:127], v[128:131], v[144:147], v[124:127]
	v_mfma_f32_16x16x32_bf16 v[124:127], v[132:135], v[148:151], v[124:127]
	v_mfma_f32_16x16x32_bf16 v[120:123], v[140:143], v[148:151], v[120:123]
	v_mfma_f32_16x16x32_bf16 v[120:123], v[136:139], v[144:147], v[120:123]
	s_waitcnt lgkmcnt(4)
	v_mfma_f32_16x16x32_bf16 v[104:107], v[136:139], v[152:155], v[104:107]
	v_mfma_f32_16x16x32_bf16 v[104:107], v[140:143], v[156:159], v[104:107]
	v_mfma_f32_16x16x32_bf16 v[108:111], v[132:135], v[156:159], v[108:111]
	v_mfma_f32_16x16x32_bf16 v[108:111], v[128:131], v[152:155], v[108:111]
	s_waitcnt lgkmcnt(2)
	v_mfma_f32_16x16x32_bf16 v[92:95], v[128:131], v[160:163], v[92:95]
	v_mfma_f32_16x16x32_bf16 v[92:95], v[132:135], v[164:167], v[92:95]
	v_mfma_f32_16x16x32_bf16 v[88:91], v[140:143], v[164:167], v[88:91]
	v_mfma_f32_16x16x32_bf16 v[88:91], v[136:139], v[160:163], v[88:91]
	s_waitcnt lgkmcnt(0)
	v_mfma_f32_16x16x32_bf16 v[72:75], v[136:139], v[168:171], v[72:75]
	v_mfma_f32_16x16x32_bf16 v[72:75], v[140:143], v[172:175], v[72:75]
	v_mfma_f32_16x16x32_bf16 v[76:79], v[132:135], v[172:175], v[76:79]
	v_mfma_f32_16x16x32_bf16 v[76:79], v[128:131], v[168:171], v[76:79]
	s_barrier
	s_add_i32 s44, 0, 0x1c000
	s_add_i32 s45, s69, s51
	s_mov_b32 m0, s45
	ds_read_b128 v[192:195], v253
	ds_read_b128 v[196:199], v253 offset:1024
	ds_read_b128 v[200:203], v253 offset:2048
	ds_read_b128 v[212:215], v253 offset:3072
	global_load_lds_dwordx4 v178, s[90:91]
	s_add_i32 m0, s45, 0x2000
	s_nop 0
	global_load_lds_dwordx4 v182, s[90:91]
	s_barrier
	s_waitcnt lgkmcnt(0)
	v_mfma_f32_16x16x32_bf16 v[116:119], v[192:195], v[144:147], v[116:119]
	v_mfma_f32_16x16x32_bf16 v[116:119], v[196:199], v[148:151], v[116:119]
	v_mfma_f32_16x16x32_bf16 v[112:115], v[212:215], v[148:151], v[112:115]
	v_mfma_f32_16x16x32_bf16 v[112:115], v[200:203], v[144:147], v[112:115]
	v_mfma_f32_16x16x32_bf16 v[96:99], v[200:203], v[152:155], v[96:99]
	v_mfma_f32_16x16x32_bf16 v[96:99], v[212:215], v[156:159], v[96:99]
	v_mfma_f32_16x16x32_bf16 v[100:103], v[196:199], v[156:159], v[100:103]
	v_mfma_f32_16x16x32_bf16 v[100:103], v[192:195], v[152:155], v[100:103]
	v_mfma_f32_16x16x32_bf16 v[84:87], v[192:195], v[160:163], v[84:87]
	v_mfma_f32_16x16x32_bf16 v[84:87], v[196:199], v[164:167], v[84:87]
	v_mfma_f32_16x16x32_bf16 v[80:83], v[212:215], v[164:167], v[80:83]
	v_mfma_f32_16x16x32_bf16 v[80:83], v[200:203], v[160:163], v[80:83]
	v_mfma_f32_16x16x32_bf16 v[64:67], v[200:203], v[168:171], v[64:67]
	v_mfma_f32_16x16x32_bf16 v[64:67], v[212:215], v[172:175], v[64:67]
	v_mfma_f32_16x16x32_bf16 v[68:71], v[196:199], v[172:175], v[68:71]
	v_mfma_f32_16x16x32_bf16 v[68:71], v[192:195], v[168:171], v[68:71]
	s_barrier
	s_mov_b32 m0, s63
	ds_read_b128 v[144:147], v209 offset:49152
	ds_read_b128 v[148:151], v209 offset:50176
	ds_read_b128 v[152:155], v209 offset:51200
	ds_read_b128 v[156:159], v209 offset:52224
	ds_read_b128 v[160:163], v209 offset:53248
	ds_read_b128 v[164:167], v209 offset:54272
	ds_read_b128 v[168:171], v209 offset:55296
	ds_read_b128 v[172:175], v209 offset:56320
	global_load_lds_dwordx4 v176, s[92:93]
	s_mov_b32 m0, s64
	s_nop 0
	global_load_lds_dwordx4 v180, s[92:93]
	s_barrier
; #define PG8_STAGE(bufoff, gbase, voff) do { _Pragma("unroll") for (int _i = 0; _i < 2; ++_i) \
;         __builtin_amdgcn_global_load_lds((const unsigned*)((const char*)(gbase) + (voff)[_i]), (LAS unsigned*)(lds + (bufoff) + ldsw + _i * 8192), 16, 0, 0); } while (0)
; #define PG8_LDA(dst, b, h) do { _Pragma("unroll") for (int m = 0; m < 4; ++m) _Pragma("unroll") for (int k = 0; k < 2; ++k) dst[m][k] = *(const LAS bf16x8*)(lds + PG8_SA(b, h) + aoff + m * 2048 + k * 1024); } while (0)
; #define PG8_WAIT_V(n) asm volatile("s_waitcnt vmcnt(" #n ")" ::: "memory")
; #define PG8_BAR __builtin_amdgcn_s_barrier()
; template <class Epi, class Ptrs>
; __device__ __forceinline__ void gemm_phase(LAS unsigned char* lds, const int K, const StaticOrder& S, const Ptrs& P, const Epi& E) {
;     ...
;         for (int t = 0; t < nt; t += 2) {
;             const bool last = (t == nt - 2);
;             const char* a1 = cA + (size_t)(t + 1) * kstep;
;             const char* a2 = last ? nA : cA + (size_t)(t + 2) * kstep; const char* b2 = last ? nB : cB + (size_t)(t + 2) * kstep;
;             const char* a3 = a2 + kstep; const char* b3 = b2 + kstep;
;             PG8_LDB(B0, 0, 0); PG8_SCHED; PG8_LDA(At, 0, 0); PG8_STAGE(PG8_SA(1, 1), a1 + hstep, voffA);
;             PG8_WAIT_L(8); PG8_BAR; PG8_WAIT_L(0); PG8_MMA(0, 0, At, B0); PG8_BAR; PG8_SCHED;
;             PG8_LDB(B1, 0, 1); PG8_STAGE(PG8_SB(0, 0), b2, voffB);
;             PG8_BAR; PG8_WAIT_L(0); PG8_MMA(0, 1, At, B1); PG8_BAR;
;             PG8_LDA(At, 0, 1); PG8_STAGE(PG8_SA(0, 0), a2, voffA);
;             PG8_BAR; PG8_WAIT_L(0); PG8_MMA(1, 0, At, B0); PG8_BAR; PG8_SCHED;
;             PG8_STAGE(PG8_SB(0, 1), b2 + hstep, voffB);
;             PG8_WAIT_V(6); PG8_BAR; PG8_MMA(1, 1, At, B1); PG8_BAR;
;             PG8_LDB(B0, 1, 0); PG8_SCHED; PG8_LDA(At, 1, 0); PG8_STAGE(PG8_SA(0, 1), a2 + hstep, voffA);
;             PG8_WAIT_L(8); PG8_BAR; PG8_WAIT_L(0); PG8_MMA(0, 0, At, B0); PG8_BAR; PG8_SCHED;
;             PG8_LDB(B1, 1, 1); PG8_STAGE(PG8_SB(1, 0), b3, voffB);
;             PG8_BAR; PG8_WAIT_L(0); PG8_MMA(0, 1, At, B1); PG8_BAR;
;             PG8_LDA(At, 1, 1); PG8_STAGE(PG8_SA(1, 0), a3, voffA);
;             PG8_BAR; PG8_WAIT_L(0); PG8_MMA(1, 0, At, B0); PG8_BAR; PG8_SCHED;
;             PG8_STAGE(PG8_SB(1, 1), b3 + hstep, voffB);
;             PG8_WAIT_V(6); PG8_BAR; PG8_MMA(1, 1, At, B1); PG8_BAR;
	s_waitcnt lgkmcnt(6)
	v_mfma_f32_16x16x32_bf16 v[60:63], v[128:131], v[144:147], v[60:63]
	v_mfma_f32_16x16x32_bf16 v[60:63], v[132:135], v[148:151], v[60:63]
	v_mfma_f32_16x16x32_bf16 v[56:59], v[140:143], v[148:151], v[56:59]
	v_mfma_f32_16x16x32_bf16 v[56:59], v[136:139], v[144:147], v[56:59]
	s_waitcnt lgkmcnt(4)
	v_mfma_f32_16x16x32_bf16 v[40:43], v[136:139], v[152:155], v[40:43]
	v_mfma_f32_16x16x32_bf16 v[40:43], v[140:143], v[156:159], v[40:43]
	v_mfma_f32_16x16x32_bf16 v[44:47], v[132:135], v[156:159], v[44:47]
	v_mfma_f32_16x16x32_bf16 v[44:47], v[128:131], v[152:155], v[44:47]
	s_waitcnt lgkmcnt(2)
	v_mfma_f32_16x16x32_bf16 v[28:31], v[128:131], v[160:163], v[28:31]
	v_mfma_f32_16x16x32_bf16 v[28:31], v[132:135], v[164:167], v[28:31]
	v_mfma_f32_16x16x32_bf16 v[24:27], v[140:143], v[164:167], v[24:27]
	v_mfma_f32_16x16x32_bf16 v[24:27], v[136:139], v[160:163], v[24:27]
	s_waitcnt lgkmcnt(0)
	v_mfma_f32_16x16x32_bf16 v[8:11], v[136:139], v[168:171], v[8:11]
	v_mfma_f32_16x16x32_bf16 v[8:11], v[140:143], v[172:175], v[8:11]
	v_mfma_f32_16x16x32_bf16 v[12:15], v[132:135], v[172:175], v[12:15]
	v_mfma_f32_16x16x32_bf16 v[12:15], v[128:131], v[168:171], v[12:15]
	s_barrier
	s_add_u32 s42, s42, 0x40080
	s_addc_u32 s43, s43, 0
	s_add_i32 s44, s44, s51
	s_mov_b32 m0, s44
	s_nop 0
	global_load_lds_dwordx4 v178, s[42:43]
	s_add_i32 m0, s44, 0x2000
	s_nop 0
	global_load_lds_dwordx4 v182, s[42:43]
	s_waitcnt vmcnt(6)
	s_barrier
	v_mfma_f32_16x16x32_bf16 v[52:55], v[192:195], v[144:147], v[52:55]
	v_mfma_f32_16x16x32_bf16 v[52:55], v[196:199], v[148:151], v[52:55]
	v_mfma_f32_16x16x32_bf16 v[48:51], v[212:215], v[148:151], v[48:51]
	v_mfma_f32_16x16x32_bf16 v[48:51], v[200:203], v[144:147], v[48:51]
	v_mfma_f32_16x16x32_bf16 v[32:35], v[200:203], v[152:155], v[32:35]
	v_mfma_f32_16x16x32_bf16 v[32:35], v[212:215], v[156:159], v[32:35]
	v_mfma_f32_16x16x32_bf16 v[36:39], v[196:199], v[156:159], v[36:39]
	v_mfma_f32_16x16x32_bf16 v[36:39], v[192:195], v[152:155], v[36:39]
	v_mfma_f32_16x16x32_bf16 v[20:23], v[192:195], v[160:163], v[20:23]
	v_mfma_f32_16x16x32_bf16 v[20:23], v[196:199], v[164:167], v[20:23]
	v_mfma_f32_16x16x32_bf16 v[16:19], v[212:215], v[164:167], v[16:19]
	v_mfma_f32_16x16x32_bf16 v[16:19], v[200:203], v[160:163], v[16:19]
	v_mfma_f32_16x16x32_bf16 v[0:3], v[200:203], v[168:171], v[0:3]
	v_mfma_f32_16x16x32_bf16 v[0:3], v[212:215], v[172:175], v[0:3]
	v_mfma_f32_16x16x32_bf16 v[4:7], v[196:199], v[172:175], v[4:7]
	v_mfma_f32_16x16x32_bf16 v[4:7], v[192:195], v[168:171], v[4:7]
	s_barrier
	s_add_i32 s41, s41, 2
	s_add_u32 s38, s38, 0x100
	s_addc_u32 s39, s39, 0
	s_add_u32 s21, s21, 0x100
	s_addc_u32 s23, s23, 0
	s_cmp_gt_u32 s41, 13
.LBB0_353:
	ds_read_b128 v[128:131], v207
	ds_read_b128 v[132:135], v207 offset:1024
	ds_read_b128 v[136:139], v207 offset:2048
	ds_read_b128 v[140:143], v207 offset:3072
	s_add_u32 s42, s38, 0xfffc0080
	s_addc_u32 s43, s39, -1
	s_cmp_eq_u32 s41, 12
	s_cselect_b32 s45, s1, s43
	s_cselect_b32 s44, s0, s42
	s_cselect_b32 s43, s25, s23
	s_cselect_b32 s42, s24, s21
	s_add_i32 m0, s54, 0xc000
	ds_read_b128 v[144:147], v209
	ds_read_b128 v[148:151], v209 offset:1024
	ds_read_b128 v[152:155], v209 offset:2048
	ds_read_b128 v[156:159], v209 offset:3072
	ds_read_b128 v[160:163], v209 offset:4096
	ds_read_b128 v[164:167], v209 offset:5120
	ds_read_b128 v[168:171], v209 offset:6144
	ds_read_b128 v[172:175], v209 offset:7168
	global_load_lds_dwordx4 v184, s[38:39]
	s_add_i32 m0, s54, 0xe000
	s_nop 0
	global_load_lds_dwordx4 v186, s[38:39]
	s_waitcnt lgkmcnt(8)
	s_barrier
	s_waitcnt lgkmcnt(6)
	v_mfma_f32_16x16x32_bf16 v[124:127], v[128:131], v[144:147], v[124:127]
	v_mfma_f32_16x16x32_bf16 v[124:127], v[132:135], v[148:151], v[124:127]
	v_mfma_f32_16x16x32_bf16 v[120:123], v[140:143], v[148:151], v[120:123]
	v_mfma_f32_16x16x32_bf16 v[120:123], v[136:139], v[144:147], v[120:123]
	s_waitcnt lgkmcnt(4)
	v_mfma_f32_16x16x32_bf16 v[104:107], v[136:139], v[152:155], v[104:107]
	v_mfma_f32_16x16x32_bf16 v[104:107], v[140:143], v[156:159], v[104:107]
	v_mfma_f32_16x16x32_bf16 v[108:111], v[132:135], v[156:159], v[108:111]
	v_mfma_f32_16x16x32_bf16 v[108:111], v[128:131], v[152:155], v[108:111]
	s_waitcnt lgkmcnt(2)
	v_mfma_f32_16x16x32_bf16 v[92:95], v[128:131], v[160:163], v[92:95]
	v_mfma_f32_16x16x32_bf16 v[92:95], v[132:135], v[164:167], v[92:95]
	v_mfma_f32_16x16x32_bf16 v[88:91], v[140:143], v[164:167], v[88:91]
	v_mfma_f32_16x16x32_bf16 v[88:91], v[136:139], v[160:163], v[88:91]
	s_waitcnt lgkmcnt(0)
	v_mfma_f32_16x16x32_bf16 v[72:75], v[136:139], v[168:171], v[72:75]
	v_mfma_f32_16x16x32_bf16 v[72:75], v[140:143], v[172:175], v[72:75]
	v_mfma_f32_16x16x32_bf16 v[76:79], v[132:135], v[172:175], v[76:79]
	v_mfma_f32_16x16x32_bf16 v[76:79], v[128:131], v[168:171], v[76:79]
	s_barrier
	s_add_i32 s69, s66, s51
	s_add_u32 s90, s42, 0x80
	s_addc_u32 s91, s43, 0
	s_mov_b32 m0, s69
	ds_read_b128 v[192:195], v210
	ds_read_b128 v[196:199], v210 offset:1024
	ds_read_b128 v[200:203], v210 offset:2048
	ds_read_b128 v[212:215], v210 offset:3072
	global_load_lds_dwordx4 v178, s[42:43]
	s_add_i32 m0, s69, 0x2000
	s_nop 0
	global_load_lds_dwordx4 v182, s[42:43]
	s_barrier
; #define PG8_STAGE(bufoff, gbase, voff) do { _Pragma("unroll") for (int _i = 0; _i < 2; ++_i) \
;         __builtin_amdgcn_global_load_lds((const unsigned*)((const char*)(gbase) + (voff)[_i]), (LAS unsigned*)(lds + (bufoff) + ldsw + _i * 8192), 16, 0, 0); } while (0)
; #define PG8_LDA(dst, b, h) do { _Pragma("unroll") for (int m = 0; m < 4; ++m) _Pragma("unroll") for (int k = 0; k < 2; ++k) dst[m][k] = *(const LAS bf16x8*)(lds + PG8_SA(b, h) + aoff + m * 2048 + k * 1024); } while (0)
; #define PG8_WAIT_V(n) asm volatile("s_waitcnt vmcnt(" #n ")" ::: "memory")
; #define PG8_BAR __builtin_amdgcn_s_barrier()
; template <class Epi, class Ptrs>
; __device__ __forceinline__ void gemm_phase(LAS unsigned char* lds, const int K, const StaticOrder& S, const Ptrs& P, const Epi& E) {
;     ...
;         for (int t = 0; t < nt; t += 2) {
;             const bool last = (t == nt - 2);
;             const char* a1 = cA + (size_t)(t + 1) * kstep;
;             const char* a2 = last ? nA : cA + (size_t)(t + 2) * kstep; const char* b2 = last ? nB : cB + (size_t)(t + 2) * kstep;
;             const char* a3 = a2 + kstep; const char* b3 = b2 + kstep;
;             PG8_LDB(B0, 0, 0); PG8_SCHED; PG8_LDA(At, 0, 0); PG8_STAGE(PG8_SA(1, 1), a1 + hstep, voffA);
;             PG8_WAIT_L(8); PG8_BAR; PG8_WAIT_L(0); PG8_MMA(0, 0, At, B0); PG8_BAR; PG8_SCHED;
;             PG8_LDB(B1, 0, 1); PG8_STAGE(PG8_SB(0, 0), b2, voffB);
;             PG8_BAR; PG8_WAIT_L(0); PG8_MMA(0, 1, At, B1); PG8_BAR;
;             PG8_LDA(At, 0, 1); PG8_STAGE(PG8_SA(0, 0), a2, voffA);
;             PG8_BAR; PG8_WAIT_L(0); PG8_MMA(1, 0, At, B0); PG8_BAR; PG8_SCHED;
;             PG8_STAGE(PG8_SB(0, 1), b2 + hstep, voffB);
;             PG8_WAIT_V(6); PG8_BAR; PG8_MMA(1, 1, At, B1); PG8_BAR;
;             PG8_LDB(B0, 1, 0); PG8_SCHED; PG8_LDA(At, 1, 0); PG8_STAGE(PG8_SA(0, 1), a2 + hstep, voffA);
;             PG8_WAIT_L(8); PG8_BAR; PG8_WAIT_L(0); PG8_MMA(0, 0, At, B0); PG8_BAR; PG8_SCHED;
;             PG8_LDB(B1, 1, 1); PG8_STAGE(PG8_SB(1, 0), b3, voffB);
;             PG8_BAR; PG8_WAIT_L(0); PG8_MMA(0, 1, At, B1); PG8_BAR;
;             PG8_LDA(At, 1, 1); PG8_STAGE(PG8_SA(1, 0), a3, voffA);
;             PG8_BAR; PG8_WAIT_L(0); PG8_MMA(1, 0, At, B0); PG8_BAR; PG8_SCHED;
;             PG8_STAGE(PG8_SB(1, 1), b3 + hstep, voffB);
;             PG8_WAIT_V(6); PG8_BAR; PG8_MMA(1, 1, At, B1); PG8_BAR;
	s_waitcnt lgkmcnt(0)
	v_mfma_f32_16x16x32_bf16 v[116:119], v[192:195], v[144:147], v[116:119]
	v_mfma_f32_16x16x32_bf16 v[116:119], v[196:199], v[148:151], v[116:119]
	v_mfma_f32_16x16x32_bf16 v[112:115], v[212:215], v[148:151], v[112:115]
	v_mfma_f32_16x16x32_bf16 v[112:115], v[200:203], v[144:147], v[112:115]
	v_mfma_f32_16x16x32_bf16 v[96:99], v[200:203], v[152:155], v[96:99]
	v_mfma_f32_16x16x32_bf16 v[96:99], v[212:215], v[156:159], v[96:99]
	v_mfma_f32_16x16x32_bf16 v[100:103], v[196:199], v[156:159], v[100:103]
	v_mfma_f32_16x16x32_bf16 v[100:103], v[192:195], v[152:155], v[100:103]
	v_mfma_f32_16x16x32_bf16 v[84:87], v[192:195], v[160:163], v[84:87]
	v_mfma_f32_16x16x32_bf16 v[84:87], v[196:199], v[164:167], v[84:87]
	v_mfma_f32_16x16x32_bf16 v[80:83], v[212:215], v[164:167], v[80:83]
	v_mfma_f32_16x16x32_bf16 v[80:83], v[200:203], v[160:163], v[80:83]
	v_mfma_f32_16x16x32_bf16 v[64:67], v[200:203], v[168:171], v[64:67]
	v_mfma_f32_16x16x32_bf16 v[64:67], v[212:215], v[172:175], v[64:67]
	v_mfma_f32_16x16x32_bf16 v[68:71], v[196:199], v[172:175], v[68:71]
	v_mfma_f32_16x16x32_bf16 v[68:71], v[192:195], v[168:171], v[68:71]
	s_barrier
	s_mov_b32 m0, s54
	s_add_u32 s92, s44, 0x80
	s_addc_u32 s93, s45, 0
	ds_read_b128 v[144:147], v209 offset:16384
	ds_read_b128 v[148:151], v209 offset:17408
	ds_read_b128 v[152:155], v209 offset:18432
	ds_read_b128 v[156:159], v209 offset:19456
	ds_read_b128 v[160:163], v209 offset:20480
	ds_read_b128 v[164:167], v209 offset:21504
	ds_read_b128 v[168:171], v209 offset:22528
	ds_read_b128 v[172:175], v209 offset:23552
	global_load_lds_dwordx4 v176, s[44:45]
	s_mov_b32 m0, s55
	s_nop 0
	global_load_lds_dwordx4 v180, s[44:45]
	s_barrier
	s_waitcnt lgkmcnt(6)
	v_mfma_f32_16x16x32_bf16 v[60:63], v[128:131], v[144:147], v[60:63]
	v_mfma_f32_16x16x32_bf16 v[60:63], v[132:135], v[148:151], v[60:63]
	v_mfma_f32_16x16x32_bf16 v[56:59], v[140:143], v[148:151], v[56:59]
	v_mfma_f32_16x16x32_bf16 v[56:59], v[136:139], v[144:147], v[56:59]
	s_waitcnt lgkmcnt(4)
	v_mfma_f32_16x16x32_bf16 v[40:43], v[136:139], v[152:155], v[40:43]
	v_mfma_f32_16x16x32_bf16 v[40:43], v[140:143], v[156:159], v[40:43]
	v_mfma_f32_16x16x32_bf16 v[44:47], v[132:135], v[156:159], v[44:47]
	v_mfma_f32_16x16x32_bf16 v[44:47], v[128:131], v[152:155], v[44:47]
	s_waitcnt lgkmcnt(2)
	v_mfma_f32_16x16x32_bf16 v[28:31], v[128:131], v[160:163], v[28:31]
	v_mfma_f32_16x16x32_bf16 v[28:31], v[132:135], v[164:167], v[28:31]
	v_mfma_f32_16x16x32_bf16 v[24:27], v[140:143], v[164:167], v[24:27]
	v_mfma_f32_16x16x32_bf16 v[24:27], v[136:139], v[160:163], v[24:27]
	s_waitcnt lgkmcnt(0)
	v_mfma_f32_16x16x32_bf16 v[8:11], v[136:139], v[168:171], v[8:11]
	v_mfma_f32_16x16x32_bf16 v[8:11], v[140:143], v[172:175], v[8:11]
	v_mfma_f32_16x16x32_bf16 v[12:15], v[132:135], v[172:175], v[12:15]
	v_mfma_f32_16x16x32_bf16 v[12:15], v[128:131], v[168:171], v[12:15]
	s_barrier
	s_add_u32 s70, s42, 0x40000
	s_addc_u32 s71, s43, 0
	s_add_i32 s69, s67, s51
	s_mov_b32 m0, s69
	s_nop 0
	global_load_lds_dwordx4 v178, s[70:71]
	s_add_i32 m0, s69, 0x2000
	s_nop 0
	global_load_lds_dwordx4 v182, s[70:71]
	s_waitcnt vmcnt(6)
	s_barrier
	v_mfma_f32_16x16x32_bf16 v[52:55], v[192:195], v[144:147], v[52:55]
	v_mfma_f32_16x16x32_bf16 v[52:55], v[196:199], v[148:151], v[52:55]
	v_mfma_f32_16x16x32_bf16 v[48:51], v[212:215], v[148:151], v[48:51]
	v_mfma_f32_16x16x32_bf16 v[48:51], v[200:203], v[144:147], v[48:51]
	v_mfma_f32_16x16x32_bf16 v[32:35], v[200:203], v[152:155], v[32:35]
	v_mfma_f32_16x16x32_bf16 v[32:35], v[212:215], v[156:159], v[32:35]
	v_mfma_f32_16x16x32_bf16 v[36:39], v[196:199], v[156:159], v[36:39]
	v_mfma_f32_16x16x32_bf16 v[36:39], v[192:195], v[152:155], v[36:39]
	v_mfma_f32_16x16x32_bf16 v[20:23], v[192:195], v[160:163], v[20:23]
	v_mfma_f32_16x16x32_bf16 v[20:23], v[196:199], v[164:167], v[20:23]
	v_mfma_f32_16x16x32_bf16 v[16:19], v[212:215], v[164:167], v[16:19]
	v_mfma_f32_16x16x32_bf16 v[16:19], v[200:203], v[160:163], v[16:19]
	v_mfma_f32_16x16x32_bf16 v[0:3], v[200:203], v[168:171], v[0:3]
	v_mfma_f32_16x16x32_bf16 v[0:3], v[212:215], v[172:175], v[0:3]
	v_mfma_f32_16x16x32_bf16 v[4:7], v[196:199], v[172:175], v[4:7]
	v_mfma_f32_16x16x32_bf16 v[4:7], v[192:195], v[168:171], v[4:7]
	s_barrier
	s_add_i32 s69, 0, 0x18000
	ds_read_b128 v[128:131], v252
	ds_read_b128 v[132:135], v252 offset:1024
	ds_read_b128 v[136:139], v252 offset:2048
	ds_read_b128 v[140:143], v252 offset:3072
	s_add_u32 s44, s44, 0x40000
	s_addc_u32 s45, s45, 0
	s_mov_b32 m0, s56
	ds_read_b128 v[144:147], v209 offset:32768
	ds_read_b128 v[148:151], v209 offset:33792
	ds_read_b128 v[152:155], v209 offset:34816
	ds_read_b128 v[156:159], v209 offset:35840
	ds_read_b128 v[160:163], v209 offset:36864
	ds_read_b128 v[164:167], v209 offset:37888
	ds_read_b128 v[168:171], v209 offset:38912
	ds_read_b128 v[172:175], v209 offset:39936
	global_load_lds_dwordx4 v176, s[44:45]
	s_mov_b32 m0, s57
	s_nop 0
	global_load_lds_dwordx4 v180, s[44:45]
	s_waitcnt lgkmcnt(8)
	s_barrier
	s_waitcnt lgkmcnt(6)
	v_mfma_f32_16x16x32_bf16 v[124:127], v[128:131], v[144:147], v[124:127]
	v_mfma_f32_16x16x32_bf16 v[124:127], v[132:135], v[148:151], v[124:127]
	v_mfma_f32_16x16x32_bf16 v[120:123], v[140:143], v[148:151], v[120:123]
	v_mfma_f32_16x16x32_bf16 v[120:123], v[136:139], v[144:147], v[120:123]
	s_waitcnt lgkmcnt(4)
	v_mfma_f32_16x16x32_bf16 v[104:107], v[136:139], v[152:155], v[104:107]
	v_mfma_f32_16x16x32_bf16 v[104:107], v[140:143], v[156:159], v[104:107]
	v_mfma_f32_16x16x32_bf16 v[108:111], v[132:135], v[156:159], v[108:111]
	v_mfma_f32_16x16x32_bf16 v[108:111], v[128:131], v[152:155], v[108:111]
	s_waitcnt lgkmcnt(2)
	v_mfma_f32_16x16x32_bf16 v[92:95], v[128:131], v[160:163], v[92:95]
	v_mfma_f32_16x16x32_bf16 v[92:95], v[132:135], v[164:167], v[92:95]
	v_mfma_f32_16x16x32_bf16 v[88:91], v[140:143], v[164:167], v[88:91]
	v_mfma_f32_16x16x32_bf16 v[88:91], v[136:139], v[160:163], v[88:91]
	s_waitcnt lgkmcnt(0)
	v_mfma_f32_16x16x32_bf16 v[72:75], v[136:139], v[168:171], v[72:75]
	v_mfma_f32_16x16x32_bf16 v[72:75], v[140:143], v[172:175], v[72:75]
	v_mfma_f32_16x16x32_bf16 v[76:79], v[132:135], v[172:175], v[76:79]
	v_mfma_f32_16x16x32_bf16 v[76:79], v[128:131], v[168:171], v[76:79]
	s_barrier
; #define PG8_STAGE(bufoff, gbase, voff) do { _Pragma("unroll") for (int _i = 0; _i < 2; ++_i) \
;         __builtin_amdgcn_global_load_lds((const unsigned*)((const char*)(gbase) + (voff)[_i]), (LAS unsigned*)(lds + (bufoff) + ldsw + _i * 8192), 16, 0, 0); } while (0)
; #define PG8_LDA(dst, b, h) do { _Pragma("unroll") for (int m = 0; m < 4; ++m) _Pragma("unroll") for (int k = 0; k < 2; ++k) dst[m][k] = *(const LAS bf16x8*)(lds + PG8_SA(b, h) + aoff + m * 2048 + k * 1024); } while (0)
; #define PG8_LDB(dst, b, h) do { _Pragma("unroll") for (int n = 0; n < 2; ++n) _Pragma("unroll") for (int k = 0; k < 2; ++k) dst[n][k] = *(const LAS bf16x8*)(lds + PG8_SB(b, h) + boff + n * 2048 + k * 1024); } while (0)
; #define PG8_WAIT_V(n) asm volatile("s_waitcnt vmcnt(" #n ")" ::: "memory")
; #define PG8_WAIT_L(n) asm volatile("s_waitcnt lgkmcnt(" #n ")" ::: "memory")
; #define PG8_BAR __builtin_amdgcn_s_barrier()
; #define PG8_SCHED __builtin_amdgcn_sched_barrier(0)
; template <class Epi, class Ptrs>
; __device__ __forceinline__ void gemm_phase(LAS unsigned char* lds, const int K, const StaticOrder& S, const Ptrs& P, const Epi& E) {
;     ...
;             PG8_LDB(B0, 0, 0); PG8_SCHED; PG8_LDA(At, 0, 0); PG8_STAGE(PG8_SA(1, 1), a1 + hstep, voffA);
;             PG8_WAIT_L(8); PG8_BAR; PG8_WAIT_L(0); PG8_MMA(0, 0, At, B0); PG8_BAR; PG8_SCHED;
;             PG8_LDB(B1, 0, 1); PG8_STAGE(PG8_SB(0, 0), b2, voffB);
;             PG8_BAR; PG8_WAIT_L(0); PG8_MMA(0, 1, At, B1); PG8_BAR;
;             PG8_LDA(At, 0, 1); PG8_STAGE(PG8_SA(0, 0), a2, voffA);
;             PG8_BAR; PG8_WAIT_L(0); PG8_MMA(1, 0, At, B0); PG8_BAR; PG8_SCHED;
;             PG8_STAGE(PG8_SB(0, 1), b2 + hstep, voffB);
;             PG8_WAIT_V(6); PG8_BAR; PG8_MMA(1, 1, At, B1); PG8_BAR;
;             PG8_LDB(B0, 1, 0); PG8_SCHED; PG8_LDA(At, 1, 0); PG8_STAGE(PG8_SA(0, 1), a2 + hstep, voffA);
;             PG8_WAIT_L(8); PG8_BAR; PG8_WAIT_L(0); PG8_MMA(0, 0, At, B0); PG8_BAR; PG8_SCHED;
;             PG8_LDB(B1, 1, 1); PG8_STAGE(PG8_SB(1, 0), b3, voffB);
;             PG8_BAR; PG8_WAIT_L(0); PG8_MMA(0, 1, At, B1); PG8_BAR;
;             PG8_LDA(At, 1, 1); PG8_STAGE(PG8_SA(1, 0), a3, voffA);
;             PG8_BAR; PG8_WAIT_L(0); PG8_MMA(1, 0, At, B0); PG8_BAR; PG8_SCHED;
;             PG8_STAGE(PG8_SB(1, 1), b3 + hstep, voffB);
;             PG8_WAIT_V(6); PG8_BAR; PG8_MMA(1, 1, At, B1); PG8_BAR;
	s_add_i32 s44, 0, 0x1c000
	s_add_i32 s45, s69, s51
	s_mov_b32 m0, s45
	ds_read_b128 v[192:195], v253
	ds_read_b128 v[196:199], v253 offset:1024
	ds_read_b128 v[200:203], v253 offset:2048
	ds_read_b128 v[212:215], v253 offset:3072
	global_load_lds_dwordx4 v178, s[90:91]
	s_add_i32 m0, s45, 0x2000
	s_nop 0
	global_load_lds_dwordx4 v182, s[90:91]
	s_barrier
	s_waitcnt lgkmcnt(0)
	v_mfma_f32_16x16x32_bf16 v[116:119], v[192:195], v[144:147], v[116:119]
	v_mfma_f32_16x16x32_bf16 v[116:119], v[196:199], v[148:151], v[116:119]
	v_mfma_f32_16x16x32_bf16 v[112:115], v[212:215], v[148:151], v[112:115]
	v_mfma_f32_16x16x32_bf16 v[112:115], v[200:203], v[144:147], v[112:115]
	v_mfma_f32_16x16x32_bf16 v[96:99], v[200:203], v[152:155], v[96:99]
	v_mfma_f32_16x16x32_bf16 v[96:99], v[212:215], v[156:159], v[96:99]
	v_mfma_f32_16x16x32_bf16 v[100:103], v[196:199], v[156:159], v[100:103]
	v_mfma_f32_16x16x32_bf16 v[100:103], v[192:195], v[152:155], v[100:103]
	v_mfma_f32_16x16x32_bf16 v[84:87], v[192:195], v[160:163], v[84:87]
	v_mfma_f32_16x16x32_bf16 v[84:87], v[196:199], v[164:167], v[84:87]
	v_mfma_f32_16x16x32_bf16 v[80:83], v[212:215], v[164:167], v[80:83]
	v_mfma_f32_16x16x32_bf16 v[80:83], v[200:203], v[160:163], v[80:83]
	v_mfma_f32_16x16x32_bf16 v[64:67], v[200:203], v[168:171], v[64:67]
	v_mfma_f32_16x16x32_bf16 v[64:67], v[212:215], v[172:175], v[64:67]
	v_mfma_f32_16x16x32_bf16 v[68:71], v[196:199], v[172:175], v[68:71]
	v_mfma_f32_16x16x32_bf16 v[68:71], v[192:195], v[168:171], v[68:71]
	s_barrier
	s_mov_b32 m0, s63
	ds_read_b128 v[144:147], v209 offset:49152
	ds_read_b128 v[148:151], v209 offset:50176
	ds_read_b128 v[152:155], v209 offset:51200
	ds_read_b128 v[156:159], v209 offset:52224
	ds_read_b128 v[160:163], v209 offset:53248
	ds_read_b128 v[164:167], v209 offset:54272
	ds_read_b128 v[168:171], v209 offset:55296
	ds_read_b128 v[172:175], v209 offset:56320
	global_load_lds_dwordx4 v176, s[92:93]
	s_mov_b32 m0, s64
	s_nop 0
	global_load_lds_dwordx4 v180, s[92:93]
	s_barrier
	s_waitcnt lgkmcnt(6)
	v_mfma_f32_16x16x32_bf16 v[60:63], v[128:131], v[144:147], v[60:63]
	v_mfma_f32_16x16x32_bf16 v[60:63], v[132:135], v[148:151], v[60:63]
	v_mfma_f32_16x16x32_bf16 v[56:59], v[140:143], v[148:151], v[56:59]
	v_mfma_f32_16x16x32_bf16 v[56:59], v[136:139], v[144:147], v[56:59]
	s_waitcnt lgkmcnt(4)
	v_mfma_f32_16x16x32_bf16 v[40:43], v[136:139], v[152:155], v[40:43]
	v_mfma_f32_16x16x32_bf16 v[40:43], v[140:143], v[156:159], v[40:43]
	v_mfma_f32_16x16x32_bf16 v[44:47], v[132:135], v[156:159], v[44:47]
	v_mfma_f32_16x16x32_bf16 v[44:47], v[128:131], v[152:155], v[44:47]
	s_waitcnt lgkmcnt(2)
	v_mfma_f32_16x16x32_bf16 v[28:31], v[128:131], v[160:163], v[28:31]
	v_mfma_f32_16x16x32_bf16 v[28:31], v[132:135], v[164:167], v[28:31]
	v_mfma_f32_16x16x32_bf16 v[24:27], v[140:143], v[164:167], v[24:27]
	v_mfma_f32_16x16x32_bf16 v[24:27], v[136:139], v[160:163], v[24:27]
	s_waitcnt lgkmcnt(0)
	v_mfma_f32_16x16x32_bf16 v[8:11], v[136:139], v[168:171], v[8:11]
	v_mfma_f32_16x16x32_bf16 v[8:11], v[140:143], v[172:175], v[8:11]
	v_mfma_f32_16x16x32_bf16 v[12:15], v[132:135], v[172:175], v[12:15]
	v_mfma_f32_16x16x32_bf16 v[12:15], v[128:131], v[168:171], v[12:15]
	s_barrier
	s_add_u32 s42, s42, 0x40080
	s_addc_u32 s43, s43, 0
	s_add_i32 s44, s44, s51
	s_mov_b32 m0, s44
	s_nop 0
	global_load_lds_dwordx4 v178, s[42:43]
	s_add_i32 m0, s44, 0x2000
	s_nop 0
	global_load_lds_dwordx4 v182, s[42:43]
	s_waitcnt vmcnt(6)
	s_barrier
	v_mfma_f32_16x16x32_bf16 v[52:55], v[192:195], v[144:147], v[52:55]
	v_mfma_f32_16x16x32_bf16 v[52:55], v[196:199], v[148:151], v[52:55]
	v_mfma_f32_16x16x32_bf16 v[48:51], v[212:215], v[148:151], v[48:51]
	v_mfma_f32_16x16x32_bf16 v[48:51], v[200:203], v[144:147], v[48:51]
	v_mfma_f32_16x16x32_bf16 v[32:35], v[200:203], v[152:155], v[32:35]
	v_mfma_f32_16x16x32_bf16 v[32:35], v[212:215], v[156:159], v[32:35]
	v_mfma_f32_16x16x32_bf16 v[36:39], v[196:199], v[156:159], v[36:39]
	v_mfma_f32_16x16x32_bf16 v[36:39], v[192:195], v[152:155], v[36:39]
	v_mfma_f32_16x16x32_bf16 v[20:23], v[192:195], v[160:163], v[20:23]
	v_mfma_f32_16x16x32_bf16 v[20:23], v[196:199], v[164:167], v[20:23]
	v_mfma_f32_16x16x32_bf16 v[16:19], v[212:215], v[164:167], v[16:19]
	v_mfma_f32_16x16x32_bf16 v[16:19], v[200:203], v[160:163], v[16:19]
	v_mfma_f32_16x16x32_bf16 v[0:3], v[200:203], v[168:171], v[0:3]
	v_mfma_f32_16x16x32_bf16 v[0:3], v[212:215], v[172:175], v[0:3]
	v_mfma_f32_16x16x32_bf16 v[4:7], v[196:199], v[172:175], v[4:7]
	v_mfma_f32_16x16x32_bf16 v[4:7], v[192:195], v[168:171], v[4:7]
	s_barrier
; __device__ __forceinline__ unsigned cvt_pk_bf16(float lo, float hi) { unsigned r; asm volatile("v_cvt_pk_bf16_f32 %0, %1, %2" : "=v"(r) : "v"(lo), "v"(hi)); return r; }
; __device__ __forceinline__ float x16_sum(float x) { auto s = __builtin_amdgcn_permlane16_swap(__float_as_uint(x), __float_as_uint(x), false, false); return __uint_as_float(s[0]) + __uint_as_float(s[1]); }
; __device__ __forceinline__ float x32_sum(float x) { auto s = __builtin_amdgcn_permlane32_swap(__float_as_uint(x), __float_as_uint(x), false, false); return __uint_as_float(s[0]) + __uint_as_float(s[1]); }
;     __device__ __forceinline__ void operator()(const f32x4 (&acc)[2][2][4][2], const Unit& u, int ui, int wr, int wc, int fr, int fq) const {
;         const int row0 = u.pm * 256 + wr * 64 + fr, col0 = u.pn * 256 + wc * 32 + 8 * fq;
;         const float* xb0 = (u.pm * 256 < MP) ? xp : xs - (size_t)MP * DM;
; #pragma unroll
;         for (int ai = 0; ai < 2; ++ai) {
;             f32x4 xv[4][2][2];
; #pragma unroll
;             for (int m = 0; m < 4; ++m)
; #pragma unroll
;                 for (int bj = 0; bj < 2; ++bj) { const float* p = xb0 + (size_t)(row0 + ai * 128 + m * 16) * DM + col0 + bj * 128; xv[m][bj][0] = *(const f32x4*)p; xv[m][bj][1] = *(const f32x4*)(p + 4); }
; #pragma unroll
;             for (int m = 0; m < 4; ++m) { const int row = row0 + ai * 128 + m * 16; const size_t off = (size_t)row * DM + col0; float ss = 0.f;
; #pragma unroll
;                 for (int bj = 0; bj < 2; ++bj) {
;                     const f32x4 v0 = acc[ai][bj][m][0] + xv[m][bj][0], v1 = acc[ai][bj][m][1] + xv[m][bj][1];
;                     u32x4 w; w.x = cvt_pk_bf16(v0[0], v0[1]); w.y = cvt_pk_bf16(v0[2], v0[3]); w.z = cvt_pk_bf16(v1[0], v1[1]); w.w = cvt_pk_bf16(v1[2], v1[3]);
;                     *(u32x4*)(xb + off + bj * 128) = w;
;                     ss += (v0[0] * v0[0] + v0[1] * v0[1]) + (v0[2] * v0[2] + v0[3] * v0[3]) + (v1[0] * v1[0] + v1[1] * v1[1]) + (v1[2] * v1[2] + v1[3] * v1[3]); }
;                 ss = x32_sum(x16_sum(ss));
;                 if (fq == 0) part[(size_t)row * 16 + u.pn * 4 + wc] = ss; }
	s_add_i32 s41, s41, 2
	s_add_u32 s38, s38, 0x100
	s_addc_u32 s39, s39, 0
	s_add_u32 s21, s21, 0x100
	s_addc_u32 s23, s23, 0
	s_cmp_gt_u32 s41, 13
	s_cbranch_scc0 .LBB0_353
	s_cmpk_lt_i32 s40, 0x80
	v_lshl_add_u32 v194, s40, 8, v204
	v_lshl_or_b32 v192, s12, 8, v206
	s_cselect_b32 s21, s37, s61
	s_cselect_b32 s23, s36, s60
	v_mov_b32_e32 v128, s23
	v_mov_b32_e32 v129, s21
	v_ashrrev_i32_e32 v193, 31, v192
	v_ashrrev_i32_e32 v195, 31, v194
	v_lshl_add_u64 v[196:197], v[192:193], 2, v[128:129]
	v_lshlrev_b64 v[128:129], 12, v[194:195]
	v_or_b32_e32 v202, 16, v194
	v_or_b32_e32 v200, 32, v194
	v_or_b32_e32 v198, 48, v194
	v_lshl_add_u64 v[128:129], v[196:197], 0, v[128:129]
	v_ashrrev_i32_e32 v203, 31, v202
	v_ashrrev_i32_e32 v201, 31, v200
	v_ashrrev_i32_e32 v199, 31, v198
	global_load_dwordx4 v[212:215], v[128:129], off
	global_load_dwordx4 v[216:219], v[128:129], off offset:16
	global_load_dwordx4 v[220:223], v[128:129], off offset:512
	global_load_dwordx4 v[224:227], v[128:129], off offset:528
	v_lshlrev_b64 v[128:129], 12, v[202:203]
	v_lshlrev_b64 v[130:131], 12, v[200:201]
	v_lshlrev_b64 v[132:133], 12, v[198:199]
	v_lshl_add_u64 v[128:129], v[196:197], 0, v[128:129]
	v_lshl_add_u64 v[130:131], v[196:197], 0, v[130:131]
	v_lshl_add_u64 v[132:133], v[196:197], 0, v[132:133]
	global_load_dwordx4 v[168:171], v[128:129], off offset:16
	global_load_dwordx4 v[172:175], v[128:129], off
	global_load_dwordx4 v[160:163], v[128:129], off offset:528
	global_load_dwordx4 v[164:167], v[128:129], off offset:512
	global_load_dwordx4 v[152:155], v[130:131], off offset:16
	global_load_dwordx4 v[156:159], v[130:131], off
	global_load_dwordx4 v[144:147], v[130:131], off offset:528
	global_load_dwordx4 v[148:151], v[130:131], off offset:512
	global_load_dwordx4 v[136:139], v[132:133], off offset:16
	global_load_dwordx4 v[140:143], v[132:133], off
	s_nop 0
	global_load_dwordx4 v[128:131], v[132:133], off offset:528
	s_nop 0
	global_load_dwordx4 v[132:135], v[132:133], off offset:512
	v_lshlrev_b64 v[228:229], 11, v[194:195]
	v_lshl_add_u64 v[228:229], s[14:15], 0, v[228:229]
	v_lshl_add_u64 v[228:229], v[192:193], 1, v[228:229]
	s_lshl_b32 s38, s12, 2
	s_ashr_i32 s39, s38, 31
	s_waitcnt vmcnt(0)
	v_pk_add_f32 v[126:127], v[126:127], v[214:215]
	v_pk_add_f32 v[124:125], v[124:125], v[212:213]
	v_pk_add_f32 v[118:119], v[118:119], v[222:223]
	v_pk_add_f32 v[116:117], v[116:117], v[220:221]
	v_pk_add_f32 v[120:121], v[120:121], v[216:217]
	v_pk_add_f32 v[214:215], v[112:113], v[224:225]
	v_cvt_pk_bf16_f32 v112, v124, v125
	v_cvt_pk_bf16_f32 v113, v126, v127
	v_mul_f32_e32 v125, v125, v125
	v_mul_f32_e32 v127, v127, v127
	v_mul_f32_e32 v211, v117, v117
	v_mul_f32_e32 v216, v119, v119
	v_pk_add_f32 v[122:123], v[122:123], v[218:219]
	v_pk_add_f32 v[212:213], v[114:115], v[226:227]
	v_cvt_pk_bf16_f32 v114, v120, v121
	v_cvt_pk_bf16_f32 v115, v122, v123
	v_mul_f32_e32 v121, v121, v121
	v_mul_f32_e32 v217, v215, v215
	global_store_dwordx4 v[228:229], v[112:115], off
	v_fmac_f32_e32 v125, v124, v124
	v_fmac_f32_e32 v127, v126, v126
	v_cvt_pk_bf16_f32 v112, v116, v117
	v_fmac_f32_e32 v211, v116, v116
	v_fmac_f32_e32 v216, v118, v118
	v_mul_f32_e32 v123, v123, v123
	v_mul_f32_e32 v218, v213, v213
	v_fmac_f32_e32 v121, v120, v120
	v_cvt_pk_bf16_f32 v113, v118, v119
	v_cvt_pk_bf16_f32 v114, v214, v215
	v_cvt_pk_bf16_f32 v115, v212, v213
	v_fmac_f32_e32 v217, v214, v214
	v_add_f32_e32 v116, v125, v127
	global_store_dwordx4 v[228:229], v[112:115], off offset:256
	v_fmac_f32_e32 v123, v122, v122
	v_fmac_f32_e32 v218, v212, v212
	v_add_f32_e32 v112, v211, v216
	v_add_f32_e32 v113, v116, v121
	v_add_f32_e32 v112, v112, v217
	v_add_f32_e32 v113, v123, v113
	v_add_f32_e32 v112, v218, v112
	v_add_f32_e32 v112, v113, v112
	v_mov_b32_e32 v113, v112
	s_nop 1
	v_permlane16_swap_b32_e32 v112, v113
	v_add_f32_e32 v112, v112, v113
	v_mov_b32_e32 v113, v112
	s_nop 1
	v_permlane32_swap_b32_e32 v112, v113
	s_and_saveexec_b64 s[40:41], s[6:7]
	s_cbranch_execz .LBB0_356
	v_lshlrev_b64 v[114:115], 6, v[194:195]
	v_lshl_add_u64 v[114:115], s[16:17], 0, v[114:115]
	v_lshl_add_u64 v[114:115], s[38:39], 2, v[114:115]
	s_lshl_b32 s12, s62, 2
	v_lshl_add_u64 v[114:115], v[114:115], 0, s[12:13]
	v_add_f32_e32 v112, v112, v113
	global_store_dword v[114:115], v112, off

; __device__ __forceinline__ unsigned xb_ld(unsigned* p)              { return __hip_atomic_load(p, __ATOMIC_RELAXED, __HIP_MEMORY_SCOPE_AGENT); }
; __device__ __forceinline__ void xcd_barrier_complete(unsigned* bar, unsigned x, unsigned& nloc, unsigned& nx) {
;     const unsigned G = gridDim.x * gridDim.y * gridDim.z;
;     unsigned sum, cnt, mine, sp = 0u;
;     for (;;) {
;         sum = 0u; cnt = 0u; mine = 0u;
; #pragma unroll
;         for (unsigned j = 0; j < 16; ++j) { const unsigned c = xb_ld(&bar[XB_XCNT(j)]); sum += c; cnt += (c > 0u) ? 1u : 0u; mine = (j == x) ? c : mine; }
;         if (sum == G) break;
;         __builtin_amdgcn_s_sleep(1);
;         if ((++sp & 255u) == 0u) { if (xb_ld(&bar[XB_TMO])) break; if (sp > XB_SPIN_CAP) { atomicAdd(&bar[XB_TMO], 1u); break; } }
;     }
;     nloc = mine > 0u ? mine : 1u; nx = cnt > 0u ? cnt : 1u;
; __device__ __forceinline__ void xcd_barrier(const XcdBarrier& b) {
;     asm volatile("s_waitcnt vmcnt(0)" ::: "memory");
;     __syncthreads();
;     if (threadIdx.x == 0) {
;         unsigned* bar = b.bar;
;         __builtin_amdgcn_s_waitcnt(0);
;         unsigned nloc = b.st[0], nx = b.st[1];
;         if (nloc == 0u) { xcd_barrier_complete(bar, b.x, nloc, nx); b.st[0] = nloc; b.st[1] = nx; }
.LBB0_373:
	s_nop 0
	s_nop 0
	s_nop 0
	s_nop 0
	s_nop 0
	s_nop 0
	s_nop 0
	s_nop 0
	s_nop 0
	s_nop 0
	s_nop 0
	s_nop 0
	s_nop 0
	s_nop 0
	s_nop 0
	s_nop 0
	s_nop 0
	s_nop 0
	s_nop 0
	s_nop 0
	s_nop 0
	s_nop 0
	s_nop 0
	s_nop 0
	s_nop 0
	s_nop 0
	s_nop 0
	s_nop 0
	s_nop 0
	s_nop 0
	s_nop 0
	s_nop 0
	s_nop 0
	s_nop 0
	s_nop 0
	s_nop 0
	s_nop 0
	s_cmp_gt_i32 s31, 4
	s_cselect_b64 s[0:1], -1, 0
	s_and_b64 s[4:5], s[10:11], s[0:1]
	s_andn2_b64 vcc, exec, s[4:5]
	s_cbranch_vccnz .LBB0_423
	s_waitcnt vmcnt(0)
	s_waitcnt vmcnt(0) lgkmcnt(0)
	s_barrier
	s_and_saveexec_b64 s[4:5], s[8:9]
	s_cbranch_execz .LBB0_422
	s_add_i32 s6, 0, 0x25ff0
	v_mov_b32_e32 v0, s6
	s_waitcnt vmcnt(0) expcnt(0) lgkmcnt(0)
	ds_read_b32 v2, v0
	s_add_i32 s6, 0, 0x25ff4
	v_mov_b32_e32 v0, s6
	ds_read_b32 v0, v0
	s_waitcnt lgkmcnt(1)
	v_cmp_ne_u32_e32 vcc, 0, v2
	s_cbranch_vccnz .LBB0_390
	s_load_dwordx2 s[12:13], s[52:53], 0x4
	s_add_u32 s6, s28, 0x3e800200
	s_addc_u32 s7, s29, 0
	s_add_u32 s10, s28, 0x3e800400
	s_addc_u32 s11, s29, 0
	s_waitcnt lgkmcnt(0)
	s_mul_i32 s60, s12, s3
	s_add_u32 s12, s28, 0x3e800500
	s_mul_i32 s60, s60, s13
	s_addc_u32 s13, s29, 0
	s_add_u32 s14, s28, 0x3e800600
	s_addc_u32 s15, s29, 0
	s_add_u32 s16, s28, 0x3e800700
	s_addc_u32 s17, s29, 0
	s_add_u32 s18, s28, 0x3e800800
	s_addc_u32 s19, s29, 0
	s_add_u32 s20, s28, 0x3e800900
	s_addc_u32 s21, s29, 0
	s_add_u32 s22, s28, 0x3e800a00
	s_addc_u32 s23, s29, 0
	s_add_u32 s24, s28, 0x3e800b00
	s_addc_u32 s25, s29, 0
	s_add_u32 s36, s28, 0x3e800c00
	s_addc_u32 s37, s29, 0
	s_add_u32 s38, s28, 0x3e800d00
	s_addc_u32 s39, s29, 0
	s_add_u32 s40, s28, 0x3e800e00
	s_addc_u32 s41, s29, 0
	s_add_u32 s42, s28, 0x3e800f00
	s_addc_u32 s43, s29, 0
	s_add_u32 s44, s28, 0x3e801000
	s_addc_u32 s45, s29, 0
	s_add_u32 s46, s28, 0x3e801100
	s_addc_u32 s47, s29, 0
	s_add_u32 s48, s28, 0x3e801200
	s_addc_u32 s49, s29, 0
	s_add_u32 s50, s28, 0x3e801300
	s_addc_u32 s51, s29, 0
	s_mov_b32 s61, 1
	v_mov_b32_e32 v16, 0
	s_branch .LBB0_378

; #define PG8_STAGE(bufoff, gbase, voff) do { _Pragma("unroll") for (int _i = 0; _i < 2; ++_i) \
;         __builtin_amdgcn_global_load_lds((const unsigned*)((const char*)(gbase) + (voff)[_i]), (LAS unsigned*)(lds + (bufoff) + ldsw + _i * 8192), 16, 0, 0); } while (0)
; #define PG8_WAIT_V(n) asm volatile("s_waitcnt vmcnt(" #n ")" ::: "memory")
; #define PG8_BAR __builtin_amdgcn_s_barrier()
; template <class Epi, class Ptrs>
; __device__ __forceinline__ void gemm_phase(LAS unsigned char* lds, const int K, const StaticOrder& S, const Ptrs& P, const Epi& E) {
;     ...
;     for (int i = 0; i < 2; ++i) { int R, C; stage_rc(tid * 16 + i * 8192, R, C); const int Rb = (R & ~31) + perm32(R & 31);
;         voffA[i] = (unsigned)(R * K + C) * 2u; voffB[i] = (unsigned)(Rb * K + C) * 2u; }
;     const size_t kstep = (size_t)(BK * 2);
;     const size_t hstep = (size_t)HALF * K * 2;
;     const unsigned ldsw = (unsigned)wid * 1024u;
;     const int aoff = lds_byte(wr * 64 + fr, fq * 8), boff = lds_byte(wc * 32 + fr, fq * 8);
;     ...
;     Unit cur, nxt; int ui = 0;
;     if (!S.next(0, cur)) return;
;     f32x4 acc[2][2][4][2];
; #pragma unroll
;     for (int a = 0; a < 2; ++a)
; #pragma unroll
;         for (int b = 0; b < 2; ++b)
; #pragma unroll
;             for (int m = 0; m < 4; ++m)
; #pragma unroll
;                 for (int n = 0; n < 2; ++n) acc[a][b][m][n] = (f32x4){0.f, 0.f, 0.f, 0.f};
;     bf16x8 At[4][2], B0[2][2], B1[2][2];
;     const char* cA; const char* cB; P.get(cur, cA, cB);
;     PG8_STAGE(PG8_SB(0, 0), cB, voffB); PG8_STAGE(PG8_SA(0, 0), cA, voffA); PG8_STAGE(PG8_SB(0, 1), cB + hstep, voffB); PG8_STAGE(PG8_SA(0, 1), cA + hstep, voffA);
;     if (wr == 1) PG8_BAR;
;     PG8_WAIT_V(4); PG8_BAR;
;     PG8_STAGE(PG8_SB(1, 0), cB + kstep, voffB); PG8_STAGE(PG8_SA(1, 0), cA + kstep, voffA); PG8_STAGE(PG8_SB(1, 1), cB + hstep + kstep, voffB);
;     PG8_WAIT_V(6); PG8_BAR;
.LBB0_427:
	s_nop 0
	s_nop 0
	s_nop 0
	s_nop 0
	s_nop 0
	s_nop 0
	s_nop 0
	s_nop 0
	s_nop 0
	s_nop 0
	s_nop 0
	s_nop 0
	s_nop 0
	s_nop 0
	s_nop 0
	s_nop 0
	s_nop 0
	s_nop 0
	s_nop 0
	s_nop 0
	s_nop 0
	s_nop 0
	s_nop 0
	s_nop 0
	s_nop 0
	s_nop 0
	s_nop 0
	s_nop 0
	s_nop 0
	s_nop 0
	s_nop 0
	s_nop 0
	s_nop 0
	s_nop 0
	s_nop 0
	s_nop 0
	s_nop 0
	s_nop 0
	s_nop 0
	s_nop 0
	s_nop 0
	s_nop 0
	s_nop 0
	s_add_u32 s10, s28, 0xe000000
	s_addc_u32 s11, s29, 0
	s_lshl_b32 s4, s4, 5
	s_mov_b64 s[12:13], 0x80
	s_and_b32 s15, s4, 0x60
	s_add_i32 m0, s39, 0x18000
	v_lshl_add_u64 v[6:7], v[6:7], 0, s[12:13]
	s_ashr_i32 s60, s3, 31
	s_lshl_b32 s14, s1, 13
	s_lshl_b32 s16, s15, 7
	s_waitcnt vmcnt(4)
	s_barrier
	global_load_lds_dwordx4 v[6:7], off
	v_lshl_add_u64 v[4:5], v[4:5], 0, s[12:13]
	s_add_i32 m0, s39, 0x1a000
	s_add_i32 s61, s39, 0x8000
	s_add_i32 s62, s39, 0xa000
	global_load_lds_dwordx4 v[4:5], off
	v_lshl_add_u64 v[2:3], v[2:3], 0, s[12:13]
	s_mov_b32 m0, s61
	s_add_u32 s4, s42, 0x40080
	global_load_lds_dwordx4 v[2:3], off
	v_lshl_add_u64 v[0:1], v[0:1], 0, s[12:13]
	s_mov_b32 m0, s62
	s_addc_u32 s5, s43, 0
	global_load_lds_dwordx4 v[0:1], off
	s_add_i32 m0, s39, 0x1c000
	v_lshl_add_u64 v[0:1], s[4:5], 0, v[130:131]
	global_load_lds_dwordx4 v[0:1], off
	v_lshl_add_u64 v[0:1], s[4:5], 0, v[134:135]
	s_add_i32 m0, s39, 0x1e000
	s_sext_i32_i8 s69, s0
	global_load_lds_dwordx4 v[0:1], off
	v_and_b32_e32 v0, 15, v208
	v_lshlrev_b32_e32 v1, 1, v11
	v_lshlrev_b32_e32 v2, 6, v208
	s_movk_i32 s0, 0x3c0
	v_lshlrev_b32_e32 v3, 2, v208
	v_and_or_b32 v2, v2, s0, v1
	v_and_b32_e32 v3, 32, v3
	v_lshl_or_b32 v146, s1, 6, v0
	v_lshl_or_b32 v0, v0, 6, v1
	v_lshlrev_b32_e32 v1, 8, v208
	v_bitop3_b32 v147, s16, v2, v3 bitop3:0xf6
	v_and_b32_e32 v1, 0x38000, v1
	v_lshlrev_b32_e32 v2, 11, v10
	v_or3_b32 v1, v8, v1, v2
	v_add_u32_e32 v136, v1, v9
	v_lshlrev_b32_e32 v1, 4, v12
	s_waitcnt vmcnt(6)
	v_and_b32_e32 v1, 0x78000, v1
	v_bitop3_b32 v0, v0, s14, v3 bitop3:0xde
	v_or3_b32 v1, v8, v1, v2
	s_add_i32 s63, 0, 0x10000
	s_add_i32 s64, 0, 0x14000
	v_or_b32_e32 v148, s15, v11
	v_mov_b32_e32 v137, v131
	v_add_u32_e32 v138, v1, v9
	v_mov_b32_e32 v139, v131
	v_mov_b64_e32 v[140:141], 0x1800
	v_mov_b64_e32 v[142:143], 0x17ff
	v_add_u32_e32 v149, s63, v147
	v_add_u32_e32 v150, 0, v0
	v_add_u32_e32 v151, s64, v147
	s_mov_b64 s[14:15], 0x100000
	s_mov_b32 s65, 0x100000
	s_mov_b64 s[16:17], 0x120000
	s_mov_b32 s66, 0x120000
	s_mov_b64 s[18:19], 0x140000
	s_mov_b32 s67, 0x140000
	s_mov_b64 s[20:21], 0x160000
	s_mov_b32 s68, 0x160000
	s_cmpk_lt_u32 s46, 0x100
	s_cbranch_scc1 .Lsprio_2
	s_setprio 1

; #define PG8_STAGE(bufoff, gbase, voff) do { _Pragma("unroll") for (int _i = 0; _i < 2; ++_i) \
;         __builtin_amdgcn_global_load_lds((const unsigned*)((const char*)(gbase) + (voff)[_i]), (LAS unsigned*)(lds + (bufoff) + ldsw + _i * 8192), 16, 0, 0); } while (0)
; #define PG8_LDA(dst, b, h) do { _Pragma("unroll") for (int m = 0; m < 4; ++m) _Pragma("unroll") for (int k = 0; k < 2; ++k) dst[m][k] = *(const LAS bf16x8*)(lds + PG8_SA(b, h) + aoff + m * 2048 + k * 1024); } while (0)
; #define PG8_WAIT_V(n) asm volatile("s_waitcnt vmcnt(" #n ")" ::: "memory")
; #define PG8_BAR __builtin_amdgcn_s_barrier()
; template <class Epi, class Ptrs>
; __device__ __forceinline__ void gemm_phase(LAS unsigned char* lds, const int K, const StaticOrder& S, const Ptrs& P, const Epi& E) {
;     ...
;         for (int t = 0; t < nt; t += 2) {
;             const bool last = (t == nt - 2);
;             const char* a1 = cA + (size_t)(t + 1) * kstep;
;             const char* a2 = last ? nA : cA + (size_t)(t + 2) * kstep; const char* b2 = last ? nB : cB + (size_t)(t + 2) * kstep;
;             const char* a3 = a2 + kstep; const char* b3 = b2 + kstep;
;             PG8_LDB(B0, 0, 0); PG8_SCHED; PG8_LDA(At, 0, 0); PG8_STAGE(PG8_SA(1, 1), a1 + hstep, voffA);
;             PG8_WAIT_L(8); PG8_BAR; PG8_WAIT_L(0); PG8_MMA(0, 0, At, B0); PG8_BAR; PG8_SCHED;
;             PG8_LDB(B1, 0, 1); PG8_STAGE(PG8_SB(0, 0), b2, voffB);
;             PG8_BAR; PG8_WAIT_L(0); PG8_MMA(0, 1, At, B1); PG8_BAR;
;             PG8_LDA(At, 0, 1); PG8_STAGE(PG8_SA(0, 0), a2, voffA);
;             PG8_BAR; PG8_WAIT_L(0); PG8_MMA(1, 0, At, B0); PG8_BAR; PG8_SCHED;
;             PG8_STAGE(PG8_SB(0, 1), b2 + hstep, voffB);
;             PG8_WAIT_V(6); PG8_BAR; PG8_MMA(1, 1, At, B1); PG8_BAR;
;             PG8_LDB(B0, 1, 0); PG8_SCHED; PG8_LDA(At, 1, 0); PG8_STAGE(PG8_SA(0, 1), a2 + hstep, voffA);
;             PG8_WAIT_L(8); PG8_BAR; PG8_WAIT_L(0); PG8_MMA(0, 0, At, B0); PG8_BAR; PG8_SCHED;
;             PG8_LDB(B1, 1, 1); PG8_STAGE(PG8_SB(1, 0), b3, voffB);
;             PG8_BAR; PG8_WAIT_L(0); PG8_MMA(0, 1, At, B1); PG8_BAR;
;             PG8_LDA(At, 1, 1); PG8_STAGE(PG8_SA(1, 0), a3, voffA);
;             PG8_BAR; PG8_WAIT_L(0); PG8_MMA(1, 0, At, B0); PG8_BAR; PG8_SCHED;
;             PG8_STAGE(PG8_SB(1, 1), b3 + hstep, voffB);
;             PG8_WAIT_V(6); PG8_BAR; PG8_MMA(1, 1, At, B1); PG8_BAR;
.LBB0_432:
	s_add_u32 s40, s40, 0x40080
	s_addc_u32 s41, s41, 0
	s_add_u32 s23, s42, 0x100
	s_addc_u32 s25, s43, 0
	s_mov_b32 s70, -2
	v_add_u32_e32 v252, 0x18000, v147
	v_add_u32_e32 v253, 0x1c000, v147
	ds_read_b128 v[152:155], v149
	ds_read_b128 v[156:159], v149 offset:1024
	ds_read_b128 v[160:163], v149 offset:2048
	ds_read_b128 v[164:167], v149 offset:3072
	s_add_u32 s42, s40, 0xfffc0080
	s_addc_u32 s43, s41, -1
	s_cmp_eq_u32 s70, 12
	s_cselect_b32 s45, s1, s43
	s_cselect_b32 s44, s0, s42
	s_cselect_b32 s43, s37, s25
	s_cselect_b32 s42, s36, s23
	s_add_i32 m0, s39, 0xc000
	ds_read_b128 v[168:171], v150
	ds_read_b128 v[172:175], v150 offset:1024
	ds_read_b128 v[176:179], v150 offset:2048
	ds_read_b128 v[180:183], v150 offset:3072
	ds_read_b128 v[184:187], v150 offset:4096
	ds_read_b128 v[188:191], v150 offset:5120
	ds_read_b128 v[192:195], v150 offset:6144
	ds_read_b128 v[196:199], v150 offset:7168
	global_load_lds_dwordx4 v136, s[40:41]
	s_add_i32 m0, s39, 0xe000
	s_nop 0
	global_load_lds_dwordx4 v138, s[40:41]
	s_waitcnt lgkmcnt(8)
	s_barrier
	s_waitcnt lgkmcnt(6)
	v_mfma_f32_16x16x32_bf16 v[124:127], v[152:155], v[168:171], 0
	v_mfma_f32_16x16x32_bf16 v[124:127], v[156:159], v[172:175], v[124:127]
	v_mfma_f32_16x16x32_bf16 v[120:123], v[164:167], v[172:175], 0
	v_mfma_f32_16x16x32_bf16 v[120:123], v[160:163], v[168:171], v[120:123]
	s_waitcnt lgkmcnt(4)
	v_mfma_f32_16x16x32_bf16 v[104:107], v[160:163], v[176:179], 0
	v_mfma_f32_16x16x32_bf16 v[104:107], v[164:167], v[180:183], v[104:107]
	v_mfma_f32_16x16x32_bf16 v[108:111], v[156:159], v[180:183], 0
	v_mfma_f32_16x16x32_bf16 v[108:111], v[152:155], v[176:179], v[108:111]
	s_waitcnt lgkmcnt(2)
	v_mfma_f32_16x16x32_bf16 v[92:95], v[152:155], v[184:187], 0
	v_mfma_f32_16x16x32_bf16 v[92:95], v[156:159], v[188:191], v[92:95]
	v_mfma_f32_16x16x32_bf16 v[88:91], v[164:167], v[188:191], 0
	v_mfma_f32_16x16x32_bf16 v[88:91], v[160:163], v[184:187], v[88:91]
	s_waitcnt lgkmcnt(0)
	v_mfma_f32_16x16x32_bf16 v[72:75], v[160:163], v[192:195], 0
	v_mfma_f32_16x16x32_bf16 v[72:75], v[164:167], v[196:199], v[72:75]
	v_mfma_f32_16x16x32_bf16 v[76:79], v[156:159], v[196:199], 0
	v_mfma_f32_16x16x32_bf16 v[76:79], v[152:155], v[192:195], v[76:79]
	s_barrier
	s_add_i32 s71, s63, s51
	s_add_u32 s76, s42, 0x80
	s_addc_u32 s77, s43, 0
	s_mov_b32 m0, s71
	ds_read_b128 v[200:203], v151
	ds_read_b128 v[204:207], v151 offset:1024
	ds_read_b128 v[210:213], v151 offset:2048
	ds_read_b128 v[214:217], v151 offset:3072
	global_load_lds_dwordx4 v130, s[42:43]
	s_add_i32 m0, s71, 0x2000
	s_nop 0
	global_load_lds_dwordx4 v134, s[42:43]
	s_barrier
	s_waitcnt lgkmcnt(0)
	v_mfma_f32_16x16x32_bf16 v[116:119], v[200:203], v[168:171], 0
	v_mfma_f32_16x16x32_bf16 v[116:119], v[204:207], v[172:175], v[116:119]
	v_mfma_f32_16x16x32_bf16 v[112:115], v[214:217], v[172:175], 0
	v_mfma_f32_16x16x32_bf16 v[112:115], v[210:213], v[168:171], v[112:115]
	v_mfma_f32_16x16x32_bf16 v[96:99], v[210:213], v[176:179], 0
	v_mfma_f32_16x16x32_bf16 v[96:99], v[214:217], v[180:183], v[96:99]
	v_mfma_f32_16x16x32_bf16 v[100:103], v[204:207], v[180:183], 0
	v_mfma_f32_16x16x32_bf16 v[100:103], v[200:203], v[176:179], v[100:103]
	v_mfma_f32_16x16x32_bf16 v[84:87], v[200:203], v[184:187], 0
	v_mfma_f32_16x16x32_bf16 v[84:87], v[204:207], v[188:191], v[84:87]
	v_mfma_f32_16x16x32_bf16 v[80:83], v[214:217], v[188:191], 0
	v_mfma_f32_16x16x32_bf16 v[80:83], v[210:213], v[184:187], v[80:83]
	v_mfma_f32_16x16x32_bf16 v[64:67], v[210:213], v[192:195], 0
	v_mfma_f32_16x16x32_bf16 v[64:67], v[214:217], v[196:199], v[64:67]
	v_mfma_f32_16x16x32_bf16 v[68:71], v[204:207], v[196:199], 0
	v_mfma_f32_16x16x32_bf16 v[68:71], v[200:203], v[192:195], v[68:71]
	s_barrier
	s_mov_b32 m0, s39
	s_add_u32 s78, s44, 0x80
	s_addc_u32 s79, s45, 0
	ds_read_b128 v[168:171], v150 offset:16384
	ds_read_b128 v[172:175], v150 offset:17408
	ds_read_b128 v[176:179], v150 offset:18432
	ds_read_b128 v[180:183], v150 offset:19456
	ds_read_b128 v[184:187], v150 offset:20480
	ds_read_b128 v[188:191], v150 offset:21504
	ds_read_b128 v[192:195], v150 offset:22528
	ds_read_b128 v[196:199], v150 offset:23552
	global_load_lds_dwordx4 v128, s[44:45]
	s_mov_b32 m0, s56
	s_nop 0
	global_load_lds_dwordx4 v132, s[44:45]
	s_barrier
	s_waitcnt lgkmcnt(6)
	v_mfma_f32_16x16x32_bf16 v[60:63], v[152:155], v[168:171], 0
	v_mfma_f32_16x16x32_bf16 v[60:63], v[156:159], v[172:175], v[60:63]
	v_mfma_f32_16x16x32_bf16 v[56:59], v[164:167], v[172:175], 0
	v_mfma_f32_16x16x32_bf16 v[56:59], v[160:163], v[168:171], v[56:59]
	s_waitcnt lgkmcnt(4)
	v_mfma_f32_16x16x32_bf16 v[40:43], v[160:163], v[176:179], 0
	v_mfma_f32_16x16x32_bf16 v[40:43], v[164:167], v[180:183], v[40:43]
	v_mfma_f32_16x16x32_bf16 v[44:47], v[156:159], v[180:183], 0
	v_mfma_f32_16x16x32_bf16 v[44:47], v[152:155], v[176:179], v[44:47]
	s_waitcnt lgkmcnt(2)
	v_mfma_f32_16x16x32_bf16 v[28:31], v[152:155], v[184:187], 0
	v_mfma_f32_16x16x32_bf16 v[28:31], v[156:159], v[188:191], v[28:31]
	v_mfma_f32_16x16x32_bf16 v[24:27], v[164:167], v[188:191], 0
	v_mfma_f32_16x16x32_bf16 v[24:27], v[160:163], v[184:187], v[24:27]
	s_waitcnt lgkmcnt(0)
	v_mfma_f32_16x16x32_bf16 v[8:11], v[160:163], v[192:195], 0
	v_mfma_f32_16x16x32_bf16 v[8:11], v[164:167], v[196:199], v[8:11]
	v_mfma_f32_16x16x32_bf16 v[12:15], v[156:159], v[196:199], 0
	v_mfma_f32_16x16x32_bf16 v[12:15], v[152:155], v[192:195], v[12:15]
	s_barrier
	s_add_u32 s72, s42, 0x40000
	s_addc_u32 s73, s43, 0
	s_add_i32 s71, s64, s51
	s_mov_b32 m0, s71
	s_nop 0
	global_load_lds_dwordx4 v130, s[72:73]
	s_add_i32 m0, s71, 0x2000
	s_nop 0
	global_load_lds_dwordx4 v134, s[72:73]
	s_waitcnt vmcnt(6)
	s_barrier
; #define PG8_STAGE(bufoff, gbase, voff) do { _Pragma("unroll") for (int _i = 0; _i < 2; ++_i) \
;         __builtin_amdgcn_global_load_lds((const unsigned*)((const char*)(gbase) + (voff)[_i]), (LAS unsigned*)(lds + (bufoff) + ldsw + _i * 8192), 16, 0, 0); } while (0)
; #define PG8_LDA(dst, b, h) do { _Pragma("unroll") for (int m = 0; m < 4; ++m) _Pragma("unroll") for (int k = 0; k < 2; ++k) dst[m][k] = *(const LAS bf16x8*)(lds + PG8_SA(b, h) + aoff + m * 2048 + k * 1024); } while (0)
; #define PG8_LDB(dst, b, h) do { _Pragma("unroll") for (int n = 0; n < 2; ++n) _Pragma("unroll") for (int k = 0; k < 2; ++k) dst[n][k] = *(const LAS bf16x8*)(lds + PG8_SB(b, h) + boff + n * 2048 + k * 1024); } while (0)
; #define PG8_WAIT_V(n) asm volatile("s_waitcnt vmcnt(" #n ")" ::: "memory")
; #define PG8_WAIT_L(n) asm volatile("s_waitcnt lgkmcnt(" #n ")" ::: "memory")
; #define PG8_BAR __builtin_amdgcn_s_barrier()
; #define PG8_SCHED __builtin_amdgcn_sched_barrier(0)
; template <class Epi, class Ptrs>
; __device__ __forceinline__ void gemm_phase(LAS unsigned char* lds, const int K, const StaticOrder& S, const Ptrs& P, const Epi& E) {
;     ...
;             PG8_LDB(B0, 0, 0); PG8_SCHED; PG8_LDA(At, 0, 0); PG8_STAGE(PG8_SA(1, 1), a1 + hstep, voffA);
;             PG8_WAIT_L(8); PG8_BAR; PG8_WAIT_L(0); PG8_MMA(0, 0, At, B0); PG8_BAR; PG8_SCHED;
;             PG8_LDB(B1, 0, 1); PG8_STAGE(PG8_SB(0, 0), b2, voffB);
;             PG8_BAR; PG8_WAIT_L(0); PG8_MMA(0, 1, At, B1); PG8_BAR;
;             PG8_LDA(At, 0, 1); PG8_STAGE(PG8_SA(0, 0), a2, voffA);
;             PG8_BAR; PG8_WAIT_L(0); PG8_MMA(1, 0, At, B0); PG8_BAR; PG8_SCHED;
;             PG8_STAGE(PG8_SB(0, 1), b2 + hstep, voffB);
;             PG8_WAIT_V(6); PG8_BAR; PG8_MMA(1, 1, At, B1); PG8_BAR;
;             PG8_LDB(B0, 1, 0); PG8_SCHED; PG8_LDA(At, 1, 0); PG8_STAGE(PG8_SA(0, 1), a2 + hstep, voffA);
;             PG8_WAIT_L(8); PG8_BAR; PG8_WAIT_L(0); PG8_MMA(0, 0, At, B0); PG8_BAR; PG8_SCHED;
;             PG8_LDB(B1, 1, 1); PG8_STAGE(PG8_SB(1, 0), b3, voffB);
;             PG8_BAR; PG8_WAIT_L(0); PG8_MMA(0, 1, At, B1); PG8_BAR;
;             PG8_LDA(At, 1, 1); PG8_STAGE(PG8_SA(1, 0), a3, voffA);
;             PG8_BAR; PG8_WAIT_L(0); PG8_MMA(1, 0, At, B0); PG8_BAR; PG8_SCHED;
;             PG8_STAGE(PG8_SB(1, 1), b3 + hstep, voffB);
;             PG8_WAIT_V(6); PG8_BAR; PG8_MMA(1, 1, At, B1); PG8_BAR;
	v_mfma_f32_16x16x32_bf16 v[52:55], v[200:203], v[168:171], 0
	v_mfma_f32_16x16x32_bf16 v[52:55], v[204:207], v[172:175], v[52:55]
	v_mfma_f32_16x16x32_bf16 v[48:51], v[214:217], v[172:175], 0
	v_mfma_f32_16x16x32_bf16 v[48:51], v[210:213], v[168:171], v[48:51]
	v_mfma_f32_16x16x32_bf16 v[32:35], v[210:213], v[176:179], 0
	v_mfma_f32_16x16x32_bf16 v[32:35], v[214:217], v[180:183], v[32:35]
	v_mfma_f32_16x16x32_bf16 v[36:39], v[204:207], v[180:183], 0
	v_mfma_f32_16x16x32_bf16 v[36:39], v[200:203], v[176:179], v[36:39]
	v_mfma_f32_16x16x32_bf16 v[20:23], v[200:203], v[184:187], 0
	v_mfma_f32_16x16x32_bf16 v[20:23], v[204:207], v[188:191], v[20:23]
	v_mfma_f32_16x16x32_bf16 v[16:19], v[214:217], v[188:191], 0
	v_mfma_f32_16x16x32_bf16 v[16:19], v[210:213], v[184:187], v[16:19]
	v_mfma_f32_16x16x32_bf16 v[0:3], v[210:213], v[192:195], 0
	v_mfma_f32_16x16x32_bf16 v[0:3], v[214:217], v[196:199], v[0:3]
	v_mfma_f32_16x16x32_bf16 v[4:7], v[204:207], v[196:199], 0
	v_mfma_f32_16x16x32_bf16 v[4:7], v[200:203], v[192:195], v[4:7]
	s_barrier
	s_add_i32 s71, 0, 0x18000
	ds_read_b128 v[152:155], v252
	ds_read_b128 v[156:159], v252 offset:1024
	ds_read_b128 v[160:163], v252 offset:2048
	ds_read_b128 v[164:167], v252 offset:3072
	s_add_u32 s44, s44, 0x40000
	s_addc_u32 s45, s45, 0
	s_mov_b32 m0, s57
	ds_read_b128 v[168:171], v150 offset:32768
	ds_read_b128 v[172:175], v150 offset:33792
	ds_read_b128 v[176:179], v150 offset:34816
	ds_read_b128 v[180:183], v150 offset:35840
	ds_read_b128 v[184:187], v150 offset:36864
	ds_read_b128 v[188:191], v150 offset:37888
	ds_read_b128 v[192:195], v150 offset:38912
	ds_read_b128 v[196:199], v150 offset:39936
	global_load_lds_dwordx4 v128, s[44:45]
	s_mov_b32 m0, s58
	s_nop 0
	global_load_lds_dwordx4 v132, s[44:45]
	s_waitcnt lgkmcnt(8)
	s_barrier
	s_waitcnt lgkmcnt(6)
	v_mfma_f32_16x16x32_bf16 v[124:127], v[152:155], v[168:171], v[124:127]
	v_mfma_f32_16x16x32_bf16 v[124:127], v[156:159], v[172:175], v[124:127]
	v_mfma_f32_16x16x32_bf16 v[120:123], v[164:167], v[172:175], v[120:123]
	v_mfma_f32_16x16x32_bf16 v[120:123], v[160:163], v[168:171], v[120:123]
	s_waitcnt lgkmcnt(4)
	v_mfma_f32_16x16x32_bf16 v[104:107], v[160:163], v[176:179], v[104:107]
	v_mfma_f32_16x16x32_bf16 v[104:107], v[164:167], v[180:183], v[104:107]
	v_mfma_f32_16x16x32_bf16 v[108:111], v[156:159], v[180:183], v[108:111]
	v_mfma_f32_16x16x32_bf16 v[108:111], v[152:155], v[176:179], v[108:111]
	s_waitcnt lgkmcnt(2)
	v_mfma_f32_16x16x32_bf16 v[92:95], v[152:155], v[184:187], v[92:95]
	v_mfma_f32_16x16x32_bf16 v[92:95], v[156:159], v[188:191], v[92:95]
	v_mfma_f32_16x16x32_bf16 v[88:91], v[164:167], v[188:191], v[88:91]
	v_mfma_f32_16x16x32_bf16 v[88:91], v[160:163], v[184:187], v[88:91]
	s_waitcnt lgkmcnt(0)
	v_mfma_f32_16x16x32_bf16 v[72:75], v[160:163], v[192:195], v[72:75]
	v_mfma_f32_16x16x32_bf16 v[72:75], v[164:167], v[196:199], v[72:75]
	v_mfma_f32_16x16x32_bf16 v[76:79], v[156:159], v[196:199], v[76:79]
	v_mfma_f32_16x16x32_bf16 v[76:79], v[152:155], v[192:195], v[76:79]
	s_barrier
	s_add_i32 s44, 0, 0x1c000
	s_add_i32 s45, s71, s51
	s_mov_b32 m0, s45
	ds_read_b128 v[200:203], v253
	ds_read_b128 v[204:207], v253 offset:1024
	ds_read_b128 v[210:213], v253 offset:2048
	ds_read_b128 v[214:217], v253 offset:3072
	global_load_lds_dwordx4 v130, s[76:77]
	s_add_i32 m0, s45, 0x2000
	s_nop 0
	global_load_lds_dwordx4 v134, s[76:77]
	s_barrier
	s_waitcnt lgkmcnt(0)
	v_mfma_f32_16x16x32_bf16 v[116:119], v[200:203], v[168:171], v[116:119]
	v_mfma_f32_16x16x32_bf16 v[116:119], v[204:207], v[172:175], v[116:119]
	v_mfma_f32_16x16x32_bf16 v[112:115], v[214:217], v[172:175], v[112:115]
	v_mfma_f32_16x16x32_bf16 v[112:115], v[210:213], v[168:171], v[112:115]
	v_mfma_f32_16x16x32_bf16 v[96:99], v[210:213], v[176:179], v[96:99]
	v_mfma_f32_16x16x32_bf16 v[96:99], v[214:217], v[180:183], v[96:99]
	v_mfma_f32_16x16x32_bf16 v[100:103], v[204:207], v[180:183], v[100:103]
	v_mfma_f32_16x16x32_bf16 v[100:103], v[200:203], v[176:179], v[100:103]
	v_mfma_f32_16x16x32_bf16 v[84:87], v[200:203], v[184:187], v[84:87]
	v_mfma_f32_16x16x32_bf16 v[84:87], v[204:207], v[188:191], v[84:87]
	v_mfma_f32_16x16x32_bf16 v[80:83], v[214:217], v[188:191], v[80:83]
	v_mfma_f32_16x16x32_bf16 v[80:83], v[210:213], v[184:187], v[80:83]
	v_mfma_f32_16x16x32_bf16 v[64:67], v[210:213], v[192:195], v[64:67]
	v_mfma_f32_16x16x32_bf16 v[64:67], v[214:217], v[196:199], v[64:67]
	v_mfma_f32_16x16x32_bf16 v[68:71], v[204:207], v[196:199], v[68:71]
	v_mfma_f32_16x16x32_bf16 v[68:71], v[200:203], v[192:195], v[68:71]
	s_barrier
	s_mov_b32 m0, s61
	ds_read_b128 v[168:171], v150 offset:49152
	ds_read_b128 v[172:175], v150 offset:50176
	ds_read_b128 v[176:179], v150 offset:51200
	ds_read_b128 v[180:183], v150 offset:52224
	ds_read_b128 v[184:187], v150 offset:53248
	ds_read_b128 v[188:191], v150 offset:54272
	ds_read_b128 v[192:195], v150 offset:55296
	ds_read_b128 v[196:199], v150 offset:56320
	global_load_lds_dwordx4 v128, s[78:79]
	s_mov_b32 m0, s62
	s_nop 0
	global_load_lds_dwordx4 v132, s[78:79]
	s_barrier
; #define PG8_STAGE(bufoff, gbase, voff) do { _Pragma("unroll") for (int _i = 0; _i < 2; ++_i) \
;         __builtin_amdgcn_global_load_lds((const unsigned*)((const char*)(gbase) + (voff)[_i]), (LAS unsigned*)(lds + (bufoff) + ldsw + _i * 8192), 16, 0, 0); } while (0)
; #define PG8_LDA(dst, b, h) do { _Pragma("unroll") for (int m = 0; m < 4; ++m) _Pragma("unroll") for (int k = 0; k < 2; ++k) dst[m][k] = *(const LAS bf16x8*)(lds + PG8_SA(b, h) + aoff + m * 2048 + k * 1024); } while (0)
; #define PG8_WAIT_V(n) asm volatile("s_waitcnt vmcnt(" #n ")" ::: "memory")
; #define PG8_BAR __builtin_amdgcn_s_barrier()
; template <class Epi, class Ptrs>
; __device__ __forceinline__ void gemm_phase(LAS unsigned char* lds, const int K, const StaticOrder& S, const Ptrs& P, const Epi& E) {
;     ...
;         for (int t = 0; t < nt; t += 2) {
;             const bool last = (t == nt - 2);
;             const char* a1 = cA + (size_t)(t + 1) * kstep;
;             const char* a2 = last ? nA : cA + (size_t)(t + 2) * kstep; const char* b2 = last ? nB : cB + (size_t)(t + 2) * kstep;
;             const char* a3 = a2 + kstep; const char* b3 = b2 + kstep;
;             PG8_LDB(B0, 0, 0); PG8_SCHED; PG8_LDA(At, 0, 0); PG8_STAGE(PG8_SA(1, 1), a1 + hstep, voffA);
;             PG8_WAIT_L(8); PG8_BAR; PG8_WAIT_L(0); PG8_MMA(0, 0, At, B0); PG8_BAR; PG8_SCHED;
;             PG8_LDB(B1, 0, 1); PG8_STAGE(PG8_SB(0, 0), b2, voffB);
;             PG8_BAR; PG8_WAIT_L(0); PG8_MMA(0, 1, At, B1); PG8_BAR;
;             PG8_LDA(At, 0, 1); PG8_STAGE(PG8_SA(0, 0), a2, voffA);
;             PG8_BAR; PG8_WAIT_L(0); PG8_MMA(1, 0, At, B0); PG8_BAR; PG8_SCHED;
;             PG8_STAGE(PG8_SB(0, 1), b2 + hstep, voffB);
;             PG8_WAIT_V(6); PG8_BAR; PG8_MMA(1, 1, At, B1); PG8_BAR;
;             PG8_LDB(B0, 1, 0); PG8_SCHED; PG8_LDA(At, 1, 0); PG8_STAGE(PG8_SA(0, 1), a2 + hstep, voffA);
;             PG8_WAIT_L(8); PG8_BAR; PG8_WAIT_L(0); PG8_MMA(0, 0, At, B0); PG8_BAR; PG8_SCHED;
;             PG8_LDB(B1, 1, 1); PG8_STAGE(PG8_SB(1, 0), b3, voffB);
;             PG8_BAR; PG8_WAIT_L(0); PG8_MMA(0, 1, At, B1); PG8_BAR;
;             PG8_LDA(At, 1, 1); PG8_STAGE(PG8_SA(1, 0), a3, voffA);
;             PG8_BAR; PG8_WAIT_L(0); PG8_MMA(1, 0, At, B0); PG8_BAR; PG8_SCHED;
;             PG8_STAGE(PG8_SB(1, 1), b3 + hstep, voffB);
;             PG8_WAIT_V(6); PG8_BAR; PG8_MMA(1, 1, At, B1); PG8_BAR;
	s_waitcnt lgkmcnt(6)
	v_mfma_f32_16x16x32_bf16 v[60:63], v[152:155], v[168:171], v[60:63]
	v_mfma_f32_16x16x32_bf16 v[60:63], v[156:159], v[172:175], v[60:63]
	v_mfma_f32_16x16x32_bf16 v[56:59], v[164:167], v[172:175], v[56:59]
	v_mfma_f32_16x16x32_bf16 v[56:59], v[160:163], v[168:171], v[56:59]
	s_waitcnt lgkmcnt(4)
	v_mfma_f32_16x16x32_bf16 v[40:43], v[160:163], v[176:179], v[40:43]
	v_mfma_f32_16x16x32_bf16 v[40:43], v[164:167], v[180:183], v[40:43]
	v_mfma_f32_16x16x32_bf16 v[44:47], v[156:159], v[180:183], v[44:47]
	v_mfma_f32_16x16x32_bf16 v[44:47], v[152:155], v[176:179], v[44:47]
	s_waitcnt lgkmcnt(2)
	v_mfma_f32_16x16x32_bf16 v[28:31], v[152:155], v[184:187], v[28:31]
	v_mfma_f32_16x16x32_bf16 v[28:31], v[156:159], v[188:191], v[28:31]
	v_mfma_f32_16x16x32_bf16 v[24:27], v[164:167], v[188:191], v[24:27]
	v_mfma_f32_16x16x32_bf16 v[24:27], v[160:163], v[184:187], v[24:27]
	s_waitcnt lgkmcnt(0)
	v_mfma_f32_16x16x32_bf16 v[8:11], v[160:163], v[192:195], v[8:11]
	v_mfma_f32_16x16x32_bf16 v[8:11], v[164:167], v[196:199], v[8:11]
	v_mfma_f32_16x16x32_bf16 v[12:15], v[156:159], v[196:199], v[12:15]
	v_mfma_f32_16x16x32_bf16 v[12:15], v[152:155], v[192:195], v[12:15]
	s_barrier
	s_add_u32 s42, s42, 0x40080
	s_addc_u32 s43, s43, 0
	s_add_i32 s44, s44, s51
	s_mov_b32 m0, s44
	s_nop 0
	global_load_lds_dwordx4 v130, s[42:43]
	s_add_i32 m0, s44, 0x2000
	s_nop 0
	global_load_lds_dwordx4 v134, s[42:43]
	s_waitcnt vmcnt(6)
	s_barrier
	v_mfma_f32_16x16x32_bf16 v[52:55], v[200:203], v[168:171], v[52:55]
	v_mfma_f32_16x16x32_bf16 v[52:55], v[204:207], v[172:175], v[52:55]
	v_mfma_f32_16x16x32_bf16 v[48:51], v[214:217], v[172:175], v[48:51]
	v_mfma_f32_16x16x32_bf16 v[48:51], v[210:213], v[168:171], v[48:51]
	v_mfma_f32_16x16x32_bf16 v[32:35], v[210:213], v[176:179], v[32:35]
	v_mfma_f32_16x16x32_bf16 v[32:35], v[214:217], v[180:183], v[32:35]
	v_mfma_f32_16x16x32_bf16 v[36:39], v[204:207], v[180:183], v[36:39]
	v_mfma_f32_16x16x32_bf16 v[36:39], v[200:203], v[176:179], v[36:39]
	v_mfma_f32_16x16x32_bf16 v[20:23], v[200:203], v[184:187], v[20:23]
	v_mfma_f32_16x16x32_bf16 v[20:23], v[204:207], v[188:191], v[20:23]
	v_mfma_f32_16x16x32_bf16 v[16:19], v[214:217], v[188:191], v[16:19]
	v_mfma_f32_16x16x32_bf16 v[16:19], v[210:213], v[184:187], v[16:19]
	v_mfma_f32_16x16x32_bf16 v[0:3], v[210:213], v[192:195], v[0:3]
	v_mfma_f32_16x16x32_bf16 v[0:3], v[214:217], v[196:199], v[0:3]
	v_mfma_f32_16x16x32_bf16 v[4:7], v[204:207], v[196:199], v[4:7]
	v_mfma_f32_16x16x32_bf16 v[4:7], v[200:203], v[192:195], v[4:7]
	s_barrier
	s_add_i32 s70, s70, 2
	s_add_u32 s40, s40, 0x100
	s_addc_u32 s41, s41, 0
	s_add_u32 s23, s23, 0x100
	s_addc_u32 s25, s25, 0
	s_cmp_gt_u32 s70, 13
.LBB0_433:
	ds_read_b128 v[152:155], v149
	ds_read_b128 v[156:159], v149 offset:1024
	ds_read_b128 v[160:163], v149 offset:2048
	ds_read_b128 v[164:167], v149 offset:3072
	s_add_u32 s42, s40, 0xfffc0080
	s_addc_u32 s43, s41, -1
	s_cmp_eq_u32 s70, 12
	s_cselect_b32 s45, s1, s43
	s_cselect_b32 s44, s0, s42
	s_cselect_b32 s43, s37, s25
	s_cselect_b32 s42, s36, s23
	s_add_i32 m0, s39, 0xc000
	ds_read_b128 v[168:171], v150
	ds_read_b128 v[172:175], v150 offset:1024
	ds_read_b128 v[176:179], v150 offset:2048
	ds_read_b128 v[180:183], v150 offset:3072
	ds_read_b128 v[184:187], v150 offset:4096
	ds_read_b128 v[188:191], v150 offset:5120
	ds_read_b128 v[192:195], v150 offset:6144
	ds_read_b128 v[196:199], v150 offset:7168
	global_load_lds_dwordx4 v136, s[40:41]
	s_add_i32 m0, s39, 0xe000
	s_nop 0
	global_load_lds_dwordx4 v138, s[40:41]
	s_waitcnt lgkmcnt(8)
	s_barrier
	s_waitcnt lgkmcnt(6)
	v_mfma_f32_16x16x32_bf16 v[124:127], v[152:155], v[168:171], v[124:127]
	v_mfma_f32_16x16x32_bf16 v[124:127], v[156:159], v[172:175], v[124:127]
	v_mfma_f32_16x16x32_bf16 v[120:123], v[164:167], v[172:175], v[120:123]
	v_mfma_f32_16x16x32_bf16 v[120:123], v[160:163], v[168:171], v[120:123]
	s_waitcnt lgkmcnt(4)
	v_mfma_f32_16x16x32_bf16 v[104:107], v[160:163], v[176:179], v[104:107]
	v_mfma_f32_16x16x32_bf16 v[104:107], v[164:167], v[180:183], v[104:107]
	v_mfma_f32_16x16x32_bf16 v[108:111], v[156:159], v[180:183], v[108:111]
	v_mfma_f32_16x16x32_bf16 v[108:111], v[152:155], v[176:179], v[108:111]
	s_waitcnt lgkmcnt(2)
	v_mfma_f32_16x16x32_bf16 v[92:95], v[152:155], v[184:187], v[92:95]
	v_mfma_f32_16x16x32_bf16 v[92:95], v[156:159], v[188:191], v[92:95]
	v_mfma_f32_16x16x32_bf16 v[88:91], v[164:167], v[188:191], v[88:91]
	v_mfma_f32_16x16x32_bf16 v[88:91], v[160:163], v[184:187], v[88:91]
	s_waitcnt lgkmcnt(0)
	v_mfma_f32_16x16x32_bf16 v[72:75], v[160:163], v[192:195], v[72:75]
	v_mfma_f32_16x16x32_bf16 v[72:75], v[164:167], v[196:199], v[72:75]
	v_mfma_f32_16x16x32_bf16 v[76:79], v[156:159], v[196:199], v[76:79]
	v_mfma_f32_16x16x32_bf16 v[76:79], v[152:155], v[192:195], v[76:79]
	s_barrier
	s_add_i32 s71, s63, s51
	s_add_u32 s76, s42, 0x80
	s_addc_u32 s77, s43, 0
	s_mov_b32 m0, s71
	ds_read_b128 v[200:203], v151
	ds_read_b128 v[204:207], v151 offset:1024
	ds_read_b128 v[210:213], v151 offset:2048
	ds_read_b128 v[214:217], v151 offset:3072
	global_load_lds_dwordx4 v130, s[42:43]
	s_add_i32 m0, s71, 0x2000
	s_nop 0
	global_load_lds_dwordx4 v134, s[42:43]
	s_barrier
; #define PG8_STAGE(bufoff, gbase, voff) do { _Pragma("unroll") for (int _i = 0; _i < 2; ++_i) \
;         __builtin_amdgcn_global_load_lds((const unsigned*)((const char*)(gbase) + (voff)[_i]), (LAS unsigned*)(lds + (bufoff) + ldsw + _i * 8192), 16, 0, 0); } while (0)
; #define PG8_LDA(dst, b, h) do { _Pragma("unroll") for (int m = 0; m < 4; ++m) _Pragma("unroll") for (int k = 0; k < 2; ++k) dst[m][k] = *(const LAS bf16x8*)(lds + PG8_SA(b, h) + aoff + m * 2048 + k * 1024); } while (0)
; #define PG8_WAIT_V(n) asm volatile("s_waitcnt vmcnt(" #n ")" ::: "memory")
; #define PG8_BAR __builtin_amdgcn_s_barrier()
; template <class Epi, class Ptrs>
; __device__ __forceinline__ void gemm_phase(LAS unsigned char* lds, const int K, const StaticOrder& S, const Ptrs& P, const Epi& E) {
;     ...
;         for (int t = 0; t < nt; t += 2) {
;             const bool last = (t == nt - 2);
;             const char* a1 = cA + (size_t)(t + 1) * kstep;
;             const char* a2 = last ? nA : cA + (size_t)(t + 2) * kstep; const char* b2 = last ? nB : cB + (size_t)(t + 2) * kstep;
;             const char* a3 = a2 + kstep; const char* b3 = b2 + kstep;
;             PG8_LDB(B0, 0, 0); PG8_SCHED; PG8_LDA(At, 0, 0); PG8_STAGE(PG8_SA(1, 1), a1 + hstep, voffA);
;             PG8_WAIT_L(8); PG8_BAR; PG8_WAIT_L(0); PG8_MMA(0, 0, At, B0); PG8_BAR; PG8_SCHED;
;             PG8_LDB(B1, 0, 1); PG8_STAGE(PG8_SB(0, 0), b2, voffB);
;             PG8_BAR; PG8_WAIT_L(0); PG8_MMA(0, 1, At, B1); PG8_BAR;
;             PG8_LDA(At, 0, 1); PG8_STAGE(PG8_SA(0, 0), a2, voffA);
;             PG8_BAR; PG8_WAIT_L(0); PG8_MMA(1, 0, At, B0); PG8_BAR; PG8_SCHED;
;             PG8_STAGE(PG8_SB(0, 1), b2 + hstep, voffB);
;             PG8_WAIT_V(6); PG8_BAR; PG8_MMA(1, 1, At, B1); PG8_BAR;
;             PG8_LDB(B0, 1, 0); PG8_SCHED; PG8_LDA(At, 1, 0); PG8_STAGE(PG8_SA(0, 1), a2 + hstep, voffA);
;             PG8_WAIT_L(8); PG8_BAR; PG8_WAIT_L(0); PG8_MMA(0, 0, At, B0); PG8_BAR; PG8_SCHED;
;             PG8_LDB(B1, 1, 1); PG8_STAGE(PG8_SB(1, 0), b3, voffB);
;             PG8_BAR; PG8_WAIT_L(0); PG8_MMA(0, 1, At, B1); PG8_BAR;
;             PG8_LDA(At, 1, 1); PG8_STAGE(PG8_SA(1, 0), a3, voffA);
;             PG8_BAR; PG8_WAIT_L(0); PG8_MMA(1, 0, At, B0); PG8_BAR; PG8_SCHED;
;             PG8_STAGE(PG8_SB(1, 1), b3 + hstep, voffB);
;             PG8_WAIT_V(6); PG8_BAR; PG8_MMA(1, 1, At, B1); PG8_BAR;
	s_waitcnt lgkmcnt(0)
	v_mfma_f32_16x16x32_bf16 v[116:119], v[200:203], v[168:171], v[116:119]
	v_mfma_f32_16x16x32_bf16 v[116:119], v[204:207], v[172:175], v[116:119]
	v_mfma_f32_16x16x32_bf16 v[112:115], v[214:217], v[172:175], v[112:115]
	v_mfma_f32_16x16x32_bf16 v[112:115], v[210:213], v[168:171], v[112:115]
	v_mfma_f32_16x16x32_bf16 v[96:99], v[210:213], v[176:179], v[96:99]
	v_mfma_f32_16x16x32_bf16 v[96:99], v[214:217], v[180:183], v[96:99]
	v_mfma_f32_16x16x32_bf16 v[100:103], v[204:207], v[180:183], v[100:103]
	v_mfma_f32_16x16x32_bf16 v[100:103], v[200:203], v[176:179], v[100:103]
	v_mfma_f32_16x16x32_bf16 v[84:87], v[200:203], v[184:187], v[84:87]
	v_mfma_f32_16x16x32_bf16 v[84:87], v[204:207], v[188:191], v[84:87]
	v_mfma_f32_16x16x32_bf16 v[80:83], v[214:217], v[188:191], v[80:83]
	v_mfma_f32_16x16x32_bf16 v[80:83], v[210:213], v[184:187], v[80:83]
	v_mfma_f32_16x16x32_bf16 v[64:67], v[210:213], v[192:195], v[64:67]
	v_mfma_f32_16x16x32_bf16 v[64:67], v[214:217], v[196:199], v[64:67]
	v_mfma_f32_16x16x32_bf16 v[68:71], v[204:207], v[196:199], v[68:71]
	v_mfma_f32_16x16x32_bf16 v[68:71], v[200:203], v[192:195], v[68:71]
	s_barrier
	s_mov_b32 m0, s39
	s_add_u32 s78, s44, 0x80
	s_addc_u32 s79, s45, 0
	ds_read_b128 v[168:171], v150 offset:16384
	ds_read_b128 v[172:175], v150 offset:17408
	ds_read_b128 v[176:179], v150 offset:18432
	ds_read_b128 v[180:183], v150 offset:19456
	ds_read_b128 v[184:187], v150 offset:20480
	ds_read_b128 v[188:191], v150 offset:21504
	ds_read_b128 v[192:195], v150 offset:22528
	ds_read_b128 v[196:199], v150 offset:23552
	global_load_lds_dwordx4 v128, s[44:45]
	s_mov_b32 m0, s56
	s_nop 0
	global_load_lds_dwordx4 v132, s[44:45]
	s_barrier
	s_waitcnt lgkmcnt(6)
	v_mfma_f32_16x16x32_bf16 v[60:63], v[152:155], v[168:171], v[60:63]
	v_mfma_f32_16x16x32_bf16 v[60:63], v[156:159], v[172:175], v[60:63]
	v_mfma_f32_16x16x32_bf16 v[56:59], v[164:167], v[172:175], v[56:59]
	v_mfma_f32_16x16x32_bf16 v[56:59], v[160:163], v[168:171], v[56:59]
	s_waitcnt lgkmcnt(4)
	v_mfma_f32_16x16x32_bf16 v[40:43], v[160:163], v[176:179], v[40:43]
	v_mfma_f32_16x16x32_bf16 v[40:43], v[164:167], v[180:183], v[40:43]
	v_mfma_f32_16x16x32_bf16 v[44:47], v[156:159], v[180:183], v[44:47]
	v_mfma_f32_16x16x32_bf16 v[44:47], v[152:155], v[176:179], v[44:47]
	s_waitcnt lgkmcnt(2)
	v_mfma_f32_16x16x32_bf16 v[28:31], v[152:155], v[184:187], v[28:31]
	v_mfma_f32_16x16x32_bf16 v[28:31], v[156:159], v[188:191], v[28:31]
	v_mfma_f32_16x16x32_bf16 v[24:27], v[164:167], v[188:191], v[24:27]
	v_mfma_f32_16x16x32_bf16 v[24:27], v[160:163], v[184:187], v[24:27]
	s_waitcnt lgkmcnt(0)
	v_mfma_f32_16x16x32_bf16 v[8:11], v[160:163], v[192:195], v[8:11]
	v_mfma_f32_16x16x32_bf16 v[8:11], v[164:167], v[196:199], v[8:11]
	v_mfma_f32_16x16x32_bf16 v[12:15], v[156:159], v[196:199], v[12:15]
	v_mfma_f32_16x16x32_bf16 v[12:15], v[152:155], v[192:195], v[12:15]
	s_barrier
	s_add_u32 s72, s42, 0x40000
	s_addc_u32 s73, s43, 0
	s_add_i32 s71, s64, s51
	s_mov_b32 m0, s71
	s_nop 0
	global_load_lds_dwordx4 v130, s[72:73]
	s_add_i32 m0, s71, 0x2000
	s_nop 0
	global_load_lds_dwordx4 v134, s[72:73]
	s_waitcnt vmcnt(6)
	s_barrier
	v_mfma_f32_16x16x32_bf16 v[52:55], v[200:203], v[168:171], v[52:55]
	v_mfma_f32_16x16x32_bf16 v[52:55], v[204:207], v[172:175], v[52:55]
	v_mfma_f32_16x16x32_bf16 v[48:51], v[214:217], v[172:175], v[48:51]
	v_mfma_f32_16x16x32_bf16 v[48:51], v[210:213], v[168:171], v[48:51]
	v_mfma_f32_16x16x32_bf16 v[32:35], v[210:213], v[176:179], v[32:35]
	v_mfma_f32_16x16x32_bf16 v[32:35], v[214:217], v[180:183], v[32:35]
	v_mfma_f32_16x16x32_bf16 v[36:39], v[204:207], v[180:183], v[36:39]
	v_mfma_f32_16x16x32_bf16 v[36:39], v[200:203], v[176:179], v[36:39]
	v_mfma_f32_16x16x32_bf16 v[20:23], v[200:203], v[184:187], v[20:23]
	v_mfma_f32_16x16x32_bf16 v[20:23], v[204:207], v[188:191], v[20:23]
	v_mfma_f32_16x16x32_bf16 v[16:19], v[214:217], v[188:191], v[16:19]
	v_mfma_f32_16x16x32_bf16 v[16:19], v[210:213], v[184:187], v[16:19]
	v_mfma_f32_16x16x32_bf16 v[0:3], v[210:213], v[192:195], v[0:3]
	v_mfma_f32_16x16x32_bf16 v[0:3], v[214:217], v[196:199], v[0:3]
	v_mfma_f32_16x16x32_bf16 v[4:7], v[204:207], v[196:199], v[4:7]
	v_mfma_f32_16x16x32_bf16 v[4:7], v[200:203], v[192:195], v[4:7]
	s_barrier
	s_add_i32 s71, 0, 0x18000
	ds_read_b128 v[152:155], v252
	ds_read_b128 v[156:159], v252 offset:1024
	ds_read_b128 v[160:163], v252 offset:2048
	ds_read_b128 v[164:167], v252 offset:3072
	s_add_u32 s44, s44, 0x40000
	s_addc_u32 s45, s45, 0
	s_mov_b32 m0, s57
	ds_read_b128 v[168:171], v150 offset:32768
	ds_read_b128 v[172:175], v150 offset:33792
	ds_read_b128 v[176:179], v150 offset:34816
	ds_read_b128 v[180:183], v150 offset:35840
	ds_read_b128 v[184:187], v150 offset:36864
	ds_read_b128 v[188:191], v150 offset:37888
	ds_read_b128 v[192:195], v150 offset:38912
	ds_read_b128 v[196:199], v150 offset:39936
	global_load_lds_dwordx4 v128, s[44:45]
	s_mov_b32 m0, s58
	s_nop 0
	global_load_lds_dwordx4 v132, s[44:45]
	s_waitcnt lgkmcnt(8)
	s_barrier
	s_waitcnt lgkmcnt(6)
	v_mfma_f32_16x16x32_bf16 v[124:127], v[152:155], v[168:171], v[124:127]
	v_mfma_f32_16x16x32_bf16 v[124:127], v[156:159], v[172:175], v[124:127]
	v_mfma_f32_16x16x32_bf16 v[120:123], v[164:167], v[172:175], v[120:123]
	v_mfma_f32_16x16x32_bf16 v[120:123], v[160:163], v[168:171], v[120:123]
	s_waitcnt lgkmcnt(4)
	v_mfma_f32_16x16x32_bf16 v[104:107], v[160:163], v[176:179], v[104:107]
	v_mfma_f32_16x16x32_bf16 v[104:107], v[164:167], v[180:183], v[104:107]
	v_mfma_f32_16x16x32_bf16 v[108:111], v[156:159], v[180:183], v[108:111]
	v_mfma_f32_16x16x32_bf16 v[108:111], v[152:155], v[176:179], v[108:111]
	s_waitcnt lgkmcnt(2)
	v_mfma_f32_16x16x32_bf16 v[92:95], v[152:155], v[184:187], v[92:95]
	v_mfma_f32_16x16x32_bf16 v[92:95], v[156:159], v[188:191], v[92:95]
	v_mfma_f32_16x16x32_bf16 v[88:91], v[164:167], v[188:191], v[88:91]
	v_mfma_f32_16x16x32_bf16 v[88:91], v[160:163], v[184:187], v[88:91]
	s_waitcnt lgkmcnt(0)
	v_mfma_f32_16x16x32_bf16 v[72:75], v[160:163], v[192:195], v[72:75]
	v_mfma_f32_16x16x32_bf16 v[72:75], v[164:167], v[196:199], v[72:75]
	v_mfma_f32_16x16x32_bf16 v[76:79], v[156:159], v[196:199], v[76:79]
	v_mfma_f32_16x16x32_bf16 v[76:79], v[152:155], v[192:195], v[76:79]
	s_barrier
; #define PG8_STAGE(bufoff, gbase, voff) do { _Pragma("unroll") for (int _i = 0; _i < 2; ++_i) \
;         __builtin_amdgcn_global_load_lds((const unsigned*)((const char*)(gbase) + (voff)[_i]), (LAS unsigned*)(lds + (bufoff) + ldsw + _i * 8192), 16, 0, 0); } while (0)
; #define PG8_LDA(dst, b, h) do { _Pragma("unroll") for (int m = 0; m < 4; ++m) _Pragma("unroll") for (int k = 0; k < 2; ++k) dst[m][k] = *(const LAS bf16x8*)(lds + PG8_SA(b, h) + aoff + m * 2048 + k * 1024); } while (0)
; #define PG8_LDB(dst, b, h) do { _Pragma("unroll") for (int n = 0; n < 2; ++n) _Pragma("unroll") for (int k = 0; k < 2; ++k) dst[n][k] = *(const LAS bf16x8*)(lds + PG8_SB(b, h) + boff + n * 2048 + k * 1024); } while (0)
; #define PG8_WAIT_V(n) asm volatile("s_waitcnt vmcnt(" #n ")" ::: "memory")
; #define PG8_WAIT_L(n) asm volatile("s_waitcnt lgkmcnt(" #n ")" ::: "memory")
; #define PG8_BAR __builtin_amdgcn_s_barrier()
; #define PG8_SCHED __builtin_amdgcn_sched_barrier(0)
; template <class Epi, class Ptrs>
; __device__ __forceinline__ void gemm_phase(LAS unsigned char* lds, const int K, const StaticOrder& S, const Ptrs& P, const Epi& E) {
;     ...
;             PG8_LDB(B0, 0, 0); PG8_SCHED; PG8_LDA(At, 0, 0); PG8_STAGE(PG8_SA(1, 1), a1 + hstep, voffA);
;             PG8_WAIT_L(8); PG8_BAR; PG8_WAIT_L(0); PG8_MMA(0, 0, At, B0); PG8_BAR; PG8_SCHED;
;             PG8_LDB(B1, 0, 1); PG8_STAGE(PG8_SB(0, 0), b2, voffB);
;             PG8_BAR; PG8_WAIT_L(0); PG8_MMA(0, 1, At, B1); PG8_BAR;
;             PG8_LDA(At, 0, 1); PG8_STAGE(PG8_SA(0, 0), a2, voffA);
;             PG8_BAR; PG8_WAIT_L(0); PG8_MMA(1, 0, At, B0); PG8_BAR; PG8_SCHED;
;             PG8_STAGE(PG8_SB(0, 1), b2 + hstep, voffB);
;             PG8_WAIT_V(6); PG8_BAR; PG8_MMA(1, 1, At, B1); PG8_BAR;
;             PG8_LDB(B0, 1, 0); PG8_SCHED; PG8_LDA(At, 1, 0); PG8_STAGE(PG8_SA(0, 1), a2 + hstep, voffA);
;             PG8_WAIT_L(8); PG8_BAR; PG8_WAIT_L(0); PG8_MMA(0, 0, At, B0); PG8_BAR; PG8_SCHED;
;             PG8_LDB(B1, 1, 1); PG8_STAGE(PG8_SB(1, 0), b3, voffB);
;             PG8_BAR; PG8_WAIT_L(0); PG8_MMA(0, 1, At, B1); PG8_BAR;
;             PG8_LDA(At, 1, 1); PG8_STAGE(PG8_SA(1, 0), a3, voffA);
;             PG8_BAR; PG8_WAIT_L(0); PG8_MMA(1, 0, At, B0); PG8_BAR; PG8_SCHED;
;             PG8_STAGE(PG8_SB(1, 1), b3 + hstep, voffB);
;             PG8_WAIT_V(6); PG8_BAR; PG8_MMA(1, 1, At, B1); PG8_BAR;
	s_add_i32 s44, 0, 0x1c000
	s_add_i32 s45, s71, s51
	s_mov_b32 m0, s45
	ds_read_b128 v[200:203], v253
	ds_read_b128 v[204:207], v253 offset:1024
	ds_read_b128 v[210:213], v253 offset:2048
	ds_read_b128 v[214:217], v253 offset:3072
	global_load_lds_dwordx4 v130, s[76:77]
	s_add_i32 m0, s45, 0x2000
	s_nop 0
	global_load_lds_dwordx4 v134, s[76:77]
	s_barrier
	s_waitcnt lgkmcnt(0)
	v_mfma_f32_16x16x32_bf16 v[116:119], v[200:203], v[168:171], v[116:119]
	v_mfma_f32_16x16x32_bf16 v[116:119], v[204:207], v[172:175], v[116:119]
	v_mfma_f32_16x16x32_bf16 v[112:115], v[214:217], v[172:175], v[112:115]
	v_mfma_f32_16x16x32_bf16 v[112:115], v[210:213], v[168:171], v[112:115]
	v_mfma_f32_16x16x32_bf16 v[96:99], v[210:213], v[176:179], v[96:99]
	v_mfma_f32_16x16x32_bf16 v[96:99], v[214:217], v[180:183], v[96:99]
	v_mfma_f32_16x16x32_bf16 v[100:103], v[204:207], v[180:183], v[100:103]
	v_mfma_f32_16x16x32_bf16 v[100:103], v[200:203], v[176:179], v[100:103]
	v_mfma_f32_16x16x32_bf16 v[84:87], v[200:203], v[184:187], v[84:87]
	v_mfma_f32_16x16x32_bf16 v[84:87], v[204:207], v[188:191], v[84:87]
	v_mfma_f32_16x16x32_bf16 v[80:83], v[214:217], v[188:191], v[80:83]
	v_mfma_f32_16x16x32_bf16 v[80:83], v[210:213], v[184:187], v[80:83]
	v_mfma_f32_16x16x32_bf16 v[64:67], v[210:213], v[192:195], v[64:67]
	v_mfma_f32_16x16x32_bf16 v[64:67], v[214:217], v[196:199], v[64:67]
	v_mfma_f32_16x16x32_bf16 v[68:71], v[204:207], v[196:199], v[68:71]
	v_mfma_f32_16x16x32_bf16 v[68:71], v[200:203], v[192:195], v[68:71]
	s_barrier
	s_mov_b32 m0, s61
	ds_read_b128 v[168:171], v150 offset:49152
	ds_read_b128 v[172:175], v150 offset:50176
	ds_read_b128 v[176:179], v150 offset:51200
	ds_read_b128 v[180:183], v150 offset:52224
	ds_read_b128 v[184:187], v150 offset:53248
	ds_read_b128 v[188:191], v150 offset:54272
	ds_read_b128 v[192:195], v150 offset:55296
	ds_read_b128 v[196:199], v150 offset:56320
	global_load_lds_dwordx4 v128, s[78:79]
	s_mov_b32 m0, s62
	s_nop 0
	global_load_lds_dwordx4 v132, s[78:79]
	s_barrier
	s_waitcnt lgkmcnt(6)
	v_mfma_f32_16x16x32_bf16 v[60:63], v[152:155], v[168:171], v[60:63]
	v_mfma_f32_16x16x32_bf16 v[60:63], v[156:159], v[172:175], v[60:63]
	v_mfma_f32_16x16x32_bf16 v[56:59], v[164:167], v[172:175], v[56:59]
	v_mfma_f32_16x16x32_bf16 v[56:59], v[160:163], v[168:171], v[56:59]
	s_waitcnt lgkmcnt(4)
	v_mfma_f32_16x16x32_bf16 v[40:43], v[160:163], v[176:179], v[40:43]
	v_mfma_f32_16x16x32_bf16 v[40:43], v[164:167], v[180:183], v[40:43]
	v_mfma_f32_16x16x32_bf16 v[44:47], v[156:159], v[180:183], v[44:47]
	v_mfma_f32_16x16x32_bf16 v[44:47], v[152:155], v[176:179], v[44:47]
	s_waitcnt lgkmcnt(2)
	v_mfma_f32_16x16x32_bf16 v[28:31], v[152:155], v[184:187], v[28:31]
	v_mfma_f32_16x16x32_bf16 v[28:31], v[156:159], v[188:191], v[28:31]
	v_mfma_f32_16x16x32_bf16 v[24:27], v[164:167], v[188:191], v[24:27]
	v_mfma_f32_16x16x32_bf16 v[24:27], v[160:163], v[184:187], v[24:27]
	s_waitcnt lgkmcnt(0)
	v_mfma_f32_16x16x32_bf16 v[8:11], v[160:163], v[192:195], v[8:11]
	v_mfma_f32_16x16x32_bf16 v[8:11], v[164:167], v[196:199], v[8:11]
	v_mfma_f32_16x16x32_bf16 v[12:15], v[156:159], v[196:199], v[12:15]
	v_mfma_f32_16x16x32_bf16 v[12:15], v[152:155], v[192:195], v[12:15]
	s_barrier
	s_add_u32 s42, s42, 0x40080
	s_addc_u32 s43, s43, 0
	s_add_i32 s44, s44, s51
	s_mov_b32 m0, s44
	s_nop 0
	global_load_lds_dwordx4 v130, s[42:43]
	s_add_i32 m0, s44, 0x2000
	s_nop 0
	global_load_lds_dwordx4 v134, s[42:43]
	s_waitcnt vmcnt(6)
	s_barrier
	v_mfma_f32_16x16x32_bf16 v[52:55], v[200:203], v[168:171], v[52:55]
	v_mfma_f32_16x16x32_bf16 v[52:55], v[204:207], v[172:175], v[52:55]
	v_mfma_f32_16x16x32_bf16 v[48:51], v[214:217], v[172:175], v[48:51]
	v_mfma_f32_16x16x32_bf16 v[48:51], v[210:213], v[168:171], v[48:51]
	v_mfma_f32_16x16x32_bf16 v[32:35], v[210:213], v[176:179], v[32:35]
	v_mfma_f32_16x16x32_bf16 v[32:35], v[214:217], v[180:183], v[32:35]
	v_mfma_f32_16x16x32_bf16 v[36:39], v[204:207], v[180:183], v[36:39]
	v_mfma_f32_16x16x32_bf16 v[36:39], v[200:203], v[176:179], v[36:39]
	v_mfma_f32_16x16x32_bf16 v[20:23], v[200:203], v[184:187], v[20:23]
	v_mfma_f32_16x16x32_bf16 v[20:23], v[204:207], v[188:191], v[20:23]
	v_mfma_f32_16x16x32_bf16 v[16:19], v[214:217], v[188:191], v[16:19]
	v_mfma_f32_16x16x32_bf16 v[16:19], v[210:213], v[184:187], v[16:19]
	v_mfma_f32_16x16x32_bf16 v[0:3], v[210:213], v[192:195], v[0:3]
	v_mfma_f32_16x16x32_bf16 v[0:3], v[214:217], v[196:199], v[0:3]
	v_mfma_f32_16x16x32_bf16 v[4:7], v[204:207], v[196:199], v[4:7]
	v_mfma_f32_16x16x32_bf16 v[4:7], v[200:203], v[192:195], v[4:7]
	s_barrier
	s_add_i32 s70, s70, 2
	s_add_u32 s40, s40, 0x100
	s_addc_u32 s41, s41, 0
	s_add_u32 s23, s23, 0x100
	s_addc_u32 s25, s25, 0
	s_cmp_gt_u32 s70, 13
	s_cbranch_scc0 .LBB0_433
; __device__ __forceinline__ unsigned cvt_pk_bf16(float lo, float hi) { unsigned r; asm volatile("v_cvt_pk_bf16_f32 %0, %1, %2" : "=v"(r) : "v"(lo), "v"(hi)); return r; }
;     __device__ __forceinline__ void operator()(const f32x4 (&acc)[2][2][4][2], const Unit& u, int ui, int wr, int wc, int fr, int fq) const {
;         const int row0 = u.pm * 256 + wr * 64 + fr, col0 = u.pn * 256 + wc * 32 + 8 * fq;
; #pragma unroll
;         for (int ai = 0; ai < 2; ++ai)
; #pragma unroll
;             for (int m = 0; m < 4; ++m) { bf16_t* rowp = hid + (size_t)(row0 + ai * 128 + m * 16) * DFF + col0;
; #pragma unroll
;                 for (int bj = 0; bj < 2; ++bj) { f32x4 v0 = acc[ai][bj][m][0], v1 = acc[ai][bj][m][1];
; #pragma unroll
;                     for (int j = 0; j < 4; ++j) { const float a = fmaxf(v0[j], 0.f), b = fmaxf(v1[j], 0.f); v0[j] = a * a; v1[j] = b * b; }
;                     u32x4 w; w.x = cvt_pk_bf16(v0[0], v0[1]); w.y = cvt_pk_bf16(v0[2], v0[3]); w.z = cvt_pk_bf16(v1[0], v1[1]); w.w = cvt_pk_bf16(v1[2], v1[3]);
;                     *(u32x4*)(rowp + bj * 128) = w; } }
	v_lshl_add_u32 v152, s38, 8, v146
	v_max_f32_e32 v120, 0, v120
	v_ashrrev_i32_e32 v153, 31, v152
	v_max_f32_e32 v121, 0, v121
	v_max_f32_e32 v122, 0, v122
	v_lshl_or_b32 v144, s69, 8, v148
	v_lshlrev_b64 v[154:155], 13, v[152:153]
	v_mul_f32_e32 v153, v120, v120
	v_max_f32_e32 v120, 0, v125
	v_ashrrev_i32_e32 v145, 31, v144
	v_max_f32_e32 v124, 0, v124
	v_mul_f32_e32 v125, v121, v121
	v_max_f32_e32 v121, 0, v126
	v_mul_f32_e32 v126, v122, v122
	v_max_f32_e32 v122, 0, v127
	v_max_f32_e32 v123, 0, v123
	v_lshl_add_u64 v[154:155], s[10:11], 0, v[154:155]
	v_lshlrev_b64 v[156:157], 1, v[144:145]
	v_mul_f32_e32 v120, v120, v120
	v_max_f32_e32 v112, 0, v112
	v_lshl_add_u64 v[144:145], v[154:155], 0, v[156:157]
	v_mul_f32_e32 v124, v124, v124
	v_mul_f32_e32 v121, v121, v121
	v_mul_f32_e32 v122, v122, v122
	v_mul_f32_e32 v123, v123, v123
	v_cvt_pk_bf16_f32 v120, v124, v120
	v_max_f32_e32 v113, 0, v113
	v_max_f32_e32 v114, 0, v114
	v_cvt_pk_bf16_f32 v121, v121, v122
	v_cvt_pk_bf16_f32 v122, v153, v125
	v_cvt_pk_bf16_f32 v123, v126, v123
	global_store_dwordx4 v[144:145], v[120:123], off
	s_nop 1
	v_mul_f32_e32 v120, v112, v112
	v_max_f32_e32 v112, 0, v117
	v_max_f32_e32 v116, 0, v116
	v_mul_f32_e32 v117, v113, v113
	v_max_f32_e32 v113, 0, v118
	v_mul_f32_e32 v118, v114, v114
	v_max_f32_e32 v114, 0, v119
	v_max_f32_e32 v115, 0, v115
	v_mul_f32_e32 v112, v112, v112
	v_mul_f32_e32 v116, v116, v116
	v_mul_f32_e32 v113, v113, v113
	v_mul_f32_e32 v114, v114, v114
	v_mul_f32_e32 v115, v115, v115
	v_cvt_pk_bf16_f32 v112, v116, v112
	v_max_f32_e32 v104, 0, v104
	v_cvt_pk_bf16_f32 v113, v113, v114
	v_cvt_pk_bf16_f32 v114, v120, v117
	v_cvt_pk_bf16_f32 v115, v118, v115
	global_store_dwordx4 v[144:145], v[112:115], off offset:256
	s_nop 0
	v_max_f32_e32 v105, 0, v105
	v_or_b32_e32 v112, 16, v152
	v_max_f32_e32 v106, 0, v106
	v_ashrrev_i32_e32 v113, 31, v112
	v_mul_f32_e32 v114, v104, v104
	v_max_f32_e32 v104, 0, v109
	v_lshlrev_b64 v[112:113], 13, v[112:113]
	v_max_f32_e32 v108, 0, v108
	v_mul_f32_e32 v109, v105, v105
	v_max_f32_e32 v105, 0, v110
	v_mul_f32_e32 v110, v106, v106
	v_max_f32_e32 v106, 0, v111
	v_max_f32_e32 v107, 0, v107
	v_lshl_add_u64 v[112:113], s[10:11], 0, v[112:113]
	v_mul_f32_e32 v104, v104, v104
	v_max_f32_e32 v96, 0, v96
	v_lshl_add_u64 v[112:113], v[112:113], 0, v[156:157]
	v_mul_f32_e32 v108, v108, v108
	v_mul_f32_e32 v105, v105, v105
	v_mul_f32_e32 v106, v106, v106
	v_mul_f32_e32 v107, v107, v107
	v_cvt_pk_bf16_f32 v104, v108, v104
	v_max_f32_e32 v97, 0, v97
	v_max_f32_e32 v98, 0, v98
	v_cvt_pk_bf16_f32 v105, v105, v106
	v_cvt_pk_bf16_f32 v106, v114, v109
	v_cvt_pk_bf16_f32 v107, v110, v107
	global_store_dwordx4 v[112:113], v[104:107], off
	s_nop 1
	v_mul_f32_e32 v104, v96, v96
	v_max_f32_e32 v96, 0, v101
	v_max_f32_e32 v100, 0, v100
	v_mul_f32_e32 v101, v97, v97
	v_max_f32_e32 v97, 0, v102
	v_mul_f32_e32 v102, v98, v98
	v_max_f32_e32 v98, 0, v103
	v_max_f32_e32 v99, 0, v99
	v_mul_f32_e32 v96, v96, v96
	v_mul_f32_e32 v100, v100, v100
	v_mul_f32_e32 v97, v97, v97
	v_mul_f32_e32 v98, v98, v98
	v_mul_f32_e32 v99, v99, v99
	v_cvt_pk_bf16_f32 v96, v100, v96
	v_max_f32_e32 v88, 0, v88
	v_cvt_pk_bf16_f32 v97, v97, v98
	v_cvt_pk_bf16_f32 v98, v104, v101
	v_cvt_pk_bf16_f32 v99, v102, v99
	global_store_dwordx4 v[112:113], v[96:99], off offset:256
	s_nop 0
	v_max_f32_e32 v89, 0, v89
	v_or_b32_e32 v96, 32, v152
	v_max_f32_e32 v90, 0, v90
	v_ashrrev_i32_e32 v97, 31, v96
	v_mul_f32_e32 v98, v88, v88
	v_max_f32_e32 v88, 0, v93
	v_lshlrev_b64 v[96:97], 13, v[96:97]
	v_max_f32_e32 v92, 0, v92
	v_mul_f32_e32 v93, v89, v89
	v_max_f32_e32 v89, 0, v94
	v_mul_f32_e32 v94, v90, v90
	v_max_f32_e32 v90, 0, v95
	v_max_f32_e32 v91, 0, v91
	v_lshl_add_u64 v[96:97], s[10:11], 0, v[96:97]
	v_mul_f32_e32 v88, v88, v88
	v_max_f32_e32 v80, 0, v80
	v_lshl_add_u64 v[96:97], v[96:97], 0, v[156:157]
	v_mul_f32_e32 v92, v92, v92
	v_mul_f32_e32 v89, v89, v89
	v_mul_f32_e32 v90, v90, v90
	v_mul_f32_e32 v91, v91, v91
	v_cvt_pk_bf16_f32 v88, v92, v88
	v_max_f32_e32 v81, 0, v81
	v_max_f32_e32 v82, 0, v82
	v_cvt_pk_bf16_f32 v89, v89, v90
	v_cvt_pk_bf16_f32 v90, v98, v93
	v_cvt_pk_bf16_f32 v91, v94, v91
	global_store_dwordx4 v[96:97], v[88:91], off
	s_nop 1
	v_mul_f32_e32 v88, v80, v80
	v_max_f32_e32 v80, 0, v85
	v_max_f32_e32 v84, 0, v84
	v_mul_f32_e32 v85, v81, v81
	v_max_f32_e32 v81, 0, v86
	v_mul_f32_e32 v86, v82, v82
	v_max_f32_e32 v82, 0, v87
	v_max_f32_e32 v83, 0, v83
	v_mul_f32_e32 v80, v80, v80
	v_mul_f32_e32 v84, v84, v84
	v_mul_f32_e32 v81, v81, v81
	v_mul_f32_e32 v82, v82, v82
	v_mul_f32_e32 v83, v83, v83
	v_cvt_pk_bf16_f32 v80, v84, v80
	v_max_f32_e32 v72, 0, v72
	v_cvt_pk_bf16_f32 v81, v81, v82
	v_cvt_pk_bf16_f32 v82, v88, v85
	v_cvt_pk_bf16_f32 v83, v86, v83
	global_store_dwordx4 v[96:97], v[80:83], off offset:256
	s_nop 0
	v_max_f32_e32 v73, 0, v73
	v_or_b32_e32 v80, 48, v152
	v_max_f32_e32 v74, 0, v74
	v_ashrrev_i32_e32 v81, 31, v80
	v_mul_f32_e32 v82, v72, v72
	v_max_f32_e32 v72, 0, v77
	v_lshlrev_b64 v[80:81], 13, v[80:81]
	v_max_f32_e32 v76, 0, v76
	v_mul_f32_e32 v77, v73, v73
	v_max_f32_e32 v73, 0, v78
	v_mul_f32_e32 v78, v74, v74
	v_max_f32_e32 v74, 0, v79
	v_max_f32_e32 v75, 0, v75
	v_lshl_add_u64 v[80:81], s[10:11], 0, v[80:81]
	v_mul_f32_e32 v72, v72, v72
	v_max_f32_e32 v64, 0, v64
	v_max_f32_e32 v65, 0, v65
	v_max_f32_e32 v66, 0, v66
	v_lshl_add_u64 v[80:81], v[80:81], 0, v[156:157]
	v_mul_f32_e32 v76, v76, v76
	v_mul_f32_e32 v73, v73, v73
	v_mul_f32_e32 v74, v74, v74
	v_mul_f32_e32 v75, v75, v75
	v_cvt_pk_bf16_f32 v72, v76, v72
	v_cvt_pk_bf16_f32 v73, v73, v74
	v_cvt_pk_bf16_f32 v74, v82, v77
	v_cvt_pk_bf16_f32 v75, v78, v75
; __device__ __forceinline__ unsigned cvt_pk_bf16(float lo, float hi) { unsigned r; asm volatile("v_cvt_pk_bf16_f32 %0, %1, %2" : "=v"(r) : "v"(lo), "v"(hi)); return r; }
; #define PG8_WAIT_V(n) asm volatile("s_waitcnt vmcnt(" #n ")" ::: "memory")
; #define PG8_BAR __builtin_amdgcn_s_barrier()
; template <class Epi, class Ptrs>
; __device__ __forceinline__ void gemm_phase(LAS unsigned char* lds, const int K, const StaticOrder& S, const Ptrs& P, const Epi& E) {
;     ...
;     PG8_WAIT_V(0);
;     if (wr == 0) PG8_BAR;
;     PG8_BAR;
;     __device__ __forceinline__ void operator()(const f32x4 (&acc)[2][2][4][2], const Unit& u, int ui, int wr, int wc, int fr, int fq) const {
;         const int row0 = u.pm * 256 + wr * 64 + fr, col0 = u.pn * 256 + wc * 32 + 8 * fq;
; #pragma unroll
;         for (int ai = 0; ai < 2; ++ai)
; #pragma unroll
;             for (int m = 0; m < 4; ++m) { bf16_t* rowp = hid + (size_t)(row0 + ai * 128 + m * 16) * DFF + col0;
; #pragma unroll
;                 for (int bj = 0; bj < 2; ++bj) { f32x4 v0 = acc[ai][bj][m][0], v1 = acc[ai][bj][m][1];
; #pragma unroll
;                     for (int j = 0; j < 4; ++j) { const float a = fmaxf(v0[j], 0.f), b = fmaxf(v1[j], 0.f); v0[j] = a * a; v1[j] = b * b; }
;                     u32x4 w; w.x = cvt_pk_bf16(v0[0], v0[1]); w.y = cvt_pk_bf16(v0[2], v0[3]); w.z = cvt_pk_bf16(v1[0], v1[1]); w.w = cvt_pk_bf16(v1[2], v1[3]);
;                     *(u32x4*)(rowp + bj * 128) = w; } }
	global_store_dwordx4 v[80:81], v[72:75], off
	v_max_f32_e32 v68, 0, v68
	v_max_f32_e32 v67, 0, v67
	v_mul_f32_e32 v72, v64, v64
	v_max_f32_e32 v64, 0, v69
	v_mul_f32_e32 v69, v65, v65
	v_max_f32_e32 v65, 0, v70
	v_mul_f32_e32 v70, v66, v66
	v_max_f32_e32 v66, 0, v71
	v_mul_f32_e32 v64, v64, v64
	v_mul_f32_e32 v65, v65, v65
	v_mul_f32_e32 v66, v66, v66
	v_max_f32_e32 v56, 0, v56
	v_mul_f32_e32 v68, v68, v68
	v_mul_f32_e32 v67, v67, v67
	v_cvt_pk_bf16_f32 v64, v68, v64
	v_cvt_pk_bf16_f32 v65, v65, v66
	v_cvt_pk_bf16_f32 v66, v72, v69
	v_max_f32_e32 v57, 0, v57
	v_max_f32_e32 v58, 0, v58
	v_cvt_pk_bf16_f32 v67, v70, v67
	global_store_dwordx4 v[80:81], v[64:67], off offset:256
	s_nop 0
	v_max_f32_e32 v60, 0, v60
	v_mul_f32_e32 v66, v56, v56
	v_max_f32_e32 v56, 0, v61
	v_mul_f32_e32 v61, v57, v57
	v_max_f32_e32 v57, 0, v62
	v_mul_f32_e32 v62, v58, v58
	v_max_f32_e32 v58, 0, v63
	v_mul_f32_e32 v60, v60, v60
	v_mul_f32_e32 v56, v56, v56
	v_max_f32_e32 v59, 0, v59
	v_mul_f32_e32 v57, v57, v57
	v_mul_f32_e32 v58, v58, v58
	v_cvt_pk_bf16_f32 v56, v60, v56
	v_add_co_u32_e32 v60, vcc, s65, v144
	v_max_f32_e32 v48, 0, v48
	v_max_f32_e32 v49, 0, v49
	v_max_f32_e32 v50, 0, v50
	v_mul_f32_e32 v59, v59, v59
	v_cvt_pk_bf16_f32 v57, v57, v58
	v_cvt_pk_bf16_f32 v58, v66, v61
	v_addc_co_u32_e32 v61, vcc, 0, v145, vcc
	v_cvt_pk_bf16_f32 v59, v62, v59
	global_store_dwordx4 v[60:61], v[56:59], off
	v_max_f32_e32 v52, 0, v52
	v_max_f32_e32 v51, 0, v51
	v_mul_f32_e32 v56, v48, v48
	v_max_f32_e32 v48, 0, v53
	v_mul_f32_e32 v53, v49, v49
	v_max_f32_e32 v49, 0, v54
	v_mul_f32_e32 v54, v50, v50
	v_max_f32_e32 v50, 0, v55
	v_mul_f32_e32 v48, v48, v48
	v_mul_f32_e32 v49, v49, v49
	v_mul_f32_e32 v50, v50, v50
	v_max_f32_e32 v40, 0, v40
	v_lshl_add_u64 v[64:65], v[144:145], 0, s[14:15]
	v_mul_f32_e32 v52, v52, v52
	v_mul_f32_e32 v51, v51, v51
	v_cvt_pk_bf16_f32 v48, v52, v48
	v_cvt_pk_bf16_f32 v49, v49, v50
	v_cvt_pk_bf16_f32 v50, v56, v53
	v_max_f32_e32 v41, 0, v41
	v_max_f32_e32 v42, 0, v42
	v_cvt_pk_bf16_f32 v51, v54, v51
	global_store_dwordx4 v[64:65], v[48:51], off offset:256
	s_nop 0
	v_max_f32_e32 v44, 0, v44
	v_mul_f32_e32 v50, v40, v40
	v_max_f32_e32 v40, 0, v45
	v_mul_f32_e32 v45, v41, v41
	v_max_f32_e32 v41, 0, v46
	v_mul_f32_e32 v46, v42, v42
	v_max_f32_e32 v42, 0, v47
	v_mul_f32_e32 v44, v44, v44
	v_mul_f32_e32 v40, v40, v40
	v_max_f32_e32 v43, 0, v43
	v_mul_f32_e32 v41, v41, v41
	v_mul_f32_e32 v42, v42, v42
	v_cvt_pk_bf16_f32 v40, v44, v40
	v_add_co_u32_e32 v44, vcc, s66, v144
	v_max_f32_e32 v32, 0, v32
	v_max_f32_e32 v33, 0, v33
	v_max_f32_e32 v34, 0, v34
	v_mul_f32_e32 v43, v43, v43
	v_cvt_pk_bf16_f32 v41, v41, v42
	v_cvt_pk_bf16_f32 v42, v50, v45
	v_addc_co_u32_e32 v45, vcc, 0, v145, vcc
	v_cvt_pk_bf16_f32 v43, v46, v43
	global_store_dwordx4 v[44:45], v[40:43], off
	v_max_f32_e32 v36, 0, v36
	v_max_f32_e32 v35, 0, v35
	v_mul_f32_e32 v40, v32, v32
	v_max_f32_e32 v32, 0, v37
	v_mul_f32_e32 v37, v33, v33
	v_max_f32_e32 v33, 0, v38
	v_mul_f32_e32 v38, v34, v34
	v_max_f32_e32 v34, 0, v39
	v_mul_f32_e32 v32, v32, v32
	v_mul_f32_e32 v33, v33, v33
	v_mul_f32_e32 v34, v34, v34
	v_max_f32_e32 v24, 0, v24
	v_lshl_add_u64 v[48:49], v[144:145], 0, s[16:17]
	v_mul_f32_e32 v36, v36, v36
	v_mul_f32_e32 v35, v35, v35
	v_cvt_pk_bf16_f32 v32, v36, v32
	v_cvt_pk_bf16_f32 v33, v33, v34
	v_cvt_pk_bf16_f32 v34, v40, v37
	v_max_f32_e32 v25, 0, v25
	v_max_f32_e32 v26, 0, v26
	v_cvt_pk_bf16_f32 v35, v38, v35
	global_store_dwordx4 v[48:49], v[32:35], off offset:256
	s_nop 0
	v_max_f32_e32 v28, 0, v28
	v_mul_f32_e32 v34, v24, v24
	v_max_f32_e32 v24, 0, v29
	v_mul_f32_e32 v29, v25, v25
	v_max_f32_e32 v25, 0, v30
	v_mul_f32_e32 v30, v26, v26
	v_max_f32_e32 v26, 0, v31
	v_mul_f32_e32 v28, v28, v28
	v_mul_f32_e32 v24, v24, v24
	v_max_f32_e32 v27, 0, v27
	v_mul_f32_e32 v25, v25, v25
	v_mul_f32_e32 v26, v26, v26
	v_cvt_pk_bf16_f32 v24, v28, v24
	v_add_co_u32_e32 v28, vcc, s67, v144
	v_max_f32_e32 v16, 0, v16
	v_max_f32_e32 v17, 0, v17
	v_max_f32_e32 v18, 0, v18
	v_mul_f32_e32 v27, v27, v27
	v_cvt_pk_bf16_f32 v25, v25, v26
	v_cvt_pk_bf16_f32 v26, v34, v29
	v_addc_co_u32_e32 v29, vcc, 0, v145, vcc
	v_cvt_pk_bf16_f32 v27, v30, v27
	global_store_dwordx4 v[28:29], v[24:27], off
	v_max_f32_e32 v20, 0, v20
	v_max_f32_e32 v19, 0, v19
	v_mul_f32_e32 v24, v16, v16
	v_max_f32_e32 v16, 0, v21
	v_mul_f32_e32 v21, v17, v17
	v_max_f32_e32 v17, 0, v22
	v_mul_f32_e32 v22, v18, v18
	v_max_f32_e32 v18, 0, v23
	v_mul_f32_e32 v16, v16, v16
	v_mul_f32_e32 v17, v17, v17
	v_mul_f32_e32 v18, v18, v18
	v_max_f32_e32 v8, 0, v8
	v_lshl_add_u64 v[32:33], v[144:145], 0, s[18:19]
	v_mul_f32_e32 v20, v20, v20
	v_mul_f32_e32 v19, v19, v19
	v_cvt_pk_bf16_f32 v16, v20, v16
	v_cvt_pk_bf16_f32 v17, v17, v18
	v_cvt_pk_bf16_f32 v18, v24, v21
	v_max_f32_e32 v9, 0, v9
	v_max_f32_e32 v10, 0, v10
	v_cvt_pk_bf16_f32 v19, v22, v19
	global_store_dwordx4 v[32:33], v[16:19], off offset:256
	s_nop 0
	v_max_f32_e32 v12, 0, v12
	v_mul_f32_e32 v18, v8, v8
	v_max_f32_e32 v8, 0, v13
	v_mul_f32_e32 v13, v9, v9
	v_max_f32_e32 v9, 0, v14
	v_mul_f32_e32 v14, v10, v10
	v_max_f32_e32 v10, 0, v15
	v_mul_f32_e32 v12, v12, v12
	v_mul_f32_e32 v8, v8, v8
	v_max_f32_e32 v11, 0, v11
	v_mul_f32_e32 v9, v9, v9
	v_mul_f32_e32 v10, v10, v10
	v_cvt_pk_bf16_f32 v8, v12, v8
	v_add_co_u32_e32 v12, vcc, s68, v144
	v_max_f32_e32 v0, 0, v0
	v_max_f32_e32 v1, 0, v1
	v_max_f32_e32 v2, 0, v2
	v_mul_f32_e32 v11, v11, v11
	v_cvt_pk_bf16_f32 v9, v9, v10
	v_cvt_pk_bf16_f32 v10, v18, v13
	v_addc_co_u32_e32 v13, vcc, 0, v145, vcc
	v_cvt_pk_bf16_f32 v11, v14, v11
	global_store_dwordx4 v[12:13], v[8:11], off
	v_max_f32_e32 v3, 0, v3
	v_max_f32_e32 v4, 0, v4
	v_mul_f32_e32 v8, v0, v0
	v_max_f32_e32 v0, 0, v5
	v_mul_f32_e32 v5, v1, v1
	v_max_f32_e32 v1, 0, v6
	v_mul_f32_e32 v6, v2, v2
	v_max_f32_e32 v2, 0, v7
	v_lshl_add_u64 v[16:17], v[144:145], 0, s[20:21]
	v_mul_f32_e32 v0, v0, v0
	v_mul_f32_e32 v1, v1, v1
	v_mul_f32_e32 v2, v2, v2
	v_mul_f32_e32 v3, v3, v3
	s_and_b64 vcc, exec, s[4:5]
	s_mov_b32 s69, s22
	s_mov_b32 s38, s24
	s_mov_b64 s[40:41], s[0:1]
	s_mov_b64 s[42:43], s[36:37]
	v_mul_f32_e32 v4, v4, v4
	v_cvt_pk_bf16_f32 v0, v4, v0
	v_cvt_pk_bf16_f32 v1, v1, v2
	v_cvt_pk_bf16_f32 v2, v8, v5
	v_cvt_pk_bf16_f32 v3, v6, v3
	global_store_dwordx4 v[16:17], v[0:3], off offset:256
	s_cbranch_vccz .LBB0_428
	s_waitcnt vmcnt(0)
	s_setprio 0
	s_cmpk_gt_u32 s46, 0xff
	s_cbranch_scc1 .LBB0_437
	s_barrier

; __device__ __forceinline__ unsigned xb_ld(unsigned* p)              { return __hip_atomic_load(p, __ATOMIC_RELAXED, __HIP_MEMORY_SCOPE_AGENT); }
; __device__ __forceinline__ unsigned xb_add(unsigned* p, unsigned v) { return __hip_atomic_fetch_add(p, v, __ATOMIC_RELAXED, __HIP_MEMORY_SCOPE_AGENT); }
; __device__ __forceinline__ void xcd_barrier_complete(unsigned* bar, unsigned x, unsigned& nloc, unsigned& nx) {
;     const unsigned G = gridDim.x * gridDim.y * gridDim.z;
;     unsigned sum, cnt, mine, sp = 0u;
;     for (;;) {
;         sum = 0u; cnt = 0u; mine = 0u;
; #pragma unroll
;         for (unsigned j = 0; j < 16; ++j) { const unsigned c = xb_ld(&bar[XB_XCNT(j)]); sum += c; cnt += (c > 0u) ? 1u : 0u; mine = (j == x) ? c : mine; }
; __device__ __forceinline__ void xcd_barrier(const XcdBarrier& b) {
;     asm volatile("s_waitcnt vmcnt(0)" ::: "memory");
;     __syncthreads();
;     if (threadIdx.x == 0) {
;         unsigned* bar = b.bar;
;         __builtin_amdgcn_s_waitcnt(0);
;         unsigned nloc = b.st[0], nx = b.st[1];
;         if (nloc == 0u) { xcd_barrier_complete(bar, b.x, nloc, nx); b.st[0] = nloc; b.st[1] = nx; }
;         const unsigned old = xb_add(&bar[XB_XSUB(b.x)], 1u);
.LBB0_438:
	s_nop 0
	s_nop 0
	s_nop 0
	s_nop 0
	s_nop 0
	s_nop 0
	s_nop 0
	s_nop 0
	s_nop 0
	s_nop 0
	s_nop 0
	s_nop 0
	s_nop 0
	s_nop 0
	s_nop 0
	s_nop 0
	s_nop 0
	s_nop 0
	s_nop 0
	s_nop 0
	s_nop 0
	s_nop 0
	s_nop 0
	s_nop 0
	s_nop 0
	s_nop 0
	s_nop 0
	s_cmp_gt_i32 s31, 5
	s_cselect_b64 s[0:1], -1, 0
	s_and_b64 s[4:5], s[6:7], s[0:1]
	s_andn2_b64 vcc, exec, s[4:5]
	s_cbranch_vccnz .LBB0_488
	s_waitcnt vmcnt(0)
	s_waitcnt vmcnt(0) lgkmcnt(0)
	s_barrier
	s_and_saveexec_b64 s[4:5], s[8:9]
	s_cbranch_execz .LBB0_487
	s_add_i32 s6, 0, 0x25ff0
	v_mov_b32_e32 v0, s6
	s_waitcnt vmcnt(0) expcnt(0) lgkmcnt(0)
	ds_read_b32 v2, v0
	s_add_i32 s6, 0, 0x25ff4
	v_mov_b32_e32 v0, s6
	ds_read_b32 v0, v0
	s_waitcnt lgkmcnt(1)
	v_cmp_ne_u32_e32 vcc, 0, v2
	s_cbranch_vccnz .LBB0_455
	s_load_dwordx2 s[10:11], s[52:53], 0x4
	s_add_u32 s6, s28, 0x3e800200
	s_addc_u32 s7, s29, 0
	s_add_u32 s8, s28, 0x3e800400
	s_addc_u32 s9, s29, 0
	s_waitcnt lgkmcnt(0)
	s_mul_i32 s31, s10, s3
	s_add_u32 s10, s28, 0x3e800500
	s_mul_i32 s31, s31, s11
	s_addc_u32 s11, s29, 0
	s_add_u32 s12, s28, 0x3e800600
	s_addc_u32 s13, s29, 0
	s_add_u32 s14, s28, 0x3e800700
	s_addc_u32 s15, s29, 0
	s_add_u32 s16, s28, 0x3e800800
	s_addc_u32 s17, s29, 0
	s_add_u32 s18, s28, 0x3e800900
	s_addc_u32 s19, s29, 0
	s_add_u32 s20, s28, 0x3e800a00
	s_addc_u32 s21, s29, 0
	s_add_u32 s22, s28, 0x3e800b00
	s_addc_u32 s23, s29, 0
	s_add_u32 s24, s28, 0x3e800c00
	s_addc_u32 s25, s29, 0
	s_add_u32 s36, s28, 0x3e800d00
	s_addc_u32 s37, s29, 0
	s_add_u32 s38, s28, 0x3e800e00
	s_addc_u32 s39, s29, 0
	s_add_u32 s40, s28, 0x3e800f00
	s_addc_u32 s41, s29, 0
	s_add_u32 s42, s28, 0x3e801000
	s_addc_u32 s43, s29, 0
	s_add_u32 s44, s28, 0x3e801100
	s_addc_u32 s45, s29, 0
	s_add_u32 s46, s28, 0x3e801200
	s_addc_u32 s47, s29, 0
	s_add_u32 s48, s28, 0x3e801300
	s_addc_u32 s49, s29, 0
	s_mov_b32 s56, 1
	v_mov_b32_e32 v16, 0
	s_branch .LBB0_443

; #define PG8_STAGE(bufoff, gbase, voff) do { _Pragma("unroll") for (int _i = 0; _i < 2; ++_i) \
;         __builtin_amdgcn_global_load_lds((const unsigned*)((const char*)(gbase) + (voff)[_i]), (LAS unsigned*)(lds + (bufoff) + ldsw + _i * 8192), 16, 0, 0); } while (0)
; #define PG8_WAIT_V(n) asm volatile("s_waitcnt vmcnt(" #n ")" ::: "memory")
; #define PG8_BAR __builtin_amdgcn_s_barrier()
; template <class Epi, class Ptrs>
; __device__ __forceinline__ void gemm_phase(LAS unsigned char* lds, const int K, const StaticOrder& S, const Ptrs& P, const Epi& E) {
;     ...
;     for (int i = 0; i < 2; ++i) { int R, C; stage_rc(tid * 16 + i * 8192, R, C); const int Rb = (R & ~31) + perm32(R & 31);
;         voffA[i] = (unsigned)(R * K + C) * 2u; voffB[i] = (unsigned)(Rb * K + C) * 2u; }
;     const size_t kstep = (size_t)(BK * 2);
;     const size_t hstep = (size_t)HALF * K * 2;
;     const unsigned ldsw = (unsigned)wid * 1024u;
;     const int aoff = lds_byte(wr * 64 + fr, fq * 8), boff = lds_byte(wc * 32 + fr, fq * 8);
;     ...
;     PG8_STAGE(PG8_SB(0, 0), cB, voffB); PG8_STAGE(PG8_SA(0, 0), cA, voffA); PG8_STAGE(PG8_SB(0, 1), cB + hstep, voffB); PG8_STAGE(PG8_SA(0, 1), cA + hstep, voffA);
;     if (wr == 1) PG8_BAR;
;     PG8_WAIT_V(4); PG8_BAR;
;     PG8_STAGE(PG8_SB(1, 0), cB + kstep, voffB); PG8_STAGE(PG8_SA(1, 0), cA + kstep, voffA); PG8_STAGE(PG8_SB(1, 1), cB + hstep + kstep, voffB);
;     PG8_WAIT_V(6); PG8_BAR;
.LBB0_516:
	s_lshl_b32 s1, s1, 5
	s_and_b32 s1, s1, 0x60
	s_lshl_b32 s10, s0, 13
	s_lshl_b32 s11, s1, 7
	s_add_u32 s6, s28, 0x2000000
	s_mov_b64 s[8:9], 0x80
	s_addc_u32 s7, s29, 0
	s_add_i32 m0, s17, 0x18000
	v_lshl_add_u64 v[6:7], v[6:7], 0, s[8:9]
	s_waitcnt vmcnt(4)
	s_barrier
	global_load_lds_dwordx4 v[6:7], off
	v_lshl_add_u64 v[4:5], v[4:5], 0, s[8:9]
	s_add_i32 m0, s17, 0x1a000
	s_add_i32 s28, s17, 0x8000
	s_add_i32 s29, s17, 0xa000
	global_load_lds_dwordx4 v[4:5], off
	v_lshl_add_u64 v[2:3], v[2:3], 0, s[8:9]
	s_mov_b32 m0, s28
	s_add_u32 s4, s22, 0x100080
	global_load_lds_dwordx4 v[2:3], off
	v_lshl_add_u64 v[0:1], v[0:1], 0, s[8:9]
	s_mov_b32 m0, s29
	s_addc_u32 s5, s23, 0
	global_load_lds_dwordx4 v[0:1], off
	s_add_i32 m0, s17, 0x1c000
	v_lshl_add_u64 v[0:1], s[4:5], 0, v[162:163]
	global_load_lds_dwordx4 v[0:1], off
	v_lshl_add_u64 v[0:1], s[4:5], 0, v[166:167]
	s_add_i32 m0, s17, 0x1e000
	v_lshlrev_b32_e32 v2, 6, v208
	global_load_lds_dwordx4 v[0:1], off
	v_and_b32_e32 v0, 15, v208
	v_lshlrev_b32_e32 v1, 1, v11
	s_movk_i32 s4, 0x3c0
	v_lshl_or_b32 v186, s0, 6, v0
	v_and_or_b32 v2, v2, s4, v1
	v_lshlrev_b32_e32 v3, 2, v208
	v_lshl_or_b32 v0, v0, 6, v1
	v_lshlrev_b32_e32 v1, 2, v186
	s_add_i32 s0, 0, 0x20000
	v_and_b32_e32 v3, 32, v3
	v_and_b32_e32 v4, 32, v1
	v_add_u32_e32 v192, s0, v1
	v_lshlrev_b32_e32 v1, 10, v208
	v_bitop3_b32 v187, s11, v2, v3 bitop3:0xf6
	v_and_b32_e32 v1, 0xe0000, v1
	v_lshlrev_b32_e32 v2, 13, v10
	v_or3_b32 v1, v8, v1, v2
	v_add_u32_e32 v168, v1, v9
	v_lshlrev_b32_e32 v1, 6, v12
	s_waitcnt vmcnt(6)
	v_and_b32_e32 v1, 0x1e0000, v1
	v_bitop3_b32 v0, v0, s10, v4 bitop3:0xde
	v_or3_b32 v1, v8, v1, v2
	s_add_i32 s42, 0, 0x10000
	s_add_i32 s43, 0, 0x14000
	v_or_b32_e32 v188, 16, v186
	v_or_b32_e32 v189, 32, v186
	v_or_b32_e32 v190, 48, v186
	v_or_b32_e32 v191, s1, v11
	v_mov_b32_e32 v169, v163
	v_add_u32_e32 v170, v1, v9
	v_mov_b32_e32 v171, v163
	v_mov_b64_e32 v[172:173], 0x600
	v_mov_b64_e32 v[174:175], 0x5ff
	v_add_u32_e32 v193, s42, v187
	v_add_u32_e32 v194, 0, v0
	s_nop 0
	s_nop 0
	s_nop 0
	s_nop 0
	s_nop 0
	s_nop 0
	s_nop 0
	s_nop 0
	s_nop 0
	s_nop 0
	s_nop 0
	s_nop 0
	s_nop 0
	s_nop 0
	s_nop 0
	s_nop 0
	s_nop 0
	s_nop 0
	s_nop 0
	s_nop 0
	s_nop 0
	s_nop 0
	s_nop 0
	s_nop 0
	s_nop 0
	s_nop 0
	s_nop 0
	s_nop 0
	s_nop 0
	s_nop 0
	s_nop 0
	s_nop 0
	s_nop 0
	s_nop 0
	s_nop 0
	s_nop 0
	s_nop 0
	s_nop 0
	s_nop 0
	s_nop 0
	s_nop 0
	s_nop 0
	s_nop 0
	s_nop 0
	s_nop 0
	s_nop 0
	s_nop 0
	s_nop 0
	s_nop 0
	s_nop 0
	v_add_u32_e32 v195, s43, v187
	s_cmpk_lt_u32 s33, 0x100
	s_cbranch_scc1 .Lsprio_3
	s_setprio 1

; #define PG8_STAGE(bufoff, gbase, voff) do { _Pragma("unroll") for (int _i = 0; _i < 2; ++_i) \
;         __builtin_amdgcn_global_load_lds((const unsigned*)((const char*)(gbase) + (voff)[_i]), (LAS unsigned*)(lds + (bufoff) + ldsw + _i * 8192), 16, 0, 0); } while (0)
; #define PG8_LDA(dst, b, h) do { _Pragma("unroll") for (int m = 0; m < 4; ++m) _Pragma("unroll") for (int k = 0; k < 2; ++k) dst[m][k] = *(const LAS bf16x8*)(lds + PG8_SA(b, h) + aoff + m * 2048 + k * 1024); } while (0)
; #define PG8_LDB(dst, b, h) do { _Pragma("unroll") for (int n = 0; n < 2; ++n) _Pragma("unroll") for (int k = 0; k < 2; ++k) dst[n][k] = *(const LAS bf16x8*)(lds + PG8_SB(b, h) + boff + n * 2048 + k * 1024); } while (0)
; #define PG8_MMA(ai, bj, At, Bt) do { __builtin_amdgcn_s_setprio(1); _Pragma("unroll") for (int m = 0; m < 4; ++m) _Pragma("unroll") for (int n = 0; n < 2; ++n) _Pragma("unroll") for (int k = 0; k < 2; ++k) \
;         acc[ai][bj][m][n] = __builtin_amdgcn_mfma_f32_16x16x32_bf16(Bt[n][k], At[m][k], acc[ai][bj][m][n], 0, 0, 0); __builtin_amdgcn_s_setprio(0); } while (0)
; #define PG8_WAIT_V(n) asm volatile("s_waitcnt vmcnt(" #n ")" ::: "memory")
; #define PG8_WAIT_L(n) asm volatile("s_waitcnt lgkmcnt(" #n ")" ::: "memory")
; template <class Epi, class Ptrs>
; __device__ __forceinline__ void gemm_phase(LAS unsigned char* lds, const int K, const StaticOrder& S, const Ptrs& P, const Epi& E) {
;     ...
;         for (int t = 0; t < nt; t += 2) {
;             const bool last = (t == nt - 2);
;             const char* a1 = cA + (size_t)(t + 1) * kstep;
;             const char* a2 = last ? nA : cA + (size_t)(t + 2) * kstep; const char* b2 = last ? nB : cB + (size_t)(t + 2) * kstep;
;             const char* a3 = a2 + kstep; const char* b3 = b2 + kstep;
;             PG8_LDB(B0, 0, 0); PG8_SCHED; PG8_LDA(At, 0, 0); PG8_STAGE(PG8_SA(1, 1), a1 + hstep, voffA);
;             PG8_WAIT_L(8); PG8_BAR; PG8_WAIT_L(0); PG8_MMA(0, 0, At, B0); PG8_BAR; PG8_SCHED;
;             PG8_LDB(B1, 0, 1); PG8_STAGE(PG8_SB(0, 0), b2, voffB);
;             PG8_BAR; PG8_WAIT_L(0); PG8_MMA(0, 1, At, B1); PG8_BAR;
;             PG8_LDA(At, 0, 1); PG8_STAGE(PG8_SA(0, 0), a2, voffA);
;             PG8_BAR; PG8_WAIT_L(0); PG8_MMA(1, 0, At, B0); PG8_BAR; PG8_SCHED;
;             PG8_STAGE(PG8_SB(0, 1), b2 + hstep, voffB);
;             PG8_WAIT_V(6); PG8_BAR; PG8_MMA(1, 1, At, B1); PG8_BAR;
.LBB0_521:
	s_add_u32 s20, s20, 0x100080
	s_addc_u32 s21, s21, 0
	s_add_u32 s11, s22, 0x100
	s_addc_u32 s13, s23, 0
	s_mov_b32 s46, -2
	v_add_u32_e32 v252, 0x18000, v187
	v_add_u32_e32 v253, 0x1c000, v187
	ds_read_b128 v[128:131], v193
	ds_read_b128 v[132:135], v193 offset:1024
	ds_read_b128 v[136:139], v193 offset:2048
	ds_read_b128 v[140:143], v193 offset:3072
	s_add_u32 s22, s20, 0xfff00080
	s_addc_u32 s23, s21, -1
	s_cmp_eq_u32 s46, 60
	s_cselect_b32 s25, s5, s23
	s_cselect_b32 s24, s4, s22
	s_cselect_b32 s23, s15, s13
	s_cselect_b32 s22, s14, s11
	s_add_i32 m0, s17, 0xc000
	ds_read_b128 v[144:147], v194
	ds_read_b128 v[148:151], v194 offset:1024
	ds_read_b128 v[152:155], v194 offset:2048
	ds_read_b128 v[156:159], v194 offset:3072
	ds_read_b128 v[176:179], v194 offset:4096
	ds_read_b128 v[180:183], v194 offset:5120
	ds_read_b128 v[196:199], v194 offset:6144
	ds_read_b128 v[200:203], v194 offset:7168
	global_load_lds_dwordx4 v168, s[20:21]
	s_add_i32 m0, s17, 0xe000
	s_nop 0
	global_load_lds_dwordx4 v170, s[20:21]
	s_waitcnt lgkmcnt(8)
	s_barrier
	s_waitcnt lgkmcnt(6)
	v_mfma_f32_16x16x32_bf16 v[124:127], v[128:131], v[144:147], 0
	v_mfma_f32_16x16x32_bf16 v[124:127], v[132:135], v[148:151], v[124:127]
	v_mfma_f32_16x16x32_bf16 v[120:123], v[140:143], v[148:151], 0
	v_mfma_f32_16x16x32_bf16 v[120:123], v[136:139], v[144:147], v[120:123]
	s_waitcnt lgkmcnt(4)
	v_mfma_f32_16x16x32_bf16 v[104:107], v[136:139], v[152:155], 0
	v_mfma_f32_16x16x32_bf16 v[104:107], v[140:143], v[156:159], v[104:107]
	v_mfma_f32_16x16x32_bf16 v[112:115], v[132:135], v[156:159], 0
	v_mfma_f32_16x16x32_bf16 v[112:115], v[128:131], v[152:155], v[112:115]
	s_waitcnt lgkmcnt(2)
	v_mfma_f32_16x16x32_bf16 v[92:95], v[128:131], v[176:179], 0
	v_mfma_f32_16x16x32_bf16 v[92:95], v[132:135], v[180:183], v[92:95]
	v_mfma_f32_16x16x32_bf16 v[88:91], v[140:143], v[180:183], 0
	v_mfma_f32_16x16x32_bf16 v[88:91], v[136:139], v[176:179], v[88:91]
	s_waitcnt lgkmcnt(0)
	v_mfma_f32_16x16x32_bf16 v[72:75], v[136:139], v[196:199], 0
	v_mfma_f32_16x16x32_bf16 v[72:75], v[140:143], v[200:203], v[72:75]
	v_mfma_f32_16x16x32_bf16 v[76:79], v[132:135], v[200:203], 0
	v_mfma_f32_16x16x32_bf16 v[76:79], v[128:131], v[196:199], v[76:79]
	s_barrier
	s_add_i32 s47, s42, s34
	s_add_u32 s90, s22, 0x80
	s_addc_u32 s91, s23, 0
	s_mov_b32 m0, s47
	ds_read_b128 v[204:207], v195
	ds_read_b128 v[208:211], v195 offset:1024
	ds_read_b128 v[212:215], v195 offset:2048
	ds_read_b128 v[216:219], v195 offset:3072
	global_load_lds_dwordx4 v162, s[22:23]
	s_add_i32 m0, s47, 0x2000
	s_nop 0
	global_load_lds_dwordx4 v166, s[22:23]
	s_barrier
	s_waitcnt lgkmcnt(0)
	v_mfma_f32_16x16x32_bf16 v[116:119], v[204:207], v[144:147], 0
	v_mfma_f32_16x16x32_bf16 v[116:119], v[208:211], v[148:151], v[116:119]
	v_mfma_f32_16x16x32_bf16 v[108:111], v[216:219], v[148:151], 0
	v_mfma_f32_16x16x32_bf16 v[108:111], v[212:215], v[144:147], v[108:111]
	v_mfma_f32_16x16x32_bf16 v[96:99], v[212:215], v[152:155], 0
	v_mfma_f32_16x16x32_bf16 v[96:99], v[216:219], v[156:159], v[96:99]
	v_mfma_f32_16x16x32_bf16 v[100:103], v[208:211], v[156:159], 0
	v_mfma_f32_16x16x32_bf16 v[100:103], v[204:207], v[152:155], v[100:103]
	v_mfma_f32_16x16x32_bf16 v[84:87], v[204:207], v[176:179], 0
	v_mfma_f32_16x16x32_bf16 v[84:87], v[208:211], v[180:183], v[84:87]
	v_mfma_f32_16x16x32_bf16 v[80:83], v[216:219], v[180:183], 0
	v_mfma_f32_16x16x32_bf16 v[80:83], v[212:215], v[176:179], v[80:83]
	v_mfma_f32_16x16x32_bf16 v[64:67], v[212:215], v[196:199], 0
	v_mfma_f32_16x16x32_bf16 v[64:67], v[216:219], v[200:203], v[64:67]
	v_mfma_f32_16x16x32_bf16 v[68:71], v[208:211], v[200:203], 0
	v_mfma_f32_16x16x32_bf16 v[68:71], v[204:207], v[196:199], v[68:71]
	s_barrier
	s_mov_b32 m0, s17
	s_add_u32 s92, s24, 0x80
	s_addc_u32 s93, s25, 0
	ds_read_b128 v[144:147], v194 offset:16384
	ds_read_b128 v[148:151], v194 offset:17408
	ds_read_b128 v[152:155], v194 offset:18432
	ds_read_b128 v[156:159], v194 offset:19456
	ds_read_b128 v[176:179], v194 offset:20480
	ds_read_b128 v[180:183], v194 offset:21504
	ds_read_b128 v[196:199], v194 offset:22528
	ds_read_b128 v[200:203], v194 offset:23552
	global_load_lds_dwordx4 v160, s[24:25]
	s_mov_b32 m0, s19
	s_nop 0
	global_load_lds_dwordx4 v164, s[24:25]
	s_barrier
	s_waitcnt lgkmcnt(6)
	v_mfma_f32_16x16x32_bf16 v[60:63], v[128:131], v[144:147], 0
	v_mfma_f32_16x16x32_bf16 v[60:63], v[132:135], v[148:151], v[60:63]
	v_mfma_f32_16x16x32_bf16 v[56:59], v[140:143], v[148:151], 0
	v_mfma_f32_16x16x32_bf16 v[56:59], v[136:139], v[144:147], v[56:59]
	s_waitcnt lgkmcnt(4)
	v_mfma_f32_16x16x32_bf16 v[40:43], v[136:139], v[152:155], 0
	v_mfma_f32_16x16x32_bf16 v[40:43], v[140:143], v[156:159], v[40:43]
	v_mfma_f32_16x16x32_bf16 v[48:51], v[132:135], v[156:159], 0
	v_mfma_f32_16x16x32_bf16 v[48:51], v[128:131], v[152:155], v[48:51]
	s_waitcnt lgkmcnt(2)
	v_mfma_f32_16x16x32_bf16 v[32:35], v[128:131], v[176:179], 0
	v_mfma_f32_16x16x32_bf16 v[32:35], v[132:135], v[180:183], v[32:35]
	v_mfma_f32_16x16x32_bf16 v[24:27], v[140:143], v[180:183], 0
	v_mfma_f32_16x16x32_bf16 v[24:27], v[136:139], v[176:179], v[24:27]
	s_waitcnt lgkmcnt(0)
	v_mfma_f32_16x16x32_bf16 v[8:11], v[136:139], v[196:199], 0
	v_mfma_f32_16x16x32_bf16 v[8:11], v[140:143], v[200:203], v[8:11]
	v_mfma_f32_16x16x32_bf16 v[16:19], v[132:135], v[200:203], 0
	v_mfma_f32_16x16x32_bf16 v[16:19], v[128:131], v[196:199], v[16:19]
	s_barrier
	s_add_u32 s48, s22, 0x100000
	s_addc_u32 s49, s23, 0
	s_add_i32 s47, s43, s34
	s_mov_b32 m0, s47
	s_nop 0
	global_load_lds_dwordx4 v162, s[48:49]
	s_add_i32 m0, s47, 0x2000
	s_nop 0
	global_load_lds_dwordx4 v166, s[48:49]
	s_waitcnt vmcnt(6)
	s_barrier
; #define PG8_STAGE(bufoff, gbase, voff) do { _Pragma("unroll") for (int _i = 0; _i < 2; ++_i) \
;         __builtin_amdgcn_global_load_lds((const unsigned*)((const char*)(gbase) + (voff)[_i]), (LAS unsigned*)(lds + (bufoff) + ldsw + _i * 8192), 16, 0, 0); } while (0)
; #define PG8_LDA(dst, b, h) do { _Pragma("unroll") for (int m = 0; m < 4; ++m) _Pragma("unroll") for (int k = 0; k < 2; ++k) dst[m][k] = *(const LAS bf16x8*)(lds + PG8_SA(b, h) + aoff + m * 2048 + k * 1024); } while (0)
; #define PG8_LDB(dst, b, h) do { _Pragma("unroll") for (int n = 0; n < 2; ++n) _Pragma("unroll") for (int k = 0; k < 2; ++k) dst[n][k] = *(const LAS bf16x8*)(lds + PG8_SB(b, h) + boff + n * 2048 + k * 1024); } while (0)
; #define PG8_MMA(ai, bj, At, Bt) do { __builtin_amdgcn_s_setprio(1); _Pragma("unroll") for (int m = 0; m < 4; ++m) _Pragma("unroll") for (int n = 0; n < 2; ++n) _Pragma("unroll") for (int k = 0; k < 2; ++k) \
;         acc[ai][bj][m][n] = __builtin_amdgcn_mfma_f32_16x16x32_bf16(Bt[n][k], At[m][k], acc[ai][bj][m][n], 0, 0, 0); __builtin_amdgcn_s_setprio(0); } while (0)
; #define PG8_WAIT_V(n) asm volatile("s_waitcnt vmcnt(" #n ")" ::: "memory")
; #define PG8_WAIT_L(n) asm volatile("s_waitcnt lgkmcnt(" #n ")" ::: "memory")
; #define PG8_BAR __builtin_amdgcn_s_barrier()
; #define PG8_SCHED __builtin_amdgcn_sched_barrier(0)
; template <class Epi, class Ptrs>
; __device__ __forceinline__ void gemm_phase(LAS unsigned char* lds, const int K, const StaticOrder& S, const Ptrs& P, const Epi& E) {
;     ...
;             PG8_WAIT_V(6); PG8_BAR; PG8_MMA(1, 1, At, B1); PG8_BAR;
;             PG8_LDB(B0, 1, 0); PG8_SCHED; PG8_LDA(At, 1, 0); PG8_STAGE(PG8_SA(0, 1), a2 + hstep, voffA);
;             PG8_WAIT_L(8); PG8_BAR; PG8_WAIT_L(0); PG8_MMA(0, 0, At, B0); PG8_BAR; PG8_SCHED;
;             PG8_LDB(B1, 1, 1); PG8_STAGE(PG8_SB(1, 0), b3, voffB);
;             PG8_BAR; PG8_WAIT_L(0); PG8_MMA(0, 1, At, B1); PG8_BAR;
;             PG8_LDA(At, 1, 1); PG8_STAGE(PG8_SA(1, 0), a3, voffA);
;             PG8_BAR; PG8_WAIT_L(0); PG8_MMA(1, 0, At, B0); PG8_BAR; PG8_SCHED;
	v_mfma_f32_16x16x32_bf16 v[52:55], v[204:207], v[144:147], 0
	v_mfma_f32_16x16x32_bf16 v[52:55], v[208:211], v[148:151], v[52:55]
	v_mfma_f32_16x16x32_bf16 v[44:47], v[216:219], v[148:151], 0
	v_mfma_f32_16x16x32_bf16 v[44:47], v[212:215], v[144:147], v[44:47]
	v_mfma_f32_16x16x32_bf16 v[28:31], v[212:215], v[152:155], 0
	v_mfma_f32_16x16x32_bf16 v[28:31], v[216:219], v[156:159], v[28:31]
	v_mfma_f32_16x16x32_bf16 v[36:39], v[208:211], v[156:159], 0
	v_mfma_f32_16x16x32_bf16 v[36:39], v[204:207], v[152:155], v[36:39]
	v_mfma_f32_16x16x32_bf16 v[20:23], v[204:207], v[176:179], 0
	v_mfma_f32_16x16x32_bf16 v[20:23], v[208:211], v[180:183], v[20:23]
	v_mfma_f32_16x16x32_bf16 v[12:15], v[216:219], v[180:183], 0
	v_mfma_f32_16x16x32_bf16 v[12:15], v[212:215], v[176:179], v[12:15]
	v_mfma_f32_16x16x32_bf16 v[0:3], v[212:215], v[196:199], 0
	v_mfma_f32_16x16x32_bf16 v[0:3], v[216:219], v[200:203], v[0:3]
	v_mfma_f32_16x16x32_bf16 v[4:7], v[208:211], v[200:203], 0
	v_mfma_f32_16x16x32_bf16 v[4:7], v[204:207], v[196:199], v[4:7]
	s_barrier
	s_add_i32 s47, 0, 0x18000
	ds_read_b128 v[128:131], v252
	ds_read_b128 v[132:135], v252 offset:1024
	ds_read_b128 v[136:139], v252 offset:2048
	ds_read_b128 v[140:143], v252 offset:3072
	s_add_u32 s24, s24, 0x100000
	s_addc_u32 s25, s25, 0
	s_mov_b32 m0, s40
	ds_read_b128 v[144:147], v194 offset:32768
	ds_read_b128 v[148:151], v194 offset:33792
	ds_read_b128 v[152:155], v194 offset:34816
	ds_read_b128 v[156:159], v194 offset:35840
	ds_read_b128 v[176:179], v194 offset:36864
	ds_read_b128 v[180:183], v194 offset:37888
	ds_read_b128 v[196:199], v194 offset:38912
	ds_read_b128 v[200:203], v194 offset:39936
	global_load_lds_dwordx4 v160, s[24:25]
	s_mov_b32 m0, s41
	s_nop 0
	global_load_lds_dwordx4 v164, s[24:25]
	s_waitcnt lgkmcnt(8)
	s_barrier
	s_waitcnt lgkmcnt(6)
	v_mfma_f32_16x16x32_bf16 v[124:127], v[128:131], v[144:147], v[124:127]
	v_mfma_f32_16x16x32_bf16 v[124:127], v[132:135], v[148:151], v[124:127]
	v_mfma_f32_16x16x32_bf16 v[120:123], v[140:143], v[148:151], v[120:123]
	v_mfma_f32_16x16x32_bf16 v[120:123], v[136:139], v[144:147], v[120:123]
	s_waitcnt lgkmcnt(4)
	v_mfma_f32_16x16x32_bf16 v[104:107], v[136:139], v[152:155], v[104:107]
	v_mfma_f32_16x16x32_bf16 v[104:107], v[140:143], v[156:159], v[104:107]
	v_mfma_f32_16x16x32_bf16 v[112:115], v[132:135], v[156:159], v[112:115]
	v_mfma_f32_16x16x32_bf16 v[112:115], v[128:131], v[152:155], v[112:115]
	s_waitcnt lgkmcnt(2)
	v_mfma_f32_16x16x32_bf16 v[92:95], v[128:131], v[176:179], v[92:95]
	v_mfma_f32_16x16x32_bf16 v[92:95], v[132:135], v[180:183], v[92:95]
	v_mfma_f32_16x16x32_bf16 v[88:91], v[140:143], v[180:183], v[88:91]
	v_mfma_f32_16x16x32_bf16 v[88:91], v[136:139], v[176:179], v[88:91]
	s_waitcnt lgkmcnt(0)
	v_mfma_f32_16x16x32_bf16 v[72:75], v[136:139], v[196:199], v[72:75]
	v_mfma_f32_16x16x32_bf16 v[72:75], v[140:143], v[200:203], v[72:75]
	v_mfma_f32_16x16x32_bf16 v[76:79], v[132:135], v[200:203], v[76:79]
	v_mfma_f32_16x16x32_bf16 v[76:79], v[128:131], v[196:199], v[76:79]
	s_barrier
	s_add_i32 s24, 0, 0x1c000
	s_add_i32 s25, s47, s34
	s_mov_b32 m0, s25
	ds_read_b128 v[204:207], v253
	ds_read_b128 v[208:211], v253 offset:1024
	ds_read_b128 v[212:215], v253 offset:2048
	ds_read_b128 v[216:219], v253 offset:3072
	global_load_lds_dwordx4 v162, s[90:91]
	s_add_i32 m0, s25, 0x2000
	s_nop 0
	global_load_lds_dwordx4 v166, s[90:91]
	s_barrier
	s_waitcnt lgkmcnt(0)
	v_mfma_f32_16x16x32_bf16 v[116:119], v[204:207], v[144:147], v[116:119]
	v_mfma_f32_16x16x32_bf16 v[116:119], v[208:211], v[148:151], v[116:119]
	v_mfma_f32_16x16x32_bf16 v[108:111], v[216:219], v[148:151], v[108:111]
	v_mfma_f32_16x16x32_bf16 v[108:111], v[212:215], v[144:147], v[108:111]
	v_mfma_f32_16x16x32_bf16 v[96:99], v[212:215], v[152:155], v[96:99]
	v_mfma_f32_16x16x32_bf16 v[96:99], v[216:219], v[156:159], v[96:99]
	v_mfma_f32_16x16x32_bf16 v[100:103], v[208:211], v[156:159], v[100:103]
	v_mfma_f32_16x16x32_bf16 v[100:103], v[204:207], v[152:155], v[100:103]
	v_mfma_f32_16x16x32_bf16 v[84:87], v[204:207], v[176:179], v[84:87]
	v_mfma_f32_16x16x32_bf16 v[84:87], v[208:211], v[180:183], v[84:87]
	v_mfma_f32_16x16x32_bf16 v[80:83], v[216:219], v[180:183], v[80:83]
	v_mfma_f32_16x16x32_bf16 v[80:83], v[212:215], v[176:179], v[80:83]
	v_mfma_f32_16x16x32_bf16 v[64:67], v[212:215], v[196:199], v[64:67]
	v_mfma_f32_16x16x32_bf16 v[64:67], v[216:219], v[200:203], v[64:67]
	v_mfma_f32_16x16x32_bf16 v[68:71], v[208:211], v[200:203], v[68:71]
	v_mfma_f32_16x16x32_bf16 v[68:71], v[204:207], v[196:199], v[68:71]
	s_barrier
	s_mov_b32 m0, s28
	ds_read_b128 v[144:147], v194 offset:49152
	ds_read_b128 v[148:151], v194 offset:50176
	ds_read_b128 v[152:155], v194 offset:51200
	ds_read_b128 v[156:159], v194 offset:52224
	ds_read_b128 v[176:179], v194 offset:53248
	ds_read_b128 v[180:183], v194 offset:54272
	ds_read_b128 v[196:199], v194 offset:55296
	ds_read_b128 v[200:203], v194 offset:56320
	global_load_lds_dwordx4 v160, s[92:93]
	s_mov_b32 m0, s29
	s_nop 0
	global_load_lds_dwordx4 v164, s[92:93]
	s_barrier
; #define PG8_STAGE(bufoff, gbase, voff) do { _Pragma("unroll") for (int _i = 0; _i < 2; ++_i) \
;         __builtin_amdgcn_global_load_lds((const unsigned*)((const char*)(gbase) + (voff)[_i]), (LAS unsigned*)(lds + (bufoff) + ldsw + _i * 8192), 16, 0, 0); } while (0)
; #define PG8_LDA(dst, b, h) do { _Pragma("unroll") for (int m = 0; m < 4; ++m) _Pragma("unroll") for (int k = 0; k < 2; ++k) dst[m][k] = *(const LAS bf16x8*)(lds + PG8_SA(b, h) + aoff + m * 2048 + k * 1024); } while (0)
; #define PG8_LDB(dst, b, h) do { _Pragma("unroll") for (int n = 0; n < 2; ++n) _Pragma("unroll") for (int k = 0; k < 2; ++k) dst[n][k] = *(const LAS bf16x8*)(lds + PG8_SB(b, h) + boff + n * 2048 + k * 1024); } while (0)
; #define PG8_MMA(ai, bj, At, Bt) do { __builtin_amdgcn_s_setprio(1); _Pragma("unroll") for (int m = 0; m < 4; ++m) _Pragma("unroll") for (int n = 0; n < 2; ++n) _Pragma("unroll") for (int k = 0; k < 2; ++k) \
;         acc[ai][bj][m][n] = __builtin_amdgcn_mfma_f32_16x16x32_bf16(Bt[n][k], At[m][k], acc[ai][bj][m][n], 0, 0, 0); __builtin_amdgcn_s_setprio(0); } while (0)
; #define PG8_WAIT_V(n) asm volatile("s_waitcnt vmcnt(" #n ")" ::: "memory")
; #define PG8_WAIT_L(n) asm volatile("s_waitcnt lgkmcnt(" #n ")" ::: "memory")
; #define PG8_BAR __builtin_amdgcn_s_barrier()
; #define PG8_SCHED __builtin_amdgcn_sched_barrier(0)
; template <class Epi, class Ptrs>
; __device__ __forceinline__ void gemm_phase(LAS unsigned char* lds, const int K, const StaticOrder& S, const Ptrs& P, const Epi& E) {
;     ...
;             PG8_LDB(B0, 0, 0); PG8_SCHED; PG8_LDA(At, 0, 0); PG8_STAGE(PG8_SA(1, 1), a1 + hstep, voffA);
;             PG8_WAIT_L(8); PG8_BAR; PG8_WAIT_L(0); PG8_MMA(0, 0, At, B0); PG8_BAR; PG8_SCHED;
;             PG8_LDB(B1, 0, 1); PG8_STAGE(PG8_SB(0, 0), b2, voffB);
;     ...
;             PG8_LDA(At, 1, 1); PG8_STAGE(PG8_SA(1, 0), a3, voffA);
;             PG8_BAR; PG8_WAIT_L(0); PG8_MMA(1, 0, At, B0); PG8_BAR; PG8_SCHED;
;             PG8_STAGE(PG8_SB(1, 1), b3 + hstep, voffB);
;             PG8_WAIT_V(6); PG8_BAR; PG8_MMA(1, 1, At, B1); PG8_BAR;
	s_waitcnt lgkmcnt(6)
	v_mfma_f32_16x16x32_bf16 v[60:63], v[128:131], v[144:147], v[60:63]
	v_mfma_f32_16x16x32_bf16 v[60:63], v[132:135], v[148:151], v[60:63]
	v_mfma_f32_16x16x32_bf16 v[56:59], v[140:143], v[148:151], v[56:59]
	v_mfma_f32_16x16x32_bf16 v[56:59], v[136:139], v[144:147], v[56:59]
	s_waitcnt lgkmcnt(4)
	v_mfma_f32_16x16x32_bf16 v[40:43], v[136:139], v[152:155], v[40:43]
	v_mfma_f32_16x16x32_bf16 v[40:43], v[140:143], v[156:159], v[40:43]
	v_mfma_f32_16x16x32_bf16 v[48:51], v[132:135], v[156:159], v[48:51]
	v_mfma_f32_16x16x32_bf16 v[48:51], v[128:131], v[152:155], v[48:51]
	s_waitcnt lgkmcnt(2)
	v_mfma_f32_16x16x32_bf16 v[32:35], v[128:131], v[176:179], v[32:35]
	v_mfma_f32_16x16x32_bf16 v[32:35], v[132:135], v[180:183], v[32:35]
	v_mfma_f32_16x16x32_bf16 v[24:27], v[140:143], v[180:183], v[24:27]
	v_mfma_f32_16x16x32_bf16 v[24:27], v[136:139], v[176:179], v[24:27]
	s_waitcnt lgkmcnt(0)
	v_mfma_f32_16x16x32_bf16 v[8:11], v[136:139], v[196:199], v[8:11]
	v_mfma_f32_16x16x32_bf16 v[8:11], v[140:143], v[200:203], v[8:11]
	v_mfma_f32_16x16x32_bf16 v[16:19], v[132:135], v[200:203], v[16:19]
	v_mfma_f32_16x16x32_bf16 v[16:19], v[128:131], v[196:199], v[16:19]
	s_barrier
	s_add_u32 s22, s22, 0x100080
	s_addc_u32 s23, s23, 0
	s_add_i32 s24, s24, s34
	s_mov_b32 m0, s24
	s_nop 0
	global_load_lds_dwordx4 v162, s[22:23]
	s_add_i32 m0, s24, 0x2000
	s_nop 0
	global_load_lds_dwordx4 v166, s[22:23]
	s_waitcnt vmcnt(6)
	s_barrier
	v_mfma_f32_16x16x32_bf16 v[52:55], v[204:207], v[144:147], v[52:55]
	v_mfma_f32_16x16x32_bf16 v[52:55], v[208:211], v[148:151], v[52:55]
	v_mfma_f32_16x16x32_bf16 v[44:47], v[216:219], v[148:151], v[44:47]
	v_mfma_f32_16x16x32_bf16 v[44:47], v[212:215], v[144:147], v[44:47]
	v_mfma_f32_16x16x32_bf16 v[28:31], v[212:215], v[152:155], v[28:31]
	v_mfma_f32_16x16x32_bf16 v[28:31], v[216:219], v[156:159], v[28:31]
	v_mfma_f32_16x16x32_bf16 v[36:39], v[208:211], v[156:159], v[36:39]
	v_mfma_f32_16x16x32_bf16 v[36:39], v[204:207], v[152:155], v[36:39]
	v_mfma_f32_16x16x32_bf16 v[20:23], v[204:207], v[176:179], v[20:23]
	v_mfma_f32_16x16x32_bf16 v[20:23], v[208:211], v[180:183], v[20:23]
	v_mfma_f32_16x16x32_bf16 v[12:15], v[216:219], v[180:183], v[12:15]
	v_mfma_f32_16x16x32_bf16 v[12:15], v[212:215], v[176:179], v[12:15]
	v_mfma_f32_16x16x32_bf16 v[0:3], v[212:215], v[196:199], v[0:3]
	v_mfma_f32_16x16x32_bf16 v[0:3], v[216:219], v[200:203], v[0:3]
	v_mfma_f32_16x16x32_bf16 v[4:7], v[208:211], v[200:203], v[4:7]
	v_mfma_f32_16x16x32_bf16 v[4:7], v[204:207], v[196:199], v[4:7]
	s_barrier
	s_add_i32 s46, s46, 2
	s_add_u32 s20, s20, 0x100
	s_addc_u32 s21, s21, 0
	s_add_u32 s11, s11, 0x100
	s_addc_u32 s13, s13, 0
	s_cmp_gt_u32 s46, 61
.LBB0_522:
	ds_read_b128 v[128:131], v193
	ds_read_b128 v[132:135], v193 offset:1024
	ds_read_b128 v[136:139], v193 offset:2048
	ds_read_b128 v[140:143], v193 offset:3072
	s_add_u32 s22, s20, 0xfff00080
	s_addc_u32 s23, s21, -1
	s_cmp_eq_u32 s46, 60
	s_cselect_b32 s25, s5, s23
	s_cselect_b32 s24, s4, s22
	s_cselect_b32 s23, s15, s13
	s_cselect_b32 s22, s14, s11
	s_add_i32 m0, s17, 0xc000
	ds_read_b128 v[144:147], v194
	ds_read_b128 v[148:151], v194 offset:1024
	ds_read_b128 v[152:155], v194 offset:2048
	ds_read_b128 v[156:159], v194 offset:3072
	ds_read_b128 v[176:179], v194 offset:4096
	ds_read_b128 v[180:183], v194 offset:5120
	ds_read_b128 v[196:199], v194 offset:6144
	ds_read_b128 v[200:203], v194 offset:7168
	global_load_lds_dwordx4 v168, s[20:21]
	s_add_i32 m0, s17, 0xe000
	s_nop 0
	global_load_lds_dwordx4 v170, s[20:21]
	s_waitcnt lgkmcnt(8)
	s_barrier
	s_waitcnt lgkmcnt(6)
	v_mfma_f32_16x16x32_bf16 v[124:127], v[128:131], v[144:147], v[124:127]
	v_mfma_f32_16x16x32_bf16 v[124:127], v[132:135], v[148:151], v[124:127]
	v_mfma_f32_16x16x32_bf16 v[120:123], v[140:143], v[148:151], v[120:123]
	v_mfma_f32_16x16x32_bf16 v[120:123], v[136:139], v[144:147], v[120:123]
	s_waitcnt lgkmcnt(4)
	v_mfma_f32_16x16x32_bf16 v[104:107], v[136:139], v[152:155], v[104:107]
	v_mfma_f32_16x16x32_bf16 v[104:107], v[140:143], v[156:159], v[104:107]
	v_mfma_f32_16x16x32_bf16 v[112:115], v[132:135], v[156:159], v[112:115]
	v_mfma_f32_16x16x32_bf16 v[112:115], v[128:131], v[152:155], v[112:115]
	s_waitcnt lgkmcnt(2)
	v_mfma_f32_16x16x32_bf16 v[92:95], v[128:131], v[176:179], v[92:95]
	v_mfma_f32_16x16x32_bf16 v[92:95], v[132:135], v[180:183], v[92:95]
	v_mfma_f32_16x16x32_bf16 v[88:91], v[140:143], v[180:183], v[88:91]
	v_mfma_f32_16x16x32_bf16 v[88:91], v[136:139], v[176:179], v[88:91]
	s_waitcnt lgkmcnt(0)
	v_mfma_f32_16x16x32_bf16 v[72:75], v[136:139], v[196:199], v[72:75]
	v_mfma_f32_16x16x32_bf16 v[72:75], v[140:143], v[200:203], v[72:75]
	v_mfma_f32_16x16x32_bf16 v[76:79], v[132:135], v[200:203], v[76:79]
	v_mfma_f32_16x16x32_bf16 v[76:79], v[128:131], v[196:199], v[76:79]
	s_barrier
	s_add_i32 s47, s42, s34
	s_add_u32 s90, s22, 0x80
	s_addc_u32 s91, s23, 0
	s_mov_b32 m0, s47
	ds_read_b128 v[204:207], v195
	ds_read_b128 v[208:211], v195 offset:1024
	ds_read_b128 v[212:215], v195 offset:2048
	ds_read_b128 v[216:219], v195 offset:3072
	global_load_lds_dwordx4 v162, s[22:23]
	s_add_i32 m0, s47, 0x2000
	s_nop 0
	global_load_lds_dwordx4 v166, s[22:23]
	s_barrier
; #define PG8_STAGE(bufoff, gbase, voff) do { _Pragma("unroll") for (int _i = 0; _i < 2; ++_i) \
;         __builtin_amdgcn_global_load_lds((const unsigned*)((const char*)(gbase) + (voff)[_i]), (LAS unsigned*)(lds + (bufoff) + ldsw + _i * 8192), 16, 0, 0); } while (0)
; #define PG8_LDA(dst, b, h) do { _Pragma("unroll") for (int m = 0; m < 4; ++m) _Pragma("unroll") for (int k = 0; k < 2; ++k) dst[m][k] = *(const LAS bf16x8*)(lds + PG8_SA(b, h) + aoff + m * 2048 + k * 1024); } while (0)
; #define PG8_LDB(dst, b, h) do { _Pragma("unroll") for (int n = 0; n < 2; ++n) _Pragma("unroll") for (int k = 0; k < 2; ++k) dst[n][k] = *(const LAS bf16x8*)(lds + PG8_SB(b, h) + boff + n * 2048 + k * 1024); } while (0)
; #define PG8_MMA(ai, bj, At, Bt) do { __builtin_amdgcn_s_setprio(1); _Pragma("unroll") for (int m = 0; m < 4; ++m) _Pragma("unroll") for (int n = 0; n < 2; ++n) _Pragma("unroll") for (int k = 0; k < 2; ++k) \
;         acc[ai][bj][m][n] = __builtin_amdgcn_mfma_f32_16x16x32_bf16(Bt[n][k], At[m][k], acc[ai][bj][m][n], 0, 0, 0); __builtin_amdgcn_s_setprio(0); } while (0)
; #define PG8_WAIT_V(n) asm volatile("s_waitcnt vmcnt(" #n ")" ::: "memory")
; #define PG8_WAIT_L(n) asm volatile("s_waitcnt lgkmcnt(" #n ")" ::: "memory")
; #define PG8_BAR __builtin_amdgcn_s_barrier()
; #define PG8_SCHED __builtin_amdgcn_sched_barrier(0)
; template <class Epi, class Ptrs>
; __device__ __forceinline__ void gemm_phase(LAS unsigned char* lds, const int K, const StaticOrder& S, const Ptrs& P, const Epi& E) {
;     ...
;             PG8_BAR; PG8_WAIT_L(0); PG8_MMA(0, 1, At, B1); PG8_BAR;
;             PG8_LDA(At, 0, 1); PG8_STAGE(PG8_SA(0, 0), a2, voffA);
;             PG8_BAR; PG8_WAIT_L(0); PG8_MMA(1, 0, At, B0); PG8_BAR; PG8_SCHED;
;             PG8_STAGE(PG8_SB(0, 1), b2 + hstep, voffB);
;             PG8_WAIT_V(6); PG8_BAR; PG8_MMA(1, 1, At, B1); PG8_BAR;
;             PG8_LDB(B0, 1, 0); PG8_SCHED; PG8_LDA(At, 1, 0); PG8_STAGE(PG8_SA(0, 1), a2 + hstep, voffA);
;             PG8_WAIT_L(8); PG8_BAR; PG8_WAIT_L(0); PG8_MMA(0, 0, At, B0); PG8_BAR; PG8_SCHED;
	s_waitcnt lgkmcnt(0)
	v_mfma_f32_16x16x32_bf16 v[116:119], v[204:207], v[144:147], v[116:119]
	v_mfma_f32_16x16x32_bf16 v[116:119], v[208:211], v[148:151], v[116:119]
	v_mfma_f32_16x16x32_bf16 v[108:111], v[216:219], v[148:151], v[108:111]
	v_mfma_f32_16x16x32_bf16 v[108:111], v[212:215], v[144:147], v[108:111]
	v_mfma_f32_16x16x32_bf16 v[96:99], v[212:215], v[152:155], v[96:99]
	v_mfma_f32_16x16x32_bf16 v[96:99], v[216:219], v[156:159], v[96:99]
	v_mfma_f32_16x16x32_bf16 v[100:103], v[208:211], v[156:159], v[100:103]
	v_mfma_f32_16x16x32_bf16 v[100:103], v[204:207], v[152:155], v[100:103]
	v_mfma_f32_16x16x32_bf16 v[84:87], v[204:207], v[176:179], v[84:87]
	v_mfma_f32_16x16x32_bf16 v[84:87], v[208:211], v[180:183], v[84:87]
	v_mfma_f32_16x16x32_bf16 v[80:83], v[216:219], v[180:183], v[80:83]
	v_mfma_f32_16x16x32_bf16 v[80:83], v[212:215], v[176:179], v[80:83]
	v_mfma_f32_16x16x32_bf16 v[64:67], v[212:215], v[196:199], v[64:67]
	v_mfma_f32_16x16x32_bf16 v[64:67], v[216:219], v[200:203], v[64:67]
	v_mfma_f32_16x16x32_bf16 v[68:71], v[208:211], v[200:203], v[68:71]
	v_mfma_f32_16x16x32_bf16 v[68:71], v[204:207], v[196:199], v[68:71]
	s_barrier
	s_mov_b32 m0, s17
	s_add_u32 s92, s24, 0x80
	s_addc_u32 s93, s25, 0
	ds_read_b128 v[144:147], v194 offset:16384
	ds_read_b128 v[148:151], v194 offset:17408
	ds_read_b128 v[152:155], v194 offset:18432
	ds_read_b128 v[156:159], v194 offset:19456
	ds_read_b128 v[176:179], v194 offset:20480
	ds_read_b128 v[180:183], v194 offset:21504
	ds_read_b128 v[196:199], v194 offset:22528
	ds_read_b128 v[200:203], v194 offset:23552
	global_load_lds_dwordx4 v160, s[24:25]
	s_mov_b32 m0, s19
	s_nop 0
	global_load_lds_dwordx4 v164, s[24:25]
	s_barrier
	s_waitcnt lgkmcnt(6)
	v_mfma_f32_16x16x32_bf16 v[60:63], v[128:131], v[144:147], v[60:63]
	v_mfma_f32_16x16x32_bf16 v[60:63], v[132:135], v[148:151], v[60:63]
	v_mfma_f32_16x16x32_bf16 v[56:59], v[140:143], v[148:151], v[56:59]
	v_mfma_f32_16x16x32_bf16 v[56:59], v[136:139], v[144:147], v[56:59]
	s_waitcnt lgkmcnt(4)
	v_mfma_f32_16x16x32_bf16 v[40:43], v[136:139], v[152:155], v[40:43]
	v_mfma_f32_16x16x32_bf16 v[40:43], v[140:143], v[156:159], v[40:43]
	v_mfma_f32_16x16x32_bf16 v[48:51], v[132:135], v[156:159], v[48:51]
	v_mfma_f32_16x16x32_bf16 v[48:51], v[128:131], v[152:155], v[48:51]
	s_waitcnt lgkmcnt(2)
	v_mfma_f32_16x16x32_bf16 v[32:35], v[128:131], v[176:179], v[32:35]
	v_mfma_f32_16x16x32_bf16 v[32:35], v[132:135], v[180:183], v[32:35]
	v_mfma_f32_16x16x32_bf16 v[24:27], v[140:143], v[180:183], v[24:27]
	v_mfma_f32_16x16x32_bf16 v[24:27], v[136:139], v[176:179], v[24:27]
	s_waitcnt lgkmcnt(0)
	v_mfma_f32_16x16x32_bf16 v[8:11], v[136:139], v[196:199], v[8:11]
	v_mfma_f32_16x16x32_bf16 v[8:11], v[140:143], v[200:203], v[8:11]
	v_mfma_f32_16x16x32_bf16 v[16:19], v[132:135], v[200:203], v[16:19]
	v_mfma_f32_16x16x32_bf16 v[16:19], v[128:131], v[196:199], v[16:19]
	s_barrier
	s_add_u32 s48, s22, 0x100000
	s_addc_u32 s49, s23, 0
	s_add_i32 s47, s43, s34
	s_mov_b32 m0, s47
	s_nop 0
	global_load_lds_dwordx4 v162, s[48:49]
	s_add_i32 m0, s47, 0x2000
	s_nop 0
	global_load_lds_dwordx4 v166, s[48:49]
	s_waitcnt vmcnt(6)
	s_barrier
	v_mfma_f32_16x16x32_bf16 v[52:55], v[204:207], v[144:147], v[52:55]
	v_mfma_f32_16x16x32_bf16 v[52:55], v[208:211], v[148:151], v[52:55]
	v_mfma_f32_16x16x32_bf16 v[44:47], v[216:219], v[148:151], v[44:47]
	v_mfma_f32_16x16x32_bf16 v[44:47], v[212:215], v[144:147], v[44:47]
	v_mfma_f32_16x16x32_bf16 v[28:31], v[212:215], v[152:155], v[28:31]
	v_mfma_f32_16x16x32_bf16 v[28:31], v[216:219], v[156:159], v[28:31]
	v_mfma_f32_16x16x32_bf16 v[36:39], v[208:211], v[156:159], v[36:39]
	v_mfma_f32_16x16x32_bf16 v[36:39], v[204:207], v[152:155], v[36:39]
	v_mfma_f32_16x16x32_bf16 v[20:23], v[204:207], v[176:179], v[20:23]
	v_mfma_f32_16x16x32_bf16 v[20:23], v[208:211], v[180:183], v[20:23]
	v_mfma_f32_16x16x32_bf16 v[12:15], v[216:219], v[180:183], v[12:15]
	v_mfma_f32_16x16x32_bf16 v[12:15], v[212:215], v[176:179], v[12:15]
	v_mfma_f32_16x16x32_bf16 v[0:3], v[212:215], v[196:199], v[0:3]
	v_mfma_f32_16x16x32_bf16 v[0:3], v[216:219], v[200:203], v[0:3]
	v_mfma_f32_16x16x32_bf16 v[4:7], v[208:211], v[200:203], v[4:7]
	v_mfma_f32_16x16x32_bf16 v[4:7], v[204:207], v[196:199], v[4:7]
	s_barrier
	s_add_i32 s47, 0, 0x18000
	ds_read_b128 v[128:131], v252
	ds_read_b128 v[132:135], v252 offset:1024
	ds_read_b128 v[136:139], v252 offset:2048
	ds_read_b128 v[140:143], v252 offset:3072
	s_add_u32 s24, s24, 0x100000
	s_addc_u32 s25, s25, 0
	s_mov_b32 m0, s40
	ds_read_b128 v[144:147], v194 offset:32768
	ds_read_b128 v[148:151], v194 offset:33792
	ds_read_b128 v[152:155], v194 offset:34816
	ds_read_b128 v[156:159], v194 offset:35840
	ds_read_b128 v[176:179], v194 offset:36864
	ds_read_b128 v[180:183], v194 offset:37888
	ds_read_b128 v[196:199], v194 offset:38912
	ds_read_b128 v[200:203], v194 offset:39936
	global_load_lds_dwordx4 v160, s[24:25]
	s_mov_b32 m0, s41
	s_nop 0
	global_load_lds_dwordx4 v164, s[24:25]
	s_waitcnt lgkmcnt(8)
	s_barrier
	s_waitcnt lgkmcnt(6)
	v_mfma_f32_16x16x32_bf16 v[124:127], v[128:131], v[144:147], v[124:127]
	v_mfma_f32_16x16x32_bf16 v[124:127], v[132:135], v[148:151], v[124:127]
	v_mfma_f32_16x16x32_bf16 v[120:123], v[140:143], v[148:151], v[120:123]
	v_mfma_f32_16x16x32_bf16 v[120:123], v[136:139], v[144:147], v[120:123]
	s_waitcnt lgkmcnt(4)
	v_mfma_f32_16x16x32_bf16 v[104:107], v[136:139], v[152:155], v[104:107]
	v_mfma_f32_16x16x32_bf16 v[104:107], v[140:143], v[156:159], v[104:107]
	v_mfma_f32_16x16x32_bf16 v[112:115], v[132:135], v[156:159], v[112:115]
	v_mfma_f32_16x16x32_bf16 v[112:115], v[128:131], v[152:155], v[112:115]
	s_waitcnt lgkmcnt(2)
	v_mfma_f32_16x16x32_bf16 v[92:95], v[128:131], v[176:179], v[92:95]
	v_mfma_f32_16x16x32_bf16 v[92:95], v[132:135], v[180:183], v[92:95]
	v_mfma_f32_16x16x32_bf16 v[88:91], v[140:143], v[180:183], v[88:91]
	v_mfma_f32_16x16x32_bf16 v[88:91], v[136:139], v[176:179], v[88:91]
	s_waitcnt lgkmcnt(0)
	v_mfma_f32_16x16x32_bf16 v[72:75], v[136:139], v[196:199], v[72:75]
	v_mfma_f32_16x16x32_bf16 v[72:75], v[140:143], v[200:203], v[72:75]
	v_mfma_f32_16x16x32_bf16 v[76:79], v[132:135], v[200:203], v[76:79]
	v_mfma_f32_16x16x32_bf16 v[76:79], v[128:131], v[196:199], v[76:79]
	s_barrier
; #define PG8_STAGE(bufoff, gbase, voff) do { _Pragma("unroll") for (int _i = 0; _i < 2; ++_i) \
;         __builtin_amdgcn_global_load_lds((const unsigned*)((const char*)(gbase) + (voff)[_i]), (LAS unsigned*)(lds + (bufoff) + ldsw + _i * 8192), 16, 0, 0); } while (0)
; #define PG8_LDA(dst, b, h) do { _Pragma("unroll") for (int m = 0; m < 4; ++m) _Pragma("unroll") for (int k = 0; k < 2; ++k) dst[m][k] = *(const LAS bf16x8*)(lds + PG8_SA(b, h) + aoff + m * 2048 + k * 1024); } while (0)
; #define PG8_LDB(dst, b, h) do { _Pragma("unroll") for (int n = 0; n < 2; ++n) _Pragma("unroll") for (int k = 0; k < 2; ++k) dst[n][k] = *(const LAS bf16x8*)(lds + PG8_SB(b, h) + boff + n * 2048 + k * 1024); } while (0)
; #define PG8_MMA(ai, bj, At, Bt) do { __builtin_amdgcn_s_setprio(1); _Pragma("unroll") for (int m = 0; m < 4; ++m) _Pragma("unroll") for (int n = 0; n < 2; ++n) _Pragma("unroll") for (int k = 0; k < 2; ++k) \
;         acc[ai][bj][m][n] = __builtin_amdgcn_mfma_f32_16x16x32_bf16(Bt[n][k], At[m][k], acc[ai][bj][m][n], 0, 0, 0); __builtin_amdgcn_s_setprio(0); } while (0)
; #define PG8_WAIT_V(n) asm volatile("s_waitcnt vmcnt(" #n ")" ::: "memory")
; #define PG8_WAIT_L(n) asm volatile("s_waitcnt lgkmcnt(" #n ")" ::: "memory")
; #define PG8_BAR __builtin_amdgcn_s_barrier()
; #define PG8_SCHED __builtin_amdgcn_sched_barrier(0)
; template <class Epi, class Ptrs>
; __device__ __forceinline__ void gemm_phase(LAS unsigned char* lds, const int K, const StaticOrder& S, const Ptrs& P, const Epi& E) {
;     ...
;             PG8_LDB(B1, 1, 1); PG8_STAGE(PG8_SB(1, 0), b3, voffB);
;             PG8_BAR; PG8_WAIT_L(0); PG8_MMA(0, 1, At, B1); PG8_BAR;
;             PG8_LDA(At, 1, 1); PG8_STAGE(PG8_SA(1, 0), a3, voffA);
;             PG8_BAR; PG8_WAIT_L(0); PG8_MMA(1, 0, At, B0); PG8_BAR; PG8_SCHED;
;             PG8_STAGE(PG8_SB(1, 1), b3 + hstep, voffB);
;             PG8_WAIT_V(6); PG8_BAR; PG8_MMA(1, 1, At, B1); PG8_BAR;
	s_add_i32 s24, 0, 0x1c000
	s_add_i32 s25, s47, s34
	s_mov_b32 m0, s25
	ds_read_b128 v[204:207], v253
	ds_read_b128 v[208:211], v253 offset:1024
	ds_read_b128 v[212:215], v253 offset:2048
	ds_read_b128 v[216:219], v253 offset:3072
	global_load_lds_dwordx4 v162, s[90:91]
	s_add_i32 m0, s25, 0x2000
	s_nop 0
	global_load_lds_dwordx4 v166, s[90:91]
	s_barrier
	s_waitcnt lgkmcnt(0)
	v_mfma_f32_16x16x32_bf16 v[116:119], v[204:207], v[144:147], v[116:119]
	v_mfma_f32_16x16x32_bf16 v[116:119], v[208:211], v[148:151], v[116:119]
	v_mfma_f32_16x16x32_bf16 v[108:111], v[216:219], v[148:151], v[108:111]
	v_mfma_f32_16x16x32_bf16 v[108:111], v[212:215], v[144:147], v[108:111]
	v_mfma_f32_16x16x32_bf16 v[96:99], v[212:215], v[152:155], v[96:99]
	v_mfma_f32_16x16x32_bf16 v[96:99], v[216:219], v[156:159], v[96:99]
	v_mfma_f32_16x16x32_bf16 v[100:103], v[208:211], v[156:159], v[100:103]
	v_mfma_f32_16x16x32_bf16 v[100:103], v[204:207], v[152:155], v[100:103]
	v_mfma_f32_16x16x32_bf16 v[84:87], v[204:207], v[176:179], v[84:87]
	v_mfma_f32_16x16x32_bf16 v[84:87], v[208:211], v[180:183], v[84:87]
	v_mfma_f32_16x16x32_bf16 v[80:83], v[216:219], v[180:183], v[80:83]
	v_mfma_f32_16x16x32_bf16 v[80:83], v[212:215], v[176:179], v[80:83]
	v_mfma_f32_16x16x32_bf16 v[64:67], v[212:215], v[196:199], v[64:67]
	v_mfma_f32_16x16x32_bf16 v[64:67], v[216:219], v[200:203], v[64:67]
	v_mfma_f32_16x16x32_bf16 v[68:71], v[208:211], v[200:203], v[68:71]
	v_mfma_f32_16x16x32_bf16 v[68:71], v[204:207], v[196:199], v[68:71]
	s_barrier
	s_mov_b32 m0, s28
	ds_read_b128 v[144:147], v194 offset:49152
	ds_read_b128 v[148:151], v194 offset:50176
	ds_read_b128 v[152:155], v194 offset:51200
	ds_read_b128 v[156:159], v194 offset:52224
	ds_read_b128 v[176:179], v194 offset:53248
	ds_read_b128 v[180:183], v194 offset:54272
	ds_read_b128 v[196:199], v194 offset:55296
	ds_read_b128 v[200:203], v194 offset:56320
	global_load_lds_dwordx4 v160, s[92:93]
	s_mov_b32 m0, s29
	s_nop 0
	global_load_lds_dwordx4 v164, s[92:93]
	s_barrier
	s_waitcnt lgkmcnt(6)
	v_mfma_f32_16x16x32_bf16 v[60:63], v[128:131], v[144:147], v[60:63]
	v_mfma_f32_16x16x32_bf16 v[60:63], v[132:135], v[148:151], v[60:63]
	v_mfma_f32_16x16x32_bf16 v[56:59], v[140:143], v[148:151], v[56:59]
	v_mfma_f32_16x16x32_bf16 v[56:59], v[136:139], v[144:147], v[56:59]
	s_waitcnt lgkmcnt(4)
	v_mfma_f32_16x16x32_bf16 v[40:43], v[136:139], v[152:155], v[40:43]
	v_mfma_f32_16x16x32_bf16 v[40:43], v[140:143], v[156:159], v[40:43]
	v_mfma_f32_16x16x32_bf16 v[48:51], v[132:135], v[156:159], v[48:51]
	v_mfma_f32_16x16x32_bf16 v[48:51], v[128:131], v[152:155], v[48:51]
	s_waitcnt lgkmcnt(2)
	v_mfma_f32_16x16x32_bf16 v[32:35], v[128:131], v[176:179], v[32:35]
	v_mfma_f32_16x16x32_bf16 v[32:35], v[132:135], v[180:183], v[32:35]
	v_mfma_f32_16x16x32_bf16 v[24:27], v[140:143], v[180:183], v[24:27]
	v_mfma_f32_16x16x32_bf16 v[24:27], v[136:139], v[176:179], v[24:27]
	s_waitcnt lgkmcnt(0)
	v_mfma_f32_16x16x32_bf16 v[8:11], v[136:139], v[196:199], v[8:11]
	v_mfma_f32_16x16x32_bf16 v[8:11], v[140:143], v[200:203], v[8:11]
	v_mfma_f32_16x16x32_bf16 v[16:19], v[132:135], v[200:203], v[16:19]
	v_mfma_f32_16x16x32_bf16 v[16:19], v[128:131], v[196:199], v[16:19]
	s_barrier
	s_add_u32 s22, s22, 0x100080
	s_addc_u32 s23, s23, 0
	s_add_i32 s24, s24, s34
	s_mov_b32 m0, s24
	s_nop 0
	global_load_lds_dwordx4 v162, s[22:23]
	s_add_i32 m0, s24, 0x2000
	s_nop 0
	global_load_lds_dwordx4 v166, s[22:23]
	s_waitcnt vmcnt(6)
	s_barrier
	v_mfma_f32_16x16x32_bf16 v[52:55], v[204:207], v[144:147], v[52:55]
	v_mfma_f32_16x16x32_bf16 v[52:55], v[208:211], v[148:151], v[52:55]
	v_mfma_f32_16x16x32_bf16 v[44:47], v[216:219], v[148:151], v[44:47]
	v_mfma_f32_16x16x32_bf16 v[44:47], v[212:215], v[144:147], v[44:47]
	v_mfma_f32_16x16x32_bf16 v[28:31], v[212:215], v[152:155], v[28:31]
	v_mfma_f32_16x16x32_bf16 v[28:31], v[216:219], v[156:159], v[28:31]
	v_mfma_f32_16x16x32_bf16 v[36:39], v[208:211], v[156:159], v[36:39]
	v_mfma_f32_16x16x32_bf16 v[36:39], v[204:207], v[152:155], v[36:39]
	v_mfma_f32_16x16x32_bf16 v[20:23], v[204:207], v[176:179], v[20:23]
	v_mfma_f32_16x16x32_bf16 v[20:23], v[208:211], v[180:183], v[20:23]
	v_mfma_f32_16x16x32_bf16 v[12:15], v[216:219], v[180:183], v[12:15]
	v_mfma_f32_16x16x32_bf16 v[12:15], v[212:215], v[176:179], v[12:15]
	v_mfma_f32_16x16x32_bf16 v[0:3], v[212:215], v[196:199], v[0:3]
	v_mfma_f32_16x16x32_bf16 v[0:3], v[216:219], v[200:203], v[0:3]
	v_mfma_f32_16x16x32_bf16 v[4:7], v[208:211], v[200:203], v[4:7]
	v_mfma_f32_16x16x32_bf16 v[4:7], v[204:207], v[196:199], v[4:7]
	s_barrier
	s_add_i32 s46, s46, 2
	s_add_u32 s20, s20, 0x100
	s_addc_u32 s21, s21, 0
	s_add_u32 s11, s11, 0x100
	s_addc_u32 s13, s13, 0
	s_cmp_gt_u32 s46, 61
	s_cbranch_scc0 .LBB0_522
; __device__ __forceinline__ float bf_lo(unsigned w) { return __uint_as_float(w << 16); }
; __device__ __forceinline__ float bf_hi(unsigned w) { return __uint_as_float(w & 0xffff0000u); }
;     __device__ __forceinline__ void operator()(const f32x4 (&acc)[2][2][4][2], const Unit& u, int ui, int wr, int wc, int fr, int fq) const {
;         const int rl0 = wr * 64 + fr, col0 = u.pn * 256 + wc * 32 + 8 * fq;
;         u32x4 xv[2][4][2];
; #pragma unroll
;         for (int ai = 0; ai < 2; ++ai)
; #pragma unroll
;             for (int m = 0; m < 4; ++m)
; #pragma unroll
;                 for (int bj = 0; bj < 2; ++bj) xv[ai][m][bj] = *(const u32x4*)(xb + (size_t)(u.pm * 256 + rl0 + ai * 128 + m * 16) * DM + col0 + bj * 128);
; #pragma unroll
;         for (int ai = 0; ai < 2; ++ai)
; #pragma unroll
;             for (int m = 0; m < 4; ++m) { const int rl = rl0 + ai * 128 + m * 16; float* rowp = out + (size_t)(u.pm * 256 + rl) * DM + col0;
;                 const float r2 = tab[ui * 256 + rl];
; #pragma unroll
;                 for (int bj = 0; bj < 2; ++bj) { const u32x4 x = xv[ai][m][bj];
;                     const f32x4 x0 = {bf_lo(x.x), bf_hi(x.x), bf_lo(x.y), bf_hi(x.y)}, x1 = {bf_lo(x.z), bf_hi(x.z), bf_lo(x.w), bf_hi(x.w)};
;                     *(f32x4*)(rowp + bj * 128) = acc[ai][bj][m][0] * r2 + x0; *(f32x4*)(rowp + bj * 128 + 4) = acc[ai][bj][m][1] * r2 + x1; } }
	s_lshl_b32 s11, s18, 8
	v_lshl_or_b32 v128, s16, 8, v191
	v_add_u32_e32 v130, s11, v186
	v_ashrrev_i32_e32 v129, 31, v128
	v_ashrrev_i32_e32 v131, 31, v130
	v_lshl_add_u64 v[132:133], v[128:129], 1, s[6:7]
	v_lshlrev_b64 v[134:135], 11, v[130:131]
	v_lshl_add_u64 v[134:135], v[132:133], 0, v[134:135]
	global_load_dwordx4 v[198:201], v[134:135], off
	global_load_dwordx4 v[202:205], v[134:135], off offset:256
	v_or_b32_e32 v134, 16, v130
	v_ashrrev_i32_e32 v135, 31, v134
	v_lshlrev_b64 v[134:135], 11, v[134:135]
	v_lshl_add_u64 v[134:135], v[132:133], 0, v[134:135]
	global_load_dwordx4 v[206:209], v[134:135], off
	global_load_dwordx4 v[210:213], v[134:135], off offset:256
	v_or_b32_e32 v136, 32, v130
	v_ashrrev_i32_e32 v137, 31, v136
	v_or_b32_e32 v138, 48, v130
	v_add_u32_e32 v184, 0x80, v130
	v_add_u32_e32 v182, 0x90, v130
	v_add_u32_e32 v180, 0xa0, v130
	v_add_u32_e32 v178, 0xb0, v130
	v_lshlrev_b64 v[176:177], 2, v[128:129]
	v_lshlrev_b64 v[128:129], 12, v[130:131]
	v_lshlrev_b64 v[130:131], 11, v[136:137]
	v_lshl_add_u64 v[130:131], v[132:133], 0, v[130:131]
	global_load_dwordx4 v[214:217], v[130:131], off
	v_ashrrev_i32_e32 v139, 31, v138
	v_ashrrev_i32_e32 v185, 31, v184
	v_ashrrev_i32_e32 v183, 31, v182
	v_ashrrev_i32_e32 v181, 31, v180
	v_ashrrev_i32_e32 v179, 31, v178
	v_lshlrev_b64 v[134:135], 11, v[138:139]
	v_lshlrev_b64 v[136:137], 11, v[184:185]
	v_lshlrev_b64 v[138:139], 11, v[182:183]
	v_lshl_add_u32 v196, s45, 10, v192
	v_lshlrev_b64 v[140:141], 11, v[180:181]
	v_lshlrev_b64 v[142:143], 11, v[178:179]
	v_lshl_add_u64 v[128:129], s[26:27], 0, v[128:129]
	v_lshl_add_u64 v[134:135], v[132:133], 0, v[134:135]
	v_lshl_add_u64 v[136:137], v[132:133], 0, v[136:137]
	v_lshl_add_u64 v[138:139], v[132:133], 0, v[138:139]
	ds_read2_b32 v[230:231], v196 offset1:16
	v_lshl_add_u64 v[234:235], v[132:133], 0, v[140:141]
	v_lshl_add_u64 v[236:237], v[132:133], 0, v[142:143]
	v_lshl_add_u64 v[238:239], v[128:129], 0, v[176:177]
	global_load_dwordx4 v[218:221], v[130:131], off offset:256
	global_load_dwordx4 v[222:225], v[134:135], off
	global_load_dwordx4 v[226:229], v[134:135], off offset:256
	global_load_dwordx4 v[156:159], v[136:137], off
	global_load_dwordx4 v[152:155], v[136:137], off offset:256
	global_load_dwordx4 v[148:151], v[138:139], off
	global_load_dwordx4 v[144:147], v[138:139], off offset:256
	global_load_dwordx4 v[140:143], v[234:235], off
	s_nop 0
	global_load_dwordx4 v[136:139], v[234:235], off offset:256
	global_load_dwordx4 v[132:135], v[236:237], off
	global_load_dwordx4 v[128:131], v[236:237], off offset:256
	v_add_u32_e32 v232, s11, v188
	v_ashrrev_i32_e32 v233, 31, v232
	s_and_b64 vcc, exec, s[0:1]
	s_mov_b32 s16, s10
	s_mov_b32 s18, s12
	s_mov_b64 s[20:21], s[4:5]
	s_mov_b64 s[22:23], s[14:15]
	s_mov_b32 s45, s44
	s_waitcnt vmcnt(0)
	v_lshlrev_b32_e32 v234, 16, v198
	v_and_b32_e32 v235, 0xffff0000, v198
	v_lshlrev_b32_e32 v198, 16, v199
	v_and_b32_e32 v199, 0xffff0000, v199
	v_lshlrev_b32_e32 v242, 16, v204
	v_and_b32_e32 v243, 0xffff0000, v204
	v_lshlrev_b32_e32 v236, 16, v200
	v_and_b32_e32 v237, 0xffff0000, v200
	v_lshlrev_b32_e32 v200, 16, v201
	v_and_b32_e32 v201, 0xffff0000, v201
	v_lshlrev_b32_e32 v240, 16, v202
	v_and_b32_e32 v241, 0xffff0000, v202
	v_lshlrev_b32_e32 v202, 16, v203
	v_and_b32_e32 v203, 0xffff0000, v203
	v_lshlrev_b32_e32 v204, 16, v205
	v_and_b32_e32 v205, 0xffff0000, v205
	s_waitcnt lgkmcnt(0)
	v_pk_fma_f32 v[126:127], v[126:127], v[230:231], v[198:199] op_sel_hi:[1,0,1]
	v_pk_fma_f32 v[124:125], v[124:125], v[230:231], v[234:235] op_sel_hi:[1,0,1]
	v_pk_fma_f32 v[108:109], v[108:109], v[230:231], v[242:243] op_sel_hi:[1,0,1]
	v_pk_fma_f32 v[122:123], v[122:123], v[230:231], v[200:201] op_sel_hi:[1,0,1]
	v_pk_fma_f32 v[120:121], v[120:121], v[230:231], v[236:237] op_sel_hi:[1,0,1]
	v_pk_fma_f32 v[118:119], v[118:119], v[230:231], v[202:203] op_sel_hi:[1,0,1]
	v_pk_fma_f32 v[116:117], v[116:117], v[230:231], v[240:241] op_sel_hi:[1,0,1]
	v_pk_fma_f32 v[110:111], v[110:111], v[230:231], v[204:205] op_sel_hi:[1,0,1]
	global_store_dwordx4 v[238:239], v[124:127], off
	global_store_dwordx4 v[238:239], v[120:123], off offset:16
	global_store_dwordx4 v[238:239], v[116:119], off offset:512
	global_store_dwordx4 v[238:239], v[108:111], off offset:528
	v_mov_b32_e32 v122, v231
	v_lshlrev_b32_e32 v118, 16, v208
	v_lshlrev_b64 v[108:109], 12, v[232:233]
	v_lshl_add_u64 v[108:109], s[26:27], 0, v[108:109]
	v_lshl_add_u64 v[116:117], v[108:109], 0, v[176:177]
	v_lshlrev_b32_e32 v108, 16, v206
	v_and_b32_e32 v109, 0xffff0000, v206
	v_lshlrev_b32_e32 v110, 16, v207
	v_and_b32_e32 v111, 0xffff0000, v207
	v_pk_fma_f32 v[110:111], v[114:115], v[122:123], v[110:111] op_sel_hi:[1,0,1]
	v_pk_fma_f32 v[108:109], v[112:113], v[122:123], v[108:109] op_sel_hi:[1,0,1]
	global_store_dwordx4 v[116:117], v[108:111], off
	v_and_b32_e32 v119, 0xffff0000, v208
	v_lshlrev_b32_e32 v120, 16, v209
	v_lshlrev_b32_e32 v108, 16, v212
	v_and_b32_e32 v109, 0xffff0000, v212
	v_lshlrev_b32_e32 v110, 16, v213
	v_and_b32_e32 v111, 0xffff0000, v213
	v_pk_fma_f32 v[98:99], v[98:99], v[122:123], v[110:111] op_sel_hi:[1,0,1]
	v_pk_fma_f32 v[96:97], v[96:97], v[122:123], v[108:109] op_sel_hi:[1,0,1]
	v_and_b32_e32 v121, 0xffff0000, v209
	global_store_dwordx4 v[116:117], v[96:99], off offset:528
	ds_read2_b32 v[98:99], v196 offset0:32 offset1:48
	v_pk_fma_f32 v[106:107], v[106:107], v[122:123], v[120:121] op_sel_hi:[1,0,1]
	v_pk_fma_f32 v[104:105], v[104:105], v[122:123], v[118:119] op_sel_hi:[1,0,1]
	v_add_u32_e32 v96, s11, v189
	global_store_dwordx4 v[116:117], v[104:107], off offset:16
	v_ashrrev_i32_e32 v97, 31, v96
	v_lshlrev_b64 v[96:97], 12, v[96:97]
	v_lshlrev_b32_e32 v104, 16, v210
	v_and_b32_e32 v105, 0xffff0000, v210
	v_lshlrev_b32_e32 v106, 16, v211
	v_and_b32_e32 v107, 0xffff0000, v211
	v_pk_fma_f32 v[102:103], v[102:103], v[122:123], v[106:107] op_sel_hi:[1,0,1]
	v_pk_fma_f32 v[100:101], v[100:101], v[122:123], v[104:105] op_sel_hi:[1,0,1]
	global_store_dwordx4 v[116:117], v[100:103], off offset:512
	v_lshl_add_u64 v[96:97], s[26:27], 0, v[96:97]
	v_lshl_add_u64 v[96:97], v[96:97], 0, v[176:177]
	v_lshlrev_b32_e32 v100, 16, v214
	v_and_b32_e32 v101, 0xffff0000, v214
	v_lshlrev_b32_e32 v102, 16, v215
	v_and_b32_e32 v103, 0xffff0000, v215
	s_waitcnt lgkmcnt(0)
; __device__ __forceinline__ float bf_lo(unsigned w) { return __uint_as_float(w << 16); }
; __device__ __forceinline__ float bf_hi(unsigned w) { return __uint_as_float(w & 0xffff0000u); }
;     __device__ __forceinline__ void operator()(const f32x4 (&acc)[2][2][4][2], const Unit& u, int ui, int wr, int wc, int fr, int fq) const {
;         const int rl0 = wr * 64 + fr, col0 = u.pn * 256 + wc * 32 + 8 * fq;
;         u32x4 xv[2][4][2];
; #pragma unroll
;         for (int ai = 0; ai < 2; ++ai)
; #pragma unroll
;             for (int m = 0; m < 4; ++m)
; #pragma unroll
;                 for (int bj = 0; bj < 2; ++bj) xv[ai][m][bj] = *(const u32x4*)(xb + (size_t)(u.pm * 256 + rl0 + ai * 128 + m * 16) * DM + col0 + bj * 128);
; #pragma unroll
;         for (int ai = 0; ai < 2; ++ai)
; #pragma unroll
;             for (int m = 0; m < 4; ++m) { const int rl = rl0 + ai * 128 + m * 16; float* rowp = out + (size_t)(u.pm * 256 + rl) * DM + col0;
;                 const float r2 = tab[ui * 256 + rl];
; #pragma unroll
;                 for (int bj = 0; bj < 2; ++bj) { const u32x4 x = xv[ai][m][bj];
;                     const f32x4 x0 = {bf_lo(x.x), bf_hi(x.x), bf_lo(x.y), bf_hi(x.y)}, x1 = {bf_lo(x.z), bf_hi(x.z), bf_lo(x.w), bf_hi(x.w)};
;                     *(f32x4*)(rowp + bj * 128) = acc[ai][bj][m][0] * r2 + x0; *(f32x4*)(rowp + bj * 128 + 4) = acc[ai][bj][m][1] * r2 + x1; } }
	v_pk_fma_f32 v[94:95], v[94:95], v[98:99], v[102:103] op_sel_hi:[1,0,1]
	v_pk_fma_f32 v[92:93], v[92:93], v[98:99], v[100:101] op_sel_hi:[1,0,1]
	global_store_dwordx4 v[96:97], v[92:95], off
	v_lshlrev_b32_e32 v104, 16, v216
	v_and_b32_e32 v105, 0xffff0000, v216
	v_lshlrev_b32_e32 v92, 16, v220
	v_and_b32_e32 v93, 0xffff0000, v220
	v_lshlrev_b32_e32 v94, 16, v221
	v_and_b32_e32 v95, 0xffff0000, v221
	v_lshlrev_b32_e32 v106, 16, v217
	v_and_b32_e32 v107, 0xffff0000, v217
	v_pk_fma_f32 v[82:83], v[82:83], v[98:99], v[94:95] op_sel_hi:[1,0,1]
	v_pk_fma_f32 v[80:81], v[80:81], v[98:99], v[92:93] op_sel_hi:[1,0,1]
	v_pk_fma_f32 v[90:91], v[90:91], v[98:99], v[106:107] op_sel_hi:[1,0,1]
	v_pk_fma_f32 v[88:89], v[88:89], v[98:99], v[104:105] op_sel_hi:[1,0,1]
	global_store_dwordx4 v[96:97], v[80:83], off offset:528
	global_store_dwordx4 v[96:97], v[88:91], off offset:16
	s_nop 0
	v_add_u32_e32 v80, s11, v190
	v_lshlrev_b32_e32 v88, 16, v218
	v_and_b32_e32 v89, 0xffff0000, v218
	v_lshlrev_b32_e32 v90, 16, v219
	v_and_b32_e32 v91, 0xffff0000, v219
	v_ashrrev_i32_e32 v81, 31, v80
	v_pk_fma_f32 v[86:87], v[86:87], v[98:99], v[90:91] op_sel_hi:[1,0,1]
	v_pk_fma_f32 v[84:85], v[84:85], v[98:99], v[88:89] op_sel_hi:[1,0,1]
	v_lshlrev_b64 v[80:81], 12, v[80:81]
	global_store_dwordx4 v[96:97], v[84:87], off offset:512
	v_lshl_add_u64 v[80:81], s[26:27], 0, v[80:81]
	v_lshlrev_b32_e32 v82, 16, v222
	v_and_b32_e32 v83, 0xffff0000, v222
	v_lshlrev_b32_e32 v84, 16, v223
	v_and_b32_e32 v85, 0xffff0000, v223
	v_mov_b32_e32 v90, v99
	v_lshl_add_u64 v[80:81], v[80:81], 0, v[176:177]
	v_pk_fma_f32 v[78:79], v[78:79], v[90:91], v[84:85] op_sel_hi:[1,0,1]
	v_pk_fma_f32 v[76:77], v[76:77], v[90:91], v[82:83] op_sel_hi:[1,0,1]
	global_store_dwordx4 v[80:81], v[76:79], off
	v_lshlrev_b32_e32 v86, 16, v224
	v_and_b32_e32 v87, 0xffff0000, v224
	v_lshlrev_b32_e32 v76, 16, v228
	v_and_b32_e32 v77, 0xffff0000, v228
	v_lshlrev_b32_e32 v78, 16, v229
	v_and_b32_e32 v79, 0xffff0000, v229
	v_pk_fma_f32 v[66:67], v[66:67], v[90:91], v[78:79] op_sel_hi:[1,0,1]
	v_pk_fma_f32 v[64:65], v[64:65], v[90:91], v[76:77] op_sel_hi:[1,0,1]
	v_lshlrev_b32_e32 v88, 16, v225
	v_and_b32_e32 v89, 0xffff0000, v225
	global_store_dwordx4 v[80:81], v[64:67], off offset:528
	ds_read2_b32 v[66:67], v196 offset0:128 offset1:144
	v_pk_fma_f32 v[74:75], v[74:75], v[90:91], v[88:89] op_sel_hi:[1,0,1]
	v_pk_fma_f32 v[72:73], v[72:73], v[90:91], v[86:87] op_sel_hi:[1,0,1]
	global_store_dwordx4 v[80:81], v[72:75], off offset:16
	v_lshlrev_b64 v[64:65], 12, v[184:185]
	v_lshl_add_u64 v[64:65], s[26:27], 0, v[64:65]
	v_lshlrev_b32_e32 v72, 16, v226
	v_and_b32_e32 v73, 0xffff0000, v226
	v_lshlrev_b32_e32 v74, 16, v227
	v_and_b32_e32 v75, 0xffff0000, v227
	v_pk_fma_f32 v[70:71], v[70:71], v[90:91], v[74:75] op_sel_hi:[1,0,1]
	v_pk_fma_f32 v[68:69], v[68:69], v[90:91], v[72:73] op_sel_hi:[1,0,1]
	global_store_dwordx4 v[80:81], v[68:71], off offset:512
	v_lshl_add_u64 v[64:65], v[64:65], 0, v[176:177]
	v_lshlrev_b32_e32 v72, 16, v158
	v_lshlrev_b32_e32 v68, 16, v156
	v_and_b32_e32 v69, 0xffff0000, v156
	v_lshlrev_b32_e32 v70, 16, v157
	v_and_b32_e32 v71, 0xffff0000, v157
	v_and_b32_e32 v73, 0xffff0000, v158
	v_lshlrev_b32_e32 v74, 16, v159
	v_and_b32_e32 v75, 0xffff0000, v159
	s_waitcnt lgkmcnt(0)
; __device__ __forceinline__ float bf_lo(unsigned w) { return __uint_as_float(w << 16); }
; __device__ __forceinline__ float bf_hi(unsigned w) { return __uint_as_float(w & 0xffff0000u); }
; #define PG8_WAIT_V(n) asm volatile("s_waitcnt vmcnt(" #n ")" ::: "memory")
; #define PG8_BAR __builtin_amdgcn_s_barrier()
; template <class Epi, class Ptrs>
; __device__ __forceinline__ void gemm_phase(LAS unsigned char* lds, const int K, const StaticOrder& S, const Ptrs& P, const Epi& E) {
;     ...
;     PG8_WAIT_V(0);
;     if (wr == 0) PG8_BAR;
;     PG8_BAR;
;     __device__ __forceinline__ void operator()(const f32x4 (&acc)[2][2][4][2], const Unit& u, int ui, int wr, int wc, int fr, int fq) const {
;         const int rl0 = wr * 64 + fr, col0 = u.pn * 256 + wc * 32 + 8 * fq;
;         u32x4 xv[2][4][2];
; #pragma unroll
;         for (int ai = 0; ai < 2; ++ai)
; #pragma unroll
;             for (int m = 0; m < 4; ++m)
; #pragma unroll
;                 for (int bj = 0; bj < 2; ++bj) xv[ai][m][bj] = *(const u32x4*)(xb + (size_t)(u.pm * 256 + rl0 + ai * 128 + m * 16) * DM + col0 + bj * 128);
; #pragma unroll
;         for (int ai = 0; ai < 2; ++ai)
; #pragma unroll
;             for (int m = 0; m < 4; ++m) { const int rl = rl0 + ai * 128 + m * 16; float* rowp = out + (size_t)(u.pm * 256 + rl) * DM + col0;
;                 const float r2 = tab[ui * 256 + rl];
; #pragma unroll
;                 for (int bj = 0; bj < 2; ++bj) { const u32x4 x = xv[ai][m][bj];
;                     const f32x4 x0 = {bf_lo(x.x), bf_hi(x.x), bf_lo(x.y), bf_hi(x.y)}, x1 = {bf_lo(x.z), bf_hi(x.z), bf_lo(x.w), bf_hi(x.w)};
;                     *(f32x4*)(rowp + bj * 128) = acc[ai][bj][m][0] * r2 + x0; *(f32x4*)(rowp + bj * 128 + 4) = acc[ai][bj][m][1] * r2 + x1; } }
	v_pk_fma_f32 v[62:63], v[62:63], v[66:67], v[70:71] op_sel_hi:[1,0,1]
	v_pk_fma_f32 v[60:61], v[60:61], v[66:67], v[68:69] op_sel_hi:[1,0,1]
	global_store_dwordx4 v[64:65], v[60:63], off
	v_pk_fma_f32 v[58:59], v[58:59], v[66:67], v[74:75] op_sel_hi:[1,0,1]
	v_pk_fma_f32 v[56:57], v[56:57], v[66:67], v[72:73] op_sel_hi:[1,0,1]
	v_lshlrev_b32_e32 v60, 16, v154
	v_and_b32_e32 v61, 0xffff0000, v154
	v_lshlrev_b32_e32 v62, 16, v155
	v_and_b32_e32 v63, 0xffff0000, v155
	global_store_dwordx4 v[64:65], v[56:59], off offset:16
	v_pk_fma_f32 v[46:47], v[46:47], v[66:67], v[62:63] op_sel_hi:[1,0,1]
	v_pk_fma_f32 v[44:45], v[44:45], v[66:67], v[60:61] op_sel_hi:[1,0,1]
	v_lshlrev_b32_e32 v56, 16, v152
	v_and_b32_e32 v57, 0xffff0000, v152
	v_lshlrev_b32_e32 v58, 16, v153
	v_and_b32_e32 v59, 0xffff0000, v153
	v_pk_fma_f32 v[54:55], v[54:55], v[66:67], v[58:59] op_sel_hi:[1,0,1]
	v_pk_fma_f32 v[52:53], v[52:53], v[66:67], v[56:57] op_sel_hi:[1,0,1]
	global_store_dwordx4 v[64:65], v[44:47], off offset:528
	global_store_dwordx4 v[64:65], v[52:55], off offset:512
	v_lshlrev_b32_e32 v56, 16, v151
	v_lshlrev_b64 v[44:45], 12, v[182:183]
	v_lshl_add_u64 v[44:45], s[26:27], 0, v[44:45]
	v_lshlrev_b32_e32 v54, 16, v150
	v_and_b32_e32 v55, 0xffff0000, v150
	v_and_b32_e32 v57, 0xffff0000, v151
	v_mov_b32_e32 v58, v67
	v_lshl_add_u64 v[52:53], v[44:45], 0, v[176:177]
	v_pk_fma_f32 v[42:43], v[42:43], v[58:59], v[56:57] op_sel_hi:[1,0,1]
	v_pk_fma_f32 v[40:41], v[40:41], v[58:59], v[54:55] op_sel_hi:[1,0,1]
	v_lshlrev_b32_e32 v44, 16, v148
	v_and_b32_e32 v45, 0xffff0000, v148
	v_lshlrev_b32_e32 v46, 16, v149
	v_and_b32_e32 v47, 0xffff0000, v149
	global_store_dwordx4 v[52:53], v[40:43], off offset:16
	v_pk_fma_f32 v[46:47], v[50:51], v[58:59], v[46:47] op_sel_hi:[1,0,1]
	v_pk_fma_f32 v[44:45], v[48:49], v[58:59], v[44:45] op_sel_hi:[1,0,1]
	v_lshlrev_b32_e32 v40, 16, v144
	v_and_b32_e32 v41, 0xffff0000, v144
	v_lshlrev_b32_e32 v42, 16, v145
	v_and_b32_e32 v43, 0xffff0000, v145
	v_pk_fma_f32 v[38:39], v[38:39], v[58:59], v[42:43] op_sel_hi:[1,0,1]
	v_pk_fma_f32 v[36:37], v[36:37], v[58:59], v[40:41] op_sel_hi:[1,0,1]
	global_store_dwordx4 v[52:53], v[44:47], off
	global_store_dwordx4 v[52:53], v[36:39], off offset:512
	ds_read2_b32 v[38:39], v196 offset0:160 offset1:176
	v_lshlrev_b32_e32 v44, 16, v146
	v_and_b32_e32 v45, 0xffff0000, v146
	v_lshlrev_b32_e32 v46, 16, v147
	v_and_b32_e32 v47, 0xffff0000, v147
	v_pk_fma_f32 v[30:31], v[30:31], v[58:59], v[46:47] op_sel_hi:[1,0,1]
	v_pk_fma_f32 v[28:29], v[28:29], v[58:59], v[44:45] op_sel_hi:[1,0,1]
	global_store_dwordx4 v[52:53], v[28:31], off offset:528
	v_lshlrev_b32_e32 v40, 16, v142
	v_and_b32_e32 v41, 0xffff0000, v142
	v_lshlrev_b64 v[28:29], 12, v[180:181]
	v_lshl_add_u64 v[28:29], s[26:27], 0, v[28:29]
	v_lshl_add_u64 v[36:37], v[28:29], 0, v[176:177]
	v_lshlrev_b32_e32 v28, 16, v140
	v_and_b32_e32 v29, 0xffff0000, v140
	v_lshlrev_b32_e32 v30, 16, v141
	v_and_b32_e32 v31, 0xffff0000, v141
	s_waitcnt lgkmcnt(0)
	v_pk_fma_f32 v[30:31], v[34:35], v[38:39], v[30:31] op_sel_hi:[1,0,1]
	v_pk_fma_f32 v[28:29], v[32:33], v[38:39], v[28:29] op_sel_hi:[1,0,1]
	v_lshlrev_b32_e32 v42, 16, v143
	v_and_b32_e32 v43, 0xffff0000, v143
	global_store_dwordx4 v[36:37], v[28:31], off
	v_pk_fma_f32 v[26:27], v[26:27], v[38:39], v[42:43] op_sel_hi:[1,0,1]
	v_pk_fma_f32 v[24:25], v[24:25], v[38:39], v[40:41] op_sel_hi:[1,0,1]
	v_lshlrev_b32_e32 v28, 16, v138
	v_and_b32_e32 v29, 0xffff0000, v138
	v_lshlrev_b32_e32 v30, 16, v139
	v_and_b32_e32 v31, 0xffff0000, v139
	v_pk_fma_f32 v[14:15], v[14:15], v[38:39], v[30:31] op_sel_hi:[1,0,1]
	v_pk_fma_f32 v[12:13], v[12:13], v[38:39], v[28:29] op_sel_hi:[1,0,1]
	global_store_dwordx4 v[36:37], v[24:27], off offset:16
	global_store_dwordx4 v[36:37], v[12:15], off offset:528
	s_nop 0
	v_lshlrev_b32_e32 v24, 16, v136
	v_and_b32_e32 v25, 0xffff0000, v136
	v_lshlrev_b32_e32 v26, 16, v137
	v_and_b32_e32 v27, 0xffff0000, v137
	v_lshlrev_b64 v[12:13], 12, v[178:179]
	v_pk_fma_f32 v[22:23], v[22:23], v[38:39], v[26:27] op_sel_hi:[1,0,1]
	v_pk_fma_f32 v[20:21], v[20:21], v[38:39], v[24:25] op_sel_hi:[1,0,1]
	v_lshl_add_u64 v[12:13], s[26:27], 0, v[12:13]
	global_store_dwordx4 v[36:37], v[20:23], off offset:512
	v_lshlrev_b32_e32 v14, 16, v133
	v_and_b32_e32 v15, 0xffff0000, v133
	v_lshl_add_u64 v[20:21], v[12:13], 0, v[176:177]
	v_lshlrev_b32_e32 v12, 16, v132
	v_and_b32_e32 v13, 0xffff0000, v132
	v_lshlrev_b32_e32 v22, 16, v134
	v_and_b32_e32 v23, 0xffff0000, v134
	v_lshlrev_b32_e32 v24, 16, v135
	v_and_b32_e32 v25, 0xffff0000, v135
	v_mov_b32_e32 v26, v39
	v_pk_fma_f32 v[14:15], v[18:19], v[26:27], v[14:15] op_sel_hi:[1,0,1]
	v_pk_fma_f32 v[12:13], v[16:17], v[26:27], v[12:13] op_sel_hi:[1,0,1]
	v_pk_fma_f32 v[10:11], v[10:11], v[26:27], v[24:25] op_sel_hi:[1,0,1]
	v_pk_fma_f32 v[8:9], v[8:9], v[26:27], v[22:23] op_sel_hi:[1,0,1]
	global_store_dwordx4 v[20:21], v[12:15], off
	global_store_dwordx4 v[20:21], v[8:11], off offset:16
	s_nop 0
	v_lshlrev_b32_e32 v12, 16, v130
	v_lshlrev_b32_e32 v8, 16, v128
	v_and_b32_e32 v9, 0xffff0000, v128
	v_lshlrev_b32_e32 v10, 16, v129
	v_and_b32_e32 v11, 0xffff0000, v129
	v_and_b32_e32 v13, 0xffff0000, v130
	v_lshlrev_b32_e32 v14, 16, v131
	v_and_b32_e32 v15, 0xffff0000, v131
	v_pk_fma_f32 v[6:7], v[6:7], v[26:27], v[10:11] op_sel_hi:[1,0,1]
	v_pk_fma_f32 v[4:5], v[4:5], v[26:27], v[8:9] op_sel_hi:[1,0,1]
	v_pk_fma_f32 v[2:3], v[2:3], v[26:27], v[14:15] op_sel_hi:[1,0,1]
	v_pk_fma_f32 v[0:1], v[0:1], v[26:27], v[12:13] op_sel_hi:[1,0,1]
	global_store_dwordx4 v[20:21], v[4:7], off offset:512
	global_store_dwordx4 v[20:21], v[0:3], off offset:528
	s_cbranch_vccz .LBB0_517
	s_waitcnt vmcnt(0)
	s_setprio 0
	s_cmpk_gt_u32 s33, 0xff
	s_cbranch_scc1 .LBB0_526
	s_barrier
